# s_setprio 0 moved behind the s_barrier that closes each MFMA segment (32 sites): the compute wave reaches the barrier one issue slot earlier; on top of v64
# speedup vs baseline: 1.0036x; 1.0001x over previous
;     __host__ __device__ __forceinline__ bool next(int i, Unit& u) const { const int vv = vid + (i / 5) * G; if (vv >= 256) return false; u.pm = vv >> 2; u.pn = (vv & 3) + 4 * (i % 5); return true; }
; #define PG8_STAGE(bufoff, gbase, voff) do { _Pragma("unroll") for (int _i = 0; _i < 2; ++_i) \
;         __builtin_amdgcn_global_load_lds((const unsigned*)((const char*)(gbase) + (voff)[_i]), (PG8_LAS unsigned*)(lds + (bufoff) + ldsw + _i * 8192), 16, 0, 0); } while (0)
; #define PG8_LDA(dst, b, h) do { _Pragma("unroll") for (int m = 0; m < 4; ++m) _Pragma("unroll") for (int k = 0; k < 2; ++k) dst[m][k] = *(const PG8_LAS bf16x8*)(lds + PG8_SA(b, h) + aoff + m * 2048 + k * 1024); } while (0)
; #define PG8_LDB(dst, b, h) do { _Pragma("unroll") for (int n = 0; n < 2; ++n) _Pragma("unroll") for (int k = 0; k < 2; ++k) dst[n][k] = *(const PG8_LAS bf16x8*)(lds + PG8_SB(b, h) + boff + n * 2048 + k * 1024); } while (0)
; #define PG8_WAIT_V(n) asm volatile("s_waitcnt vmcnt(" #n ")" ::: "memory")
;     ...
;         const bool has_next = S.next(ui + 1, nxt);
;         const char* nA = has_next ? (const char*)g.A + (size_t)nxt.pm * tstepA + (size_t)nxt.pn * APN + kofA : cA; const char* nB = has_next ? (const char*)g.Bt + (size_t)nxt.pn * tstepB + S.b_off(nxt) + kofB : cB;
;         for (int t = 0; t < nt; t += 2) {
;             const bool last = (t == nt - 2);
;             const char* a1 = cA + (ptrdiff_t)(t + 1) * kstepA;
;             const char* a2 = last ? nA : cA + (ptrdiff_t)(t + 2) * kstepA; const char* b2 = last ? nB : cB + (ptrdiff_t)(t + 2) * kstep;
;             const char* a3 = a2 + kstepA; const char* b3 = b2 + kstep;
;             if (last && has_next) S.a_ready(nxt);
;             if constexpr (SP2) {
;             PG8_LDB(B0, 0, 0); PG8_LDB(B1, 0, 1); PG8_SCHED; PG8_LDA(At, 0, 0); PG8_STAGE(PG8_SA(1, 1), a1 + hstepA, voffA);
;             PG8_WAIT_V(8); PG8_WAIT_L(0); PG8_BAR; PG8_MMA(0, 0, At, B0); PG8_MMA(0, 1, At, B1); PG8_BAR; PG8_SCHED;
;             PG8_LDA(At, 0, 1); PG8_STAGE(PG8_SB(0, 0), b2, voffB); PG8_STAGE(PG8_SB(0, 1), b2 + hstepB, voffB); PG8_STAGE(PG8_SA(0, 0), a2, voffA);
;             PG8_WAIT_V(8); PG8_WAIT_L(0); PG8_BAR; PG8_MMA(1, 0, At, B0); PG8_MMA(1, 1, At, B1); PG8_BAR; PG8_SCHED;
;     __device__ __forceinline__ size_t b_off(const pg8::Unit& u) const { return (size_t)(u.pm >> 3) * 4 * 131072; }
.LBB0_97:
	s_mov_b64 s[30:31], s[6:7]
	s_ashr_i32 s6, s14, 2
	s_and_b32 s6, s6, -8
	s_and_b32 s7, s14, 7
	s_mov_b32 s20, s58
	s_mov_b32 s21, s57
	v_cmp_lt_i64_e64 s[4:5], s[14:15], v[138:139]
	s_bfe_u32 s57, s14, 0x20003
	s_or_b32 s58, s6, s7
	s_and_b64 s[6:7], s[4:5], exec
	s_cselect_b32 s24, s58, s20
	s_cselect_b32 s6, s57, s21
	s_ashr_i32 s25, s24, 31
	s_lshl_b64 s[20:21], s[24:25], 20
	s_add_u32 s20, s2, s20
	s_addc_u32 s21, s3, s21
	s_ashr_i32 s7, s6, 31
	s_lshl_b64 s[6:7], s[6:7], 17
	s_add_u32 s20, s20, s6
	s_addc_u32 s21, s21, s7
	s_and_b64 s[28:29], s[4:5], exec
	ds_read_b128 v[0:3], v141
	ds_read_b128 v[4:7], v141 offset:1024
	ds_read_b128 v[8:11], v141 offset:2048
	ds_read_b128 v[12:15], v141 offset:3072
	ds_read_b128 v[16:19], v142
	ds_read_b128 v[20:23], v142 offset:1024
	ds_read_b128 v[24:27], v142 offset:2048
	ds_read_b128 v[28:31], v142 offset:3072
	s_cselect_b32 s29, s21, s27
	s_cselect_b32 s28, s20, s26
	s_add_u32 s25, s33, s6
	s_addc_u32 s34, s36, s7
	s_ashr_i32 s6, s24, 3
	s_ashr_i32 s7, s6, 31
	s_lshl_b64 s[6:7], s[6:7], 19
	s_add_u32 s6, s25, s6
	s_addc_u32 s7, s34, s7
	s_and_b64 s[24:25], s[4:5], exec
	s_cselect_b32 s25, s7, s31
	s_cselect_b32 s24, s6, s30
	s_add_u32 s60, s26, 0x10000
	s_addc_u32 s61, s27, 0
	s_add_u32 s34, s26, 0x18000
	s_addc_u32 s35, s27, 0
	s_add_u32 s62, s26, 0xc000
	s_addc_u32 s63, s27, 0
	s_mov_b32 m0, s46
	ds_read_b128 v[32:35], v143
	ds_read_b128 v[36:39], v143 offset:1024
	ds_read_b128 v[40:43], v143 offset:2048
	ds_read_b128 v[44:47], v143 offset:3072
	ds_read_b128 v[48:51], v143 offset:4096
	ds_read_b128 v[52:55], v143 offset:5120
	ds_read_b128 v[56:59], v143 offset:6144
	ds_read_b128 v[60:63], v143 offset:7168
	global_load_lds_dwordx4 v134, s[62:63]
	v_lshl_add_u64 v[64:65], s[62:63], 0, v[130:131]
	s_mov_b32 m0, s47
	s_nop 0
	global_load_lds_dwordx4 v[64:65], off
	s_waitcnt vmcnt(8)
	s_waitcnt lgkmcnt(0)
	s_barrier
	s_setprio 1
	v_mfma_f32_16x16x32_bf16 v[64:67], v[0:3], v[32:35], 0
	v_mfma_f32_16x16x32_bf16 v[64:67], v[4:7], v[36:39], v[64:67]
	v_mfma_f32_16x16x32_bf16 v[68:71], v[8:11], v[32:35], 0
	v_mfma_f32_16x16x32_bf16 v[68:71], v[12:15], v[36:39], v[68:71]
	v_mfma_f32_16x16x32_bf16 v[72:75], v[0:3], v[40:43], 0
	v_mfma_f32_16x16x32_bf16 v[72:75], v[4:7], v[44:47], v[72:75]
	v_mfma_f32_16x16x32_bf16 v[76:79], v[8:11], v[40:43], 0
	v_mfma_f32_16x16x32_bf16 v[76:79], v[12:15], v[44:47], v[76:79]
	v_mfma_f32_16x16x32_bf16 v[80:83], v[0:3], v[48:51], 0
	v_mfma_f32_16x16x32_bf16 v[80:83], v[4:7], v[52:55], v[80:83]
	v_mfma_f32_16x16x32_bf16 v[84:87], v[8:11], v[48:51], 0
	v_mfma_f32_16x16x32_bf16 v[84:87], v[12:15], v[52:55], v[84:87]
	v_mfma_f32_16x16x32_bf16 v[88:91], v[0:3], v[56:59], 0
	v_mfma_f32_16x16x32_bf16 v[88:91], v[4:7], v[60:63], v[88:91]
	v_mfma_f32_16x16x32_bf16 v[92:95], v[8:11], v[56:59], 0
	v_mfma_f32_16x16x32_bf16 v[92:95], v[12:15], v[60:63], v[92:95]
	s_setprio 0
	s_setprio 1
	v_mfma_f32_16x16x32_bf16 v[96:99], v[16:19], v[32:35], 0
	v_mfma_f32_16x16x32_bf16 v[96:99], v[20:23], v[36:39], v[96:99]
	v_mfma_f32_16x16x32_bf16 v[32:35], v[24:27], v[32:35], 0
	v_mfma_f32_16x16x32_bf16 v[32:35], v[28:31], v[36:39], v[32:35]
	v_mfma_f32_16x16x32_bf16 v[36:39], v[16:19], v[40:43], 0
	v_mfma_f32_16x16x32_bf16 v[36:39], v[20:23], v[44:47], v[36:39]
	v_mfma_f32_16x16x32_bf16 v[40:43], v[24:27], v[40:43], 0
	v_mfma_f32_16x16x32_bf16 v[40:43], v[28:31], v[44:47], v[40:43]
	v_mfma_f32_16x16x32_bf16 v[44:47], v[16:19], v[48:51], 0
	v_mfma_f32_16x16x32_bf16 v[44:47], v[20:23], v[52:55], v[44:47]
	v_mfma_f32_16x16x32_bf16 v[48:51], v[24:27], v[48:51], 0
	v_mfma_f32_16x16x32_bf16 v[48:51], v[28:31], v[52:55], v[48:51]
	v_mfma_f32_16x16x32_bf16 v[52:55], v[16:19], v[56:59], 0
	v_mfma_f32_16x16x32_bf16 v[52:55], v[20:23], v[60:63], v[52:55]
	v_mfma_f32_16x16x32_bf16 v[56:59], v[24:27], v[56:59], 0
	v_mfma_f32_16x16x32_bf16 v[56:59], v[28:31], v[60:63], v[56:59]
	s_barrier
	s_setprio 0
	v_lshl_add_u64 v[210:211], s[30:31], 0, v[132:133]
	s_mov_b32 m0, s48
	v_lshl_add_u64 v[146:147], v[210:211], 0, s[16:17]
	v_lshl_add_u64 v[212:213], s[30:31], 0, v[128:129]
	s_add_u32 s62, s30, 0x10100
	ds_read_b128 v[60:63], v143 offset:16384
	ds_read_b128 v[100:103], v143 offset:17408
	ds_read_b128 v[104:107], v143 offset:18432
	ds_read_b128 v[108:111], v143 offset:19456
	ds_read_b128 v[112:115], v143 offset:20480
	ds_read_b128 v[116:119], v143 offset:21504
	ds_read_b128 v[120:123], v143 offset:22528
	ds_read_b128 v[124:127], v143 offset:23552
	global_load_lds_dwordx4 v[146:147], off
	v_lshl_add_u64 v[146:147], v[212:213], 0, s[16:17]
	s_mov_b32 m0, s50
	s_addc_u32 s63, s31, 0
	global_load_lds_dwordx4 v[146:147], off
	s_mov_b32 m0, s51
	s_nop 0
	global_load_lds_dwordx4 v132, s[62:63]
	s_mov_b32 m0, s52
	s_nop 0
	global_load_lds_dwordx4 v128, s[62:63]
	s_mov_b32 m0, s23
	s_nop 0
	global_load_lds_dwordx4 v134, s[60:61]
	v_lshl_add_u64 v[146:147], s[60:61], 0, v[130:131]
	s_mov_b32 m0, s37
	s_nop 0
	global_load_lds_dwordx4 v[146:147], off
	s_waitcnt vmcnt(8)
	s_waitcnt lgkmcnt(0)
	s_barrier
; #define PG8_STAGE(bufoff, gbase, voff) do { _Pragma("unroll") for (int _i = 0; _i < 2; ++_i) \
;         __builtin_amdgcn_global_load_lds((const unsigned*)((const char*)(gbase) + (voff)[_i]), (PG8_LAS unsigned*)(lds + (bufoff) + ldsw + _i * 8192), 16, 0, 0); } while (0)
; #define PG8_LDA(dst, b, h) do { _Pragma("unroll") for (int m = 0; m < 4; ++m) _Pragma("unroll") for (int k = 0; k < 2; ++k) dst[m][k] = *(const PG8_LAS bf16x8*)(lds + PG8_SA(b, h) + aoff + m * 2048 + k * 1024); } while (0)
; #define PG8_LDB(dst, b, h) do { _Pragma("unroll") for (int n = 0; n < 2; ++n) _Pragma("unroll") for (int k = 0; k < 2; ++k) dst[n][k] = *(const PG8_LAS bf16x8*)(lds + PG8_SB(b, h) + boff + n * 2048 + k * 1024); } while (0)
; #define PG8_MMA(ai, bj, At, Bt) do { __builtin_amdgcn_s_setprio(1); _Pragma("unroll") for (int m = 0; m < 4; ++m) _Pragma("unroll") for (int n = 0; n < 2; ++n) _Pragma("unroll") for (int k = 0; k < 2; ++k) \
;         acc[ai][bj][m][n] = __builtin_amdgcn_mfma_f32_16x16x32_bf16(Bt[n][k], At[m][k], acc[ai][bj][m][n], 0, 0, 0); __builtin_amdgcn_s_setprio(0); } while (0)
; #define PG8_WAIT_V(n) asm volatile("s_waitcnt vmcnt(" #n ")" ::: "memory")
; #define PG8_WAIT_L(n) asm volatile("s_waitcnt lgkmcnt(" #n ")" ::: "memory")
; #define PG8_BAR __builtin_amdgcn_s_barrier()
; #define PG8_SCHED __builtin_amdgcn_sched_barrier(0)
;     ...
;             PG8_WAIT_V(8); PG8_WAIT_L(0); PG8_BAR; PG8_MMA(1, 0, At, B0); PG8_MMA(1, 1, At, B1); PG8_BAR; PG8_SCHED;
;             PG8_LDB(B0, 1, 0); PG8_LDB(B1, 1, 1); PG8_SCHED; PG8_LDA(At, 1, 0); PG8_STAGE(PG8_SA(0, 1), a2 + hstepA, voffA);
;             PG8_WAIT_V(8); PG8_WAIT_L(0); PG8_BAR; PG8_MMA(0, 0, At, B0); PG8_MMA(0, 1, At, B1); PG8_BAR; PG8_SCHED;
	s_setprio 1
	v_mfma_f32_16x16x32_bf16 v[146:149], v[0:3], v[60:63], 0
	v_mfma_f32_16x16x32_bf16 v[146:149], v[4:7], v[100:103], v[146:149]
	v_mfma_f32_16x16x32_bf16 v[154:157], v[0:3], v[104:107], 0
	v_mfma_f32_16x16x32_bf16 v[154:157], v[4:7], v[108:111], v[154:157]
	v_mfma_f32_16x16x32_bf16 v[162:165], v[0:3], v[112:115], 0
	v_mfma_f32_16x16x32_bf16 v[162:165], v[4:7], v[116:119], v[162:165]
	v_mfma_f32_16x16x32_bf16 v[0:3], v[0:3], v[120:123], 0
	v_mfma_f32_16x16x32_bf16 v[0:3], v[4:7], v[124:127], v[0:3]
	v_mfma_f32_16x16x32_bf16 v[4:7], v[8:11], v[120:123], 0
	v_mfma_f32_16x16x32_bf16 v[4:7], v[12:15], v[124:127], v[4:7]
	v_mfma_f32_16x16x32_bf16 v[150:153], v[8:11], v[60:63], 0
	v_mfma_f32_16x16x32_bf16 v[150:153], v[12:15], v[100:103], v[150:153]
	v_mfma_f32_16x16x32_bf16 v[158:161], v[8:11], v[104:107], 0
	v_mfma_f32_16x16x32_bf16 v[158:161], v[12:15], v[108:111], v[158:161]
	v_mfma_f32_16x16x32_bf16 v[166:169], v[8:11], v[112:115], 0
	v_mfma_f32_16x16x32_bf16 v[166:169], v[12:15], v[116:119], v[166:169]
	s_setprio 0
	s_setprio 1
	v_mfma_f32_16x16x32_bf16 v[8:11], v[16:19], v[60:63], 0
	v_mfma_f32_16x16x32_bf16 v[8:11], v[20:23], v[100:103], v[8:11]
	v_mfma_f32_16x16x32_bf16 v[12:15], v[24:27], v[60:63], 0
	v_mfma_f32_16x16x32_bf16 v[12:15], v[28:31], v[100:103], v[12:15]
	v_mfma_f32_16x16x32_bf16 v[60:63], v[16:19], v[104:107], 0
	v_mfma_f32_16x16x32_bf16 v[60:63], v[20:23], v[108:111], v[60:63]
	v_mfma_f32_16x16x32_bf16 v[100:103], v[24:27], v[104:107], 0
	v_mfma_f32_16x16x32_bf16 v[100:103], v[28:31], v[108:111], v[100:103]
	v_mfma_f32_16x16x32_bf16 v[104:107], v[16:19], v[112:115], 0
	v_mfma_f32_16x16x32_bf16 v[104:107], v[20:23], v[116:119], v[104:107]
	v_mfma_f32_16x16x32_bf16 v[16:19], v[16:19], v[120:123], 0
	v_mfma_f32_16x16x32_bf16 v[16:19], v[20:23], v[124:127], v[16:19]
	v_mfma_f32_16x16x32_bf16 v[108:111], v[24:27], v[112:115], 0
	v_mfma_f32_16x16x32_bf16 v[108:111], v[28:31], v[116:119], v[108:111]
	v_mfma_f32_16x16x32_bf16 v[20:23], v[24:27], v[120:123], 0
	v_mfma_f32_16x16x32_bf16 v[20:23], v[28:31], v[124:127], v[20:23]
	s_barrier
	s_setprio 0
	ds_read_b128 v[24:27], v144
	ds_read_b128 v[28:31], v144 offset:1024
	ds_read_b128 v[112:115], v144 offset:2048
	ds_read_b128 v[116:119], v144 offset:3072
	ds_read_b128 v[120:123], v145
	ds_read_b128 v[124:127], v145 offset:1024
	ds_read_b128 v[170:173], v145 offset:2048
	ds_read_b128 v[174:177], v145 offset:3072
	s_add_u32 s60, s26, 0x14000
	s_addc_u32 s61, s27, 0
	s_mov_b32 m0, s39
	ds_read_b128 v[178:181], v143 offset:32768
	ds_read_b128 v[182:185], v143 offset:33792
	ds_read_b128 v[186:189], v143 offset:34816
	ds_read_b128 v[190:193], v143 offset:35840
	ds_read_b128 v[194:197], v143 offset:36864
	ds_read_b128 v[198:201], v143 offset:37888
	ds_read_b128 v[202:205], v143 offset:38912
	ds_read_b128 v[206:209], v143 offset:39936
	global_load_lds_dwordx4 v134, s[60:61]
	v_lshl_add_u64 v[214:215], s[60:61], 0, v[130:131]
	s_mov_b32 m0, s40
	s_nop 0
	global_load_lds_dwordx4 v[214:215], off
	s_waitcnt vmcnt(8)
	s_waitcnt lgkmcnt(0)
	s_barrier
	s_setprio 1
	v_mfma_f32_16x16x32_bf16 v[64:67], v[24:27], v[178:181], v[64:67]
	v_mfma_f32_16x16x32_bf16 v[64:67], v[28:31], v[182:185], v[64:67]
	v_mfma_f32_16x16x32_bf16 v[68:71], v[116:119], v[182:185], v[68:71]
	v_mfma_f32_16x16x32_bf16 v[68:71], v[112:115], v[178:181], v[68:71]
	v_mfma_f32_16x16x32_bf16 v[76:79], v[112:115], v[186:189], v[76:79]
	v_mfma_f32_16x16x32_bf16 v[76:79], v[116:119], v[190:193], v[76:79]
	v_mfma_f32_16x16x32_bf16 v[72:75], v[28:31], v[190:193], v[72:75]
	v_mfma_f32_16x16x32_bf16 v[72:75], v[24:27], v[186:189], v[72:75]
	v_mfma_f32_16x16x32_bf16 v[80:83], v[24:27], v[194:197], v[80:83]
	v_mfma_f32_16x16x32_bf16 v[80:83], v[28:31], v[198:201], v[80:83]
	v_mfma_f32_16x16x32_bf16 v[84:87], v[116:119], v[198:201], v[84:87]
	v_mfma_f32_16x16x32_bf16 v[84:87], v[112:115], v[194:197], v[84:87]
	v_mfma_f32_16x16x32_bf16 v[92:95], v[112:115], v[202:205], v[92:95]
	v_mfma_f32_16x16x32_bf16 v[92:95], v[116:119], v[206:209], v[92:95]
	v_mfma_f32_16x16x32_bf16 v[88:91], v[28:31], v[206:209], v[88:91]
	v_mfma_f32_16x16x32_bf16 v[88:91], v[24:27], v[202:205], v[88:91]
	s_setprio 0
	s_setprio 1
	v_mfma_f32_16x16x32_bf16 v[96:99], v[120:123], v[178:181], v[96:99]
	v_mfma_f32_16x16x32_bf16 v[96:99], v[124:127], v[182:185], v[96:99]
	v_mfma_f32_16x16x32_bf16 v[32:35], v[174:177], v[182:185], v[32:35]
	v_mfma_f32_16x16x32_bf16 v[32:35], v[170:173], v[178:181], v[32:35]
	v_mfma_f32_16x16x32_bf16 v[40:43], v[170:173], v[186:189], v[40:43]
	v_mfma_f32_16x16x32_bf16 v[40:43], v[174:177], v[190:193], v[40:43]
	v_mfma_f32_16x16x32_bf16 v[36:39], v[124:127], v[190:193], v[36:39]
	v_mfma_f32_16x16x32_bf16 v[36:39], v[120:123], v[186:189], v[36:39]
	v_mfma_f32_16x16x32_bf16 v[44:47], v[120:123], v[194:197], v[44:47]
	v_mfma_f32_16x16x32_bf16 v[44:47], v[124:127], v[198:201], v[44:47]
	v_mfma_f32_16x16x32_bf16 v[48:51], v[174:177], v[198:201], v[48:51]
	v_mfma_f32_16x16x32_bf16 v[48:51], v[170:173], v[194:197], v[48:51]
	v_mfma_f32_16x16x32_bf16 v[56:59], v[170:173], v[202:205], v[56:59]
	v_mfma_f32_16x16x32_bf16 v[56:59], v[174:177], v[206:209], v[56:59]
	v_mfma_f32_16x16x32_bf16 v[52:55], v[124:127], v[206:209], v[52:55]
	v_mfma_f32_16x16x32_bf16 v[52:55], v[120:123], v[202:205], v[52:55]
	s_barrier
; #define PG8_STAGE(bufoff, gbase, voff) do { _Pragma("unroll") for (int _i = 0; _i < 2; ++_i) \
;         __builtin_amdgcn_global_load_lds((const unsigned*)((const char*)(gbase) + (voff)[_i]), (PG8_LAS unsigned*)(lds + (bufoff) + ldsw + _i * 8192), 16, 0, 0); } while (0)
; #define PG8_LDA(dst, b, h) do { _Pragma("unroll") for (int m = 0; m < 4; ++m) _Pragma("unroll") for (int k = 0; k < 2; ++k) dst[m][k] = *(const PG8_LAS bf16x8*)(lds + PG8_SA(b, h) + aoff + m * 2048 + k * 1024); } while (0)
; #define PG8_LDB(dst, b, h) do { _Pragma("unroll") for (int n = 0; n < 2; ++n) _Pragma("unroll") for (int k = 0; k < 2; ++k) dst[n][k] = *(const PG8_LAS bf16x8*)(lds + PG8_SB(b, h) + boff + n * 2048 + k * 1024); } while (0)
; #define PG8_MMA(ai, bj, At, Bt) do { __builtin_amdgcn_s_setprio(1); _Pragma("unroll") for (int m = 0; m < 4; ++m) _Pragma("unroll") for (int n = 0; n < 2; ++n) _Pragma("unroll") for (int k = 0; k < 2; ++k) \
;         acc[ai][bj][m][n] = __builtin_amdgcn_mfma_f32_16x16x32_bf16(Bt[n][k], At[m][k], acc[ai][bj][m][n], 0, 0, 0); __builtin_amdgcn_s_setprio(0); } while (0)
; #define PG8_WAIT_V(n) asm volatile("s_waitcnt vmcnt(" #n ")" ::: "memory")
; #define PG8_WAIT_L(n) asm volatile("s_waitcnt lgkmcnt(" #n ")" ::: "memory")
; #define PG8_BAR __builtin_amdgcn_s_barrier()
; #define PG8_SCHED __builtin_amdgcn_sched_barrier(0)
;     ...
;             PG8_LDB(B0, 0, 0); PG8_LDB(B1, 0, 1); PG8_SCHED; PG8_LDA(At, 0, 0); PG8_STAGE(PG8_SA(1, 1), a1 + hstepA, voffA);
;             PG8_WAIT_V(8); PG8_WAIT_L(0); PG8_BAR; PG8_MMA(0, 0, At, B0); PG8_MMA(0, 1, At, B1); PG8_BAR; PG8_SCHED;
;             PG8_LDA(At, 0, 1); PG8_STAGE(PG8_SB(0, 0), b2, voffB); PG8_STAGE(PG8_SB(0, 1), b2 + hstepB, voffB); PG8_STAGE(PG8_SA(0, 0), a2, voffA);
;             PG8_WAIT_V(8); PG8_WAIT_L(0); PG8_BAR; PG8_MMA(1, 0, At, B0); PG8_MMA(1, 1, At, B1); PG8_BAR; PG8_SCHED;
;             PG8_LDB(B0, 1, 0); PG8_LDB(B1, 1, 1); PG8_SCHED; PG8_LDA(At, 1, 0); PG8_STAGE(PG8_SA(0, 1), a2 + hstepA, voffA);
;             PG8_WAIT_V(8); PG8_WAIT_L(0); PG8_BAR; PG8_MMA(0, 0, At, B0); PG8_MMA(0, 1, At, B1); PG8_BAR; PG8_SCHED;
;             PG8_LDA(At, 1, 1); PG8_STAGE(PG8_SB(1, 0), b3, voffB); PG8_STAGE(PG8_SB(1, 1), b3 + hstepB, voffB); PG8_STAGE(PG8_SA(1, 0), a3, voffA);
;             PG8_WAIT_V(8); PG8_WAIT_L(0); PG8_BAR; PG8_MMA(1, 0, At, B0); PG8_MMA(1, 1, At, B1); PG8_BAR; PG8_SCHED;
	s_setprio 0
	s_mov_b32 m0, s53
	v_lshl_add_u64 v[210:211], v[210:211], 0, s[18:19]
	s_add_u32 s30, s30, 0x10180
	ds_read_b128 v[178:181], v143 offset:49152
	ds_read_b128 v[182:185], v143 offset:50176
	ds_read_b128 v[186:189], v143 offset:51200
	ds_read_b128 v[190:193], v143 offset:52224
	ds_read_b128 v[194:197], v143 offset:53248
	ds_read_b128 v[198:201], v143 offset:54272
	ds_read_b128 v[202:205], v143 offset:55296
	ds_read_b128 v[206:209], v143 offset:56320
	global_load_lds_dwordx4 v[210:211], off
	v_lshl_add_u64 v[210:211], v[212:213], 0, s[18:19]
	s_mov_b32 m0, s54
	s_addc_u32 s31, s31, 0
	global_load_lds_dwordx4 v[210:211], off
	s_mov_b32 m0, s55
	s_nop 0
	global_load_lds_dwordx4 v132, s[30:31]
	s_mov_b32 m0, s56
	s_nop 0
	global_load_lds_dwordx4 v128, s[30:31]
	s_mov_b32 m0, s42
	s_nop 0
	global_load_lds_dwordx4 v134, s[34:35]
	s_mov_b32 m0, s43
	s_nop 0
	global_load_lds_dwordx4 v130, s[34:35]
	s_waitcnt vmcnt(8)
	s_waitcnt lgkmcnt(0)
	s_barrier
	s_setprio 1
	v_mfma_f32_16x16x32_bf16 v[0:3], v[24:27], v[202:205], v[0:3]
	v_mfma_f32_16x16x32_bf16 v[0:3], v[28:31], v[206:209], v[0:3]
	v_mfma_f32_16x16x32_bf16 v[4:7], v[116:119], v[206:209], v[4:7]
	v_mfma_f32_16x16x32_bf16 v[4:7], v[112:115], v[202:205], v[4:7]
	v_mfma_f32_16x16x32_bf16 v[150:153], v[112:115], v[178:181], v[150:153]
	v_mfma_f32_16x16x32_bf16 v[150:153], v[116:119], v[182:185], v[150:153]
	v_mfma_f32_16x16x32_bf16 v[146:149], v[28:31], v[182:185], v[146:149]
	v_mfma_f32_16x16x32_bf16 v[146:149], v[24:27], v[178:181], v[146:149]
	v_mfma_f32_16x16x32_bf16 v[154:157], v[24:27], v[186:189], v[154:157]
	v_mfma_f32_16x16x32_bf16 v[154:157], v[28:31], v[190:193], v[154:157]
	v_mfma_f32_16x16x32_bf16 v[158:161], v[116:119], v[190:193], v[158:161]
	v_mfma_f32_16x16x32_bf16 v[158:161], v[112:115], v[186:189], v[158:161]
	v_mfma_f32_16x16x32_bf16 v[166:169], v[112:115], v[194:197], v[166:169]
	v_mfma_f32_16x16x32_bf16 v[166:169], v[116:119], v[198:201], v[166:169]
	v_mfma_f32_16x16x32_bf16 v[162:165], v[28:31], v[198:201], v[162:165]
	v_mfma_f32_16x16x32_bf16 v[162:165], v[24:27], v[194:197], v[162:165]
	s_setprio 0
	s_setprio 1
	v_mfma_f32_16x16x32_bf16 v[8:11], v[120:123], v[178:181], v[8:11]
	v_mfma_f32_16x16x32_bf16 v[8:11], v[124:127], v[182:185], v[8:11]
	v_mfma_f32_16x16x32_bf16 v[12:15], v[170:173], v[178:181], v[12:15]
	v_mfma_f32_16x16x32_bf16 v[12:15], v[174:177], v[182:185], v[12:15]
	v_mfma_f32_16x16x32_bf16 v[24:27], v[120:123], v[186:189], v[60:63]
	v_mfma_f32_16x16x32_bf16 v[24:27], v[124:127], v[190:193], v[24:27]
	v_mfma_f32_16x16x32_bf16 v[28:31], v[170:173], v[186:189], v[100:103]
	v_mfma_f32_16x16x32_bf16 v[28:31], v[174:177], v[190:193], v[28:31]
	v_mfma_f32_16x16x32_bf16 v[60:63], v[120:123], v[194:197], v[104:107]
	v_mfma_f32_16x16x32_bf16 v[60:63], v[124:127], v[198:201], v[60:63]
	v_mfma_f32_16x16x32_bf16 v[100:103], v[170:173], v[194:197], v[108:111]
	v_mfma_f32_16x16x32_bf16 v[100:103], v[174:177], v[198:201], v[100:103]
	v_mfma_f32_16x16x32_bf16 v[16:19], v[120:123], v[202:205], v[16:19]
	v_mfma_f32_16x16x32_bf16 v[16:19], v[124:127], v[206:209], v[16:19]
	v_mfma_f32_16x16x32_bf16 v[20:23], v[170:173], v[202:205], v[20:23]
	v_mfma_f32_16x16x32_bf16 v[20:23], v[174:177], v[206:209], v[20:23]
	s_barrier
	s_setprio 0
	ds_read_b128 v[104:107], v141
	ds_read_b128 v[108:111], v141 offset:1024
	ds_read_b128 v[112:115], v141 offset:2048
	ds_read_b128 v[116:119], v141 offset:3072
	ds_read_b128 v[120:123], v142
	ds_read_b128 v[124:127], v142 offset:1024
	ds_read_b128 v[170:173], v142 offset:2048
	ds_read_b128 v[174:177], v142 offset:3072
	s_add_u32 s30, s28, 0x8000
	s_addc_u32 s31, s29, 0
	s_add_u32 s26, s26, 0x1c000
	s_addc_u32 s27, s27, 0
	s_mov_b32 m0, s46
	ds_read_b128 v[178:181], v143
	ds_read_b128 v[182:185], v143 offset:1024
	ds_read_b128 v[186:189], v143 offset:2048
	ds_read_b128 v[190:193], v143 offset:3072
	ds_read_b128 v[194:197], v143 offset:4096
	ds_read_b128 v[198:201], v143 offset:5120
	ds_read_b128 v[202:205], v143 offset:6144
	ds_read_b128 v[206:209], v143 offset:7168
	global_load_lds_dwordx4 v134, s[26:27]
	v_lshl_add_u64 v[210:211], s[26:27], 0, v[130:131]
	s_mov_b32 m0, s47
	s_nop 0
	global_load_lds_dwordx4 v[210:211], off
	s_waitcnt vmcnt(8)
	s_waitcnt lgkmcnt(0)
	s_barrier
	s_setprio 1
	v_mfma_f32_16x16x32_bf16 v[64:67], v[104:107], v[178:181], v[64:67]
	v_mfma_f32_16x16x32_bf16 v[64:67], v[108:111], v[182:185], v[64:67]
	v_mfma_f32_16x16x32_bf16 v[68:71], v[112:115], v[178:181], v[68:71]
	v_mfma_f32_16x16x32_bf16 v[68:71], v[116:119], v[182:185], v[68:71]
	v_mfma_f32_16x16x32_bf16 v[72:75], v[104:107], v[186:189], v[72:75]
	v_mfma_f32_16x16x32_bf16 v[72:75], v[108:111], v[190:193], v[72:75]
	v_mfma_f32_16x16x32_bf16 v[76:79], v[112:115], v[186:189], v[76:79]
	v_mfma_f32_16x16x32_bf16 v[76:79], v[116:119], v[190:193], v[76:79]
	v_mfma_f32_16x16x32_bf16 v[80:83], v[104:107], v[194:197], v[80:83]
	v_mfma_f32_16x16x32_bf16 v[80:83], v[108:111], v[198:201], v[80:83]
	v_mfma_f32_16x16x32_bf16 v[84:87], v[112:115], v[194:197], v[84:87]
	v_mfma_f32_16x16x32_bf16 v[84:87], v[116:119], v[198:201], v[84:87]
	v_mfma_f32_16x16x32_bf16 v[88:91], v[104:107], v[202:205], v[88:91]
	v_mfma_f32_16x16x32_bf16 v[210:213], v[108:111], v[206:209], v[88:91]
	v_mfma_f32_16x16x32_bf16 v[88:91], v[112:115], v[202:205], v[92:95]
	v_mfma_f32_16x16x32_bf16 v[214:217], v[116:119], v[206:209], v[88:91]
	s_setprio 0
	s_setprio 1
	v_mfma_f32_16x16x32_bf16 v[88:91], v[120:123], v[178:181], v[96:99]
	v_mfma_f32_16x16x32_bf16 v[96:99], v[124:127], v[182:185], v[88:91]
	v_mfma_f32_16x16x32_bf16 v[32:35], v[170:173], v[178:181], v[32:35]
	v_mfma_f32_16x16x32_bf16 v[32:35], v[174:177], v[182:185], v[32:35]
	v_mfma_f32_16x16x32_bf16 v[36:39], v[120:123], v[186:189], v[36:39]
	v_mfma_f32_16x16x32_bf16 v[36:39], v[124:127], v[190:193], v[36:39]
	v_mfma_f32_16x16x32_bf16 v[40:43], v[170:173], v[186:189], v[40:43]
	v_mfma_f32_16x16x32_bf16 v[40:43], v[174:177], v[190:193], v[40:43]
	v_mfma_f32_16x16x32_bf16 v[44:47], v[120:123], v[194:197], v[44:47]
	v_mfma_f32_16x16x32_bf16 v[44:47], v[124:127], v[198:201], v[44:47]
	v_mfma_f32_16x16x32_bf16 v[48:51], v[170:173], v[194:197], v[48:51]
	v_mfma_f32_16x16x32_bf16 v[48:51], v[174:177], v[198:201], v[48:51]
	v_mfma_f32_16x16x32_bf16 v[52:55], v[120:123], v[202:205], v[52:55]
	v_mfma_f32_16x16x32_bf16 v[52:55], v[124:127], v[206:209], v[52:55]
	v_mfma_f32_16x16x32_bf16 v[56:59], v[170:173], v[202:205], v[56:59]
	v_mfma_f32_16x16x32_bf16 v[56:59], v[174:177], v[206:209], v[56:59]
	s_barrier
; #define PG8_STAGE(bufoff, gbase, voff) do { _Pragma("unroll") for (int _i = 0; _i < 2; ++_i) \
;         __builtin_amdgcn_global_load_lds((const unsigned*)((const char*)(gbase) + (voff)[_i]), (PG8_LAS unsigned*)(lds + (bufoff) + ldsw + _i * 8192), 16, 0, 0); } while (0)
; #define PG8_LDA(dst, b, h) do { _Pragma("unroll") for (int m = 0; m < 4; ++m) _Pragma("unroll") for (int k = 0; k < 2; ++k) dst[m][k] = *(const PG8_LAS bf16x8*)(lds + PG8_SA(b, h) + aoff + m * 2048 + k * 1024); } while (0)
; #define PG8_LDB(dst, b, h) do { _Pragma("unroll") for (int n = 0; n < 2; ++n) _Pragma("unroll") for (int k = 0; k < 2; ++k) dst[n][k] = *(const PG8_LAS bf16x8*)(lds + PG8_SB(b, h) + boff + n * 2048 + k * 1024); } while (0)
; #define PG8_MMA(ai, bj, At, Bt) do { __builtin_amdgcn_s_setprio(1); _Pragma("unroll") for (int m = 0; m < 4; ++m) _Pragma("unroll") for (int n = 0; n < 2; ++n) _Pragma("unroll") for (int k = 0; k < 2; ++k) \
;         acc[ai][bj][m][n] = __builtin_amdgcn_mfma_f32_16x16x32_bf16(Bt[n][k], At[m][k], acc[ai][bj][m][n], 0, 0, 0); __builtin_amdgcn_s_setprio(0); } while (0)
; #define PG8_WAIT_V(n) asm volatile("s_waitcnt vmcnt(" #n ")" ::: "memory")
; #define PG8_WAIT_L(n) asm volatile("s_waitcnt lgkmcnt(" #n ")" ::: "memory")
; #define PG8_BAR __builtin_amdgcn_s_barrier()
; #define PG8_SCHED __builtin_amdgcn_sched_barrier(0)
;     ...
;             PG8_LDA(At, 0, 1); PG8_STAGE(PG8_SB(0, 0), b2, voffB); PG8_STAGE(PG8_SB(0, 1), b2 + hstepB, voffB); PG8_STAGE(PG8_SA(0, 0), a2, voffA);
;             PG8_WAIT_V(8); PG8_WAIT_L(0); PG8_BAR; PG8_MMA(1, 0, At, B0); PG8_MMA(1, 1, At, B1); PG8_BAR; PG8_SCHED;
;             PG8_LDB(B0, 1, 0); PG8_LDB(B1, 1, 1); PG8_SCHED; PG8_LDA(At, 1, 0); PG8_STAGE(PG8_SA(0, 1), a2 + hstepA, voffA);
;             PG8_WAIT_V(8); PG8_WAIT_L(0); PG8_BAR; PG8_MMA(0, 0, At, B0); PG8_MMA(0, 1, At, B1); PG8_BAR; PG8_SCHED;
	s_setprio 0
	s_mov_b32 m0, s48
	v_lshl_add_u64 v[246:247], s[24:25], 0, v[132:133]
	s_add_u32 s26, s24, 0x10000
	ds_read_b128 v[88:91], v143 offset:16384
	ds_read_b128 v[92:95], v143 offset:17408
	ds_read_b128 v[178:181], v143 offset:18432
	ds_read_b128 v[182:185], v143 offset:19456
	ds_read_b128 v[186:189], v143 offset:20480
	ds_read_b128 v[190:193], v143 offset:21504
	ds_read_b128 v[194:197], v143 offset:22528
	ds_read_b128 v[198:201], v143 offset:23552
	global_load_lds_dwordx4 v[246:247], off
	v_lshl_add_u64 v[248:249], s[24:25], 0, v[128:129]
	s_mov_b32 m0, s50
	s_addc_u32 s27, s25, 0
	global_load_lds_dwordx4 v[248:249], off
	s_mov_b32 m0, s51
	s_nop 0
	global_load_lds_dwordx4 v132, s[26:27]
	s_mov_b32 m0, s52
	s_nop 0
	global_load_lds_dwordx4 v128, s[26:27]
	s_mov_b32 m0, s23
	s_nop 0
	global_load_lds_dwordx4 v134, s[28:29]
	v_lshl_add_u64 v[202:203], s[28:29], 0, v[130:131]
	s_mov_b32 m0, s37
	s_nop 0
	global_load_lds_dwordx4 v[202:203], off
	s_waitcnt vmcnt(8)
	s_waitcnt lgkmcnt(0)
	s_barrier
	s_setprio 1
	v_mfma_f32_16x16x32_bf16 v[0:3], v[104:107], v[194:197], v[0:3]
	v_mfma_f32_16x16x32_bf16 v[0:3], v[108:111], v[198:201], v[0:3]
	v_mfma_f32_16x16x32_bf16 v[4:7], v[116:119], v[198:201], v[4:7]
	v_mfma_f32_16x16x32_bf16 v[4:7], v[112:115], v[194:197], v[4:7]
	v_mfma_f32_16x16x32_bf16 v[150:153], v[112:115], v[88:91], v[150:153]
	v_mfma_f32_16x16x32_bf16 v[150:153], v[116:119], v[92:95], v[150:153]
	v_mfma_f32_16x16x32_bf16 v[146:149], v[108:111], v[92:95], v[146:149]
	v_mfma_f32_16x16x32_bf16 v[146:149], v[104:107], v[88:91], v[146:149]
	v_mfma_f32_16x16x32_bf16 v[154:157], v[104:107], v[178:181], v[154:157]
	v_mfma_f32_16x16x32_bf16 v[154:157], v[108:111], v[182:185], v[154:157]
	v_mfma_f32_16x16x32_bf16 v[158:161], v[116:119], v[182:185], v[158:161]
	v_mfma_f32_16x16x32_bf16 v[158:161], v[112:115], v[178:181], v[158:161]
	v_mfma_f32_16x16x32_bf16 v[166:169], v[112:115], v[186:189], v[166:169]
	v_mfma_f32_16x16x32_bf16 v[166:169], v[116:119], v[190:193], v[166:169]
	v_mfma_f32_16x16x32_bf16 v[162:165], v[108:111], v[190:193], v[162:165]
	v_mfma_f32_16x16x32_bf16 v[162:165], v[104:107], v[186:189], v[162:165]
	s_setprio 0
	s_setprio 1
	v_mfma_f32_16x16x32_bf16 v[8:11], v[120:123], v[88:91], v[8:11]
	v_mfma_f32_16x16x32_bf16 v[202:205], v[124:127], v[92:95], v[8:11]
	v_mfma_f32_16x16x32_bf16 v[8:11], v[170:173], v[88:91], v[12:15]
	v_mfma_f32_16x16x32_bf16 v[206:209], v[174:177], v[92:95], v[8:11]
	v_mfma_f32_16x16x32_bf16 v[8:11], v[120:123], v[178:181], v[24:27]
	v_mfma_f32_16x16x32_bf16 v[218:221], v[124:127], v[182:185], v[8:11]
	v_mfma_f32_16x16x32_bf16 v[8:11], v[170:173], v[178:181], v[28:31]
	v_mfma_f32_16x16x32_bf16 v[178:181], v[174:177], v[182:185], v[8:11]
	v_mfma_f32_16x16x32_bf16 v[8:11], v[120:123], v[186:189], v[60:63]
	v_mfma_f32_16x16x32_bf16 v[182:185], v[124:127], v[190:193], v[8:11]
	v_mfma_f32_16x16x32_bf16 v[8:11], v[170:173], v[186:189], v[100:103]
	v_mfma_f32_16x16x32_bf16 v[186:189], v[174:177], v[190:193], v[8:11]
	v_mfma_f32_16x16x32_bf16 v[8:11], v[120:123], v[194:197], v[16:19]
	v_mfma_f32_16x16x32_bf16 v[190:193], v[124:127], v[198:201], v[8:11]
	v_mfma_f32_16x16x32_bf16 v[8:11], v[170:173], v[194:197], v[20:23]
	v_mfma_f32_16x16x32_bf16 v[170:173], v[174:177], v[198:201], v[8:11]
	s_barrier
	s_setprio 0
	s_nop 4
	ds_read_b128 v[8:11], v144
	ds_read_b128 v[12:15], v144 offset:1024
	ds_read_b128 v[16:19], v144 offset:2048
	ds_read_b128 v[20:23], v144 offset:3072
	ds_read_b128 v[174:177], v145
	ds_read_b128 v[194:197], v145 offset:1024
	ds_read_b128 v[198:201], v145 offset:2048
	ds_read_b128 v[222:225], v145 offset:3072
	s_add_u32 s26, s28, 0x4000
	s_addc_u32 s27, s29, 0
	s_mov_b32 m0, s39
	ds_read_b128 v[24:27], v143 offset:32768
	ds_read_b128 v[28:31], v143 offset:33792
	ds_read_b128 v[60:63], v143 offset:34816
	ds_read_b128 v[226:229], v143 offset:35840
	ds_read_b128 v[230:233], v143 offset:36864
	ds_read_b128 v[234:237], v143 offset:37888
	ds_read_b128 v[238:241], v143 offset:38912
	ds_read_b128 v[242:245], v143 offset:39936
	global_load_lds_dwordx4 v134, s[26:27]
	v_lshl_add_u64 v[88:89], s[26:27], 0, v[130:131]
	s_mov_b32 m0, s40
	s_nop 0
	global_load_lds_dwordx4 v[88:89], off
	s_waitcnt vmcnt(8)
	s_waitcnt lgkmcnt(0)
	s_barrier
; #define PG8_STAGE(bufoff, gbase, voff) do { _Pragma("unroll") for (int _i = 0; _i < 2; ++_i) \
;         __builtin_amdgcn_global_load_lds((const unsigned*)((const char*)(gbase) + (voff)[_i]), (PG8_LAS unsigned*)(lds + (bufoff) + ldsw + _i * 8192), 16, 0, 0); } while (0)
; #define PG8_LDA(dst, b, h) do { _Pragma("unroll") for (int m = 0; m < 4; ++m) _Pragma("unroll") for (int k = 0; k < 2; ++k) dst[m][k] = *(const PG8_LAS bf16x8*)(lds + PG8_SA(b, h) + aoff + m * 2048 + k * 1024); } while (0)
; #define PG8_MMA(ai, bj, At, Bt) do { __builtin_amdgcn_s_setprio(1); _Pragma("unroll") for (int m = 0; m < 4; ++m) _Pragma("unroll") for (int n = 0; n < 2; ++n) _Pragma("unroll") for (int k = 0; k < 2; ++k) \
;         acc[ai][bj][m][n] = __builtin_amdgcn_mfma_f32_16x16x32_bf16(Bt[n][k], At[m][k], acc[ai][bj][m][n], 0, 0, 0); __builtin_amdgcn_s_setprio(0); } while (0)
; #define PG8_WAIT_V(n) asm volatile("s_waitcnt vmcnt(" #n ")" ::: "memory")
; #define PG8_WAIT_L(n) asm volatile("s_waitcnt lgkmcnt(" #n ")" ::: "memory")
; #define PG8_BAR __builtin_amdgcn_s_barrier()
; #define PG8_SCHED __builtin_amdgcn_sched_barrier(0)
;     ...
;             PG8_WAIT_V(8); PG8_WAIT_L(0); PG8_BAR; PG8_MMA(0, 0, At, B0); PG8_MMA(0, 1, At, B1); PG8_BAR; PG8_SCHED;
;             PG8_LDA(At, 1, 1); PG8_STAGE(PG8_SB(1, 0), b3, voffB); PG8_STAGE(PG8_SB(1, 1), b3 + hstepB, voffB); PG8_STAGE(PG8_SA(1, 0), a3, voffA);
;             PG8_WAIT_V(8); PG8_WAIT_L(0); PG8_BAR; PG8_MMA(1, 0, At, B0); PG8_MMA(1, 1, At, B1); PG8_BAR; PG8_SCHED;
;     ...
;         if constexpr (ALIGN_EPI) { if (wr == 0) PG8_BAR; }
	s_setprio 1
	v_mfma_f32_16x16x32_bf16 v[64:67], v[8:11], v[24:27], v[64:67]
	v_mfma_f32_16x16x32_bf16 v[124:127], v[12:15], v[28:31], v[64:67]
	v_mfma_f32_16x16x32_bf16 v[64:67], v[16:19], v[24:27], v[68:71]
	v_mfma_f32_16x16x32_bf16 v[120:123], v[20:23], v[28:31], v[64:67]
	v_mfma_f32_16x16x32_bf16 v[64:67], v[8:11], v[60:63], v[72:75]
	v_mfma_f32_16x16x32_bf16 v[108:111], v[12:15], v[226:229], v[64:67]
	v_mfma_f32_16x16x32_bf16 v[64:67], v[16:19], v[60:63], v[76:79]
	v_mfma_f32_16x16x32_bf16 v[104:107], v[20:23], v[226:229], v[64:67]
	v_mfma_f32_16x16x32_bf16 v[64:67], v[8:11], v[230:233], v[80:83]
	v_mfma_f32_16x16x32_bf16 v[92:95], v[12:15], v[234:237], v[64:67]
	v_mfma_f32_16x16x32_bf16 v[64:67], v[16:19], v[230:233], v[84:87]
	v_mfma_f32_16x16x32_bf16 v[88:91], v[20:23], v[234:237], v[64:67]
	v_mfma_f32_16x16x32_bf16 v[64:67], v[8:11], v[238:241], v[210:213]
	v_mfma_f32_16x16x32_bf16 v[76:79], v[12:15], v[242:245], v[64:67]
	v_mfma_f32_16x16x32_bf16 v[64:67], v[16:19], v[238:241], v[214:217]
	v_mfma_f32_16x16x32_bf16 v[72:75], v[20:23], v[242:245], v[64:67]
	s_setprio 0
	s_setprio 1
	v_mfma_f32_16x16x32_bf16 v[64:67], v[174:177], v[24:27], v[96:99]
	v_mfma_f32_16x16x32_bf16 v[24:27], v[198:201], v[24:27], v[32:35]
	v_mfma_f32_16x16x32_bf16 v[112:115], v[222:225], v[28:31], v[24:27]
	v_mfma_f32_16x16x32_bf16 v[24:27], v[174:177], v[60:63], v[36:39]
	v_mfma_f32_16x16x32_bf16 v[100:103], v[194:197], v[226:229], v[24:27]
	v_mfma_f32_16x16x32_bf16 v[24:27], v[198:201], v[60:63], v[40:43]
	v_mfma_f32_16x16x32_bf16 v[96:99], v[222:225], v[226:229], v[24:27]
	v_mfma_f32_16x16x32_bf16 v[24:27], v[174:177], v[230:233], v[44:47]
	v_mfma_f32_16x16x32_bf16 v[84:87], v[194:197], v[234:237], v[24:27]
	v_mfma_f32_16x16x32_bf16 v[24:27], v[198:201], v[230:233], v[48:51]
	v_mfma_f32_16x16x32_bf16 v[80:83], v[222:225], v[234:237], v[24:27]
	v_mfma_f32_16x16x32_bf16 v[24:27], v[174:177], v[238:241], v[52:55]
	v_mfma_f32_16x16x32_bf16 v[60:63], v[194:197], v[242:245], v[24:27]
	v_mfma_f32_16x16x32_bf16 v[24:27], v[198:201], v[238:241], v[56:59]
	v_mfma_f32_16x16x32_bf16 v[116:119], v[194:197], v[28:31], v[64:67]
	v_mfma_f32_16x16x32_bf16 v[56:59], v[222:225], v[242:245], v[24:27]
	s_barrier
	s_setprio 0
	s_mov_b32 m0, s53
	s_nop 2
	v_lshl_add_u64 v[24:25], v[246:247], 0, s[12:13]
	s_add_u32 s24, s24, 0x10080
	ds_read_b128 v[32:35], v143 offset:49152
	ds_read_b128 v[36:39], v143 offset:50176
	ds_read_b128 v[210:213], v143 offset:51200
	ds_read_b128 v[214:217], v143 offset:52224
	ds_read_b128 v[226:229], v143 offset:53248
	ds_read_b128 v[230:233], v143 offset:54272
	ds_read_b128 v[234:237], v143 offset:55296
	ds_read_b128 v[238:241], v143 offset:56320
	global_load_lds_dwordx4 v[24:25], off
	v_lshl_add_u64 v[24:25], v[248:249], 0, s[12:13]
	s_mov_b32 m0, s54
	s_addc_u32 s25, s25, 0
	global_load_lds_dwordx4 v[24:25], off
	s_mov_b32 m0, s55
	s_nop 0
	global_load_lds_dwordx4 v132, s[24:25]
	s_mov_b32 m0, s56
	s_nop 0
	global_load_lds_dwordx4 v128, s[24:25]
	s_mov_b32 m0, s42
	s_nop 0
	global_load_lds_dwordx4 v134, s[30:31]
	v_lshl_add_u64 v[24:25], s[30:31], 0, v[130:131]
	s_mov_b32 m0, s43
	s_nop 0
	global_load_lds_dwordx4 v[24:25], off
	s_waitcnt vmcnt(8)
	s_waitcnt lgkmcnt(0)
	s_barrier
	s_setprio 1
	v_mfma_f32_16x16x32_bf16 v[24:27], v[8:11], v[32:35], v[146:149]
	v_mfma_f32_16x16x32_bf16 v[68:71], v[12:15], v[36:39], v[24:27]
	v_mfma_f32_16x16x32_bf16 v[24:27], v[16:19], v[32:35], v[150:153]
	v_mfma_f32_16x16x32_bf16 v[64:67], v[20:23], v[36:39], v[24:27]
	v_mfma_f32_16x16x32_bf16 v[24:27], v[8:11], v[210:213], v[154:157]
	v_mfma_f32_16x16x32_bf16 v[44:47], v[12:15], v[214:217], v[24:27]
	v_mfma_f32_16x16x32_bf16 v[24:27], v[16:19], v[210:213], v[158:161]
	v_mfma_f32_16x16x32_bf16 v[40:43], v[20:23], v[214:217], v[24:27]
	v_mfma_f32_16x16x32_bf16 v[24:27], v[8:11], v[226:229], v[162:165]
	v_mfma_f32_16x16x32_bf16 v[28:31], v[12:15], v[230:233], v[24:27]
	v_mfma_f32_16x16x32_bf16 v[0:3], v[8:11], v[234:237], v[0:3]
	v_mfma_f32_16x16x32_bf16 v[12:15], v[12:15], v[238:241], v[0:3]
	v_mfma_f32_16x16x32_bf16 v[24:27], v[16:19], v[226:229], v[166:169]
	v_mfma_f32_16x16x32_bf16 v[24:27], v[20:23], v[230:233], v[24:27]
	v_mfma_f32_16x16x32_bf16 v[0:3], v[16:19], v[234:237], v[4:7]
	v_mfma_f32_16x16x32_bf16 v[8:11], v[20:23], v[238:241], v[0:3]
	s_setprio 0
	s_setprio 1
	v_mfma_f32_16x16x32_bf16 v[0:3], v[174:177], v[32:35], v[202:205]
	v_mfma_f32_16x16x32_bf16 v[52:55], v[194:197], v[36:39], v[0:3]
	v_mfma_f32_16x16x32_bf16 v[0:3], v[198:201], v[32:35], v[206:209]
	v_mfma_f32_16x16x32_bf16 v[48:51], v[222:225], v[36:39], v[0:3]
	v_mfma_f32_16x16x32_bf16 v[0:3], v[174:177], v[210:213], v[218:221]
	v_mfma_f32_16x16x32_bf16 v[36:39], v[194:197], v[214:217], v[0:3]
	v_mfma_f32_16x16x32_bf16 v[0:3], v[198:201], v[210:213], v[178:181]
	v_mfma_f32_16x16x32_bf16 v[32:35], v[222:225], v[214:217], v[0:3]
	v_mfma_f32_16x16x32_bf16 v[0:3], v[174:177], v[226:229], v[182:185]
	v_mfma_f32_16x16x32_bf16 v[20:23], v[194:197], v[230:233], v[0:3]
	v_mfma_f32_16x16x32_bf16 v[0:3], v[198:201], v[226:229], v[186:189]
	v_mfma_f32_16x16x32_bf16 v[16:19], v[222:225], v[230:233], v[0:3]
	v_mfma_f32_16x16x32_bf16 v[0:3], v[174:177], v[234:237], v[190:193]
	v_mfma_f32_16x16x32_bf16 v[4:7], v[194:197], v[238:241], v[0:3]
	v_mfma_f32_16x16x32_bf16 v[0:3], v[198:201], v[234:237], v[170:173]
	v_mfma_f32_16x16x32_bf16 v[0:3], v[222:225], v[238:241], v[0:3]
	s_barrier
	s_setprio 0
	s_and_b64 vcc, exec, s[0:1]
	s_cbranch_vccnz .LBB0_99
	s_barrier

; #define PG8_STAGE(bufoff, gbase, voff) do { _Pragma("unroll") for (int _i = 0; _i < 2; ++_i) \
;         __builtin_amdgcn_global_load_lds((const unsigned*)((const char*)(gbase) + (voff)[_i]), (PG8_LAS unsigned*)(lds + (bufoff) + ldsw + _i * 8192), 16, 0, 0); } while (0)
; #define PG8_LDA(dst, b, h) do { _Pragma("unroll") for (int m = 0; m < 4; ++m) _Pragma("unroll") for (int k = 0; k < 2; ++k) dst[m][k] = *(const PG8_LAS bf16x8*)(lds + PG8_SA(b, h) + aoff + m * 2048 + k * 1024); } while (0)
; #define PG8_LDB(dst, b, h) do { _Pragma("unroll") for (int n = 0; n < 2; ++n) _Pragma("unroll") for (int k = 0; k < 2; ++k) dst[n][k] = *(const PG8_LAS bf16x8*)(lds + PG8_SB(b, h) + boff + n * 2048 + k * 1024); } while (0)
; #define PG8_MMA(ai, bj, At, Bt) do { __builtin_amdgcn_s_setprio(1); _Pragma("unroll") for (int m = 0; m < 4; ++m) _Pragma("unroll") for (int n = 0; n < 2; ++n) _Pragma("unroll") for (int k = 0; k < 2; ++k) \
;         acc[ai][bj][m][n] = __builtin_amdgcn_mfma_f32_16x16x32_bf16(Bt[n][k], At[m][k], acc[ai][bj][m][n], 0, 0, 0); __builtin_amdgcn_s_setprio(0); } while (0)
; #define PG8_WAIT_V(n) asm volatile("s_waitcnt vmcnt(" #n ")" ::: "memory")
; #define PG8_WAIT_L(n) asm volatile("s_waitcnt lgkmcnt(" #n ")" ::: "memory")
; #define PG8_BAR __builtin_amdgcn_s_barrier()
; #define PG8_SCHED __builtin_amdgcn_sched_barrier(0)
;     ...
;             const bool last = (t == nt - 2);
;             const char* a1 = cA + (ptrdiff_t)(t + 1) * kstepA;
;             const char* a2 = last ? nA : cA + (ptrdiff_t)(t + 2) * kstepA; const char* b2 = last ? nB : cB + (ptrdiff_t)(t + 2) * kstep;
;             const char* a3 = a2 + kstepA; const char* b3 = b2 + kstep;
;             if (last && has_next) S.a_ready(nxt);
;             if constexpr (SP2) {
;             PG8_LDB(B0, 0, 0); PG8_LDB(B1, 0, 1); PG8_SCHED; PG8_LDA(At, 0, 0); PG8_STAGE(PG8_SA(1, 1), a1 + hstepA, voffA);
;             PG8_WAIT_V(8); PG8_WAIT_L(0); PG8_BAR; PG8_MMA(0, 0, At, B0); PG8_MMA(0, 1, At, B1); PG8_BAR; PG8_SCHED;
;             PG8_LDA(At, 0, 1); PG8_STAGE(PG8_SB(0, 0), b2, voffB); PG8_STAGE(PG8_SB(0, 1), b2 + hstepB, voffB); PG8_STAGE(PG8_SA(0, 0), a2, voffA);
;             PG8_WAIT_V(8); PG8_WAIT_L(0); PG8_BAR; PG8_MMA(1, 0, At, B0); PG8_MMA(1, 1, At, B1); PG8_BAR; PG8_SCHED;
.Lin_nostg:
	s_add_u32 s65, s6, 0x4000
	s_addc_u32 s66, s7, 0
	s_cmp_eq_u32 vcc_lo, 28
	s_cselect_b32 s90, s54, s65
	s_cselect_b32 s91, s29, s66
	s_cselect_b32 s88, s55, s56
	s_cselect_b32 s89, s31, s57
	s_add_u32 s86, s90, 0x8000
	s_addc_u32 s87, s91, 0
	s_add_i32 s65, 0, 0x10000
	s_add_i32 s66, 0, 0x14000
	v_add_u32_e32 v22, s65, v182
	v_add_u32_e32 v54, s66, v182
	ds_read_b128 v[10:13], v22
	ds_read_b128 v[14:17], v22 offset:1024
	ds_read_b128 v[18:21], v22 offset:2048
	ds_read_b128 v[22:25], v22 offset:3072
	ds_read_b128 v[26:29], v54
	ds_read_b128 v[38:41], v54 offset:1024
	ds_read_b128 v[50:53], v54 offset:2048
	ds_read_b128 v[54:57], v54 offset:3072
	s_add_i32 m0, s51, 0xc000
	ds_read_b128 v[172:175], v183
	ds_read_b128 v[176:179], v183 offset:1024
	ds_read_b128 v[184:187], v183 offset:2048
	ds_read_b128 v[188:191], v183 offset:3072
	ds_read_b128 v[192:195], v183 offset:4096
	ds_read_b128 v[196:199], v183 offset:5120
	ds_read_b128 v[200:203], v183 offset:6144
	ds_read_b128 v[204:207], v183 offset:7168
	global_load_lds_dwordx4 v168, s[6:7]
	s_add_i32 m0, s51, 0xe000
	s_nop 0
	global_load_lds_dwordx4 v170, s[6:7]
	s_waitcnt vmcnt(8)
	s_waitcnt lgkmcnt(0)
	s_barrier
	s_setprio 1
	v_mfma_f32_16x16x32_bf16 v[158:161], v[10:13], v[172:175], 0
	v_mfma_f32_16x16x32_bf16 v[158:161], v[14:17], v[176:179], v[158:161]
	v_mfma_f32_16x16x32_bf16 v[154:157], v[22:25], v[176:179], 0
	v_mfma_f32_16x16x32_bf16 v[154:157], v[18:21], v[172:175], v[154:157]
	v_mfma_f32_16x16x32_bf16 v[138:141], v[18:21], v[184:187], 0
	v_mfma_f32_16x16x32_bf16 v[138:141], v[22:25], v[188:191], v[138:141]
	v_mfma_f32_16x16x32_bf16 v[142:145], v[14:17], v[188:191], 0
	v_mfma_f32_16x16x32_bf16 v[142:145], v[10:13], v[184:187], v[142:145]
	v_mfma_f32_16x16x32_bf16 v[126:129], v[10:13], v[192:195], 0
	v_mfma_f32_16x16x32_bf16 v[126:129], v[14:17], v[196:199], v[126:129]
	v_mfma_f32_16x16x32_bf16 v[122:125], v[22:25], v[196:199], 0
	v_mfma_f32_16x16x32_bf16 v[122:125], v[18:21], v[192:195], v[122:125]
	v_mfma_f32_16x16x32_bf16 v[106:109], v[18:21], v[200:203], 0
	v_mfma_f32_16x16x32_bf16 v[106:109], v[22:25], v[204:207], v[106:109]
	v_mfma_f32_16x16x32_bf16 v[110:113], v[14:17], v[204:207], 0
	v_mfma_f32_16x16x32_bf16 v[110:113], v[10:13], v[200:203], v[110:113]
	s_setprio 0
	s_setprio 1
	v_mfma_f32_16x16x32_bf16 v[150:153], v[26:29], v[172:175], 0
	v_mfma_f32_16x16x32_bf16 v[150:153], v[38:41], v[176:179], v[150:153]
	v_mfma_f32_16x16x32_bf16 v[146:149], v[54:57], v[176:179], 0
	v_mfma_f32_16x16x32_bf16 v[146:149], v[50:53], v[172:175], v[146:149]
	v_mfma_f32_16x16x32_bf16 v[130:133], v[50:53], v[184:187], 0
	v_mfma_f32_16x16x32_bf16 v[130:133], v[54:57], v[188:191], v[130:133]
	v_mfma_f32_16x16x32_bf16 v[134:137], v[38:41], v[188:191], 0
	v_mfma_f32_16x16x32_bf16 v[134:137], v[26:29], v[184:187], v[134:137]
	v_mfma_f32_16x16x32_bf16 v[118:121], v[26:29], v[192:195], 0
	v_mfma_f32_16x16x32_bf16 v[118:121], v[38:41], v[196:199], v[118:121]
	v_mfma_f32_16x16x32_bf16 v[114:117], v[54:57], v[196:199], 0
	v_mfma_f32_16x16x32_bf16 v[114:117], v[50:53], v[192:195], v[114:117]
	v_mfma_f32_16x16x32_bf16 v[98:101], v[50:53], v[200:203], 0
	v_mfma_f32_16x16x32_bf16 v[98:101], v[54:57], v[204:207], v[98:101]
	v_mfma_f32_16x16x32_bf16 v[102:105], v[38:41], v[204:207], 0
	v_mfma_f32_16x16x32_bf16 v[102:105], v[26:29], v[200:203], v[102:105]
	s_barrier
	s_setprio 0
	s_add_i32 s65, s65, s2
	s_mov_b32 m0, s65
	ds_read_b128 v[172:175], v183 offset:16384
	ds_read_b128 v[176:179], v183 offset:17408
	ds_read_b128 v[184:187], v183 offset:18432
	ds_read_b128 v[188:191], v183 offset:19456
	ds_read_b128 v[192:195], v183 offset:20480
	ds_read_b128 v[196:199], v183 offset:21504
	ds_read_b128 v[200:203], v183 offset:22528
	ds_read_b128 v[204:207], v183 offset:23552
	global_load_lds_dwordx4 v0, s[88:89]
	s_add_i32 m0, s65, 0x2000
	s_add_u32 s96, s88, 0x4000
	s_addc_u32 s97, s89, 0
	s_add_i32 s65, s66, s2
	global_load_lds_dwordx4 v162, s[88:89]
	s_mov_b32 m0, s65
	s_nop 0
	global_load_lds_dwordx4 v0, s[96:97]
	s_add_i32 m0, s65, 0x2000
	s_nop 0
	global_load_lds_dwordx4 v162, s[96:97]
	s_mov_b32 m0, s51
	s_nop 0
	global_load_lds_dwordx4 v166, s[90:91]
	s_mov_b32 m0, s92
	s_nop 0
	global_load_lds_dwordx4 v164, s[90:91]
	s_waitcnt vmcnt(8)
	s_waitcnt lgkmcnt(0)
	s_barrier
	s_setprio 1
	v_mfma_f32_16x16x32_bf16 v[94:97], v[10:13], v[172:175], 0
	v_mfma_f32_16x16x32_bf16 v[94:97], v[14:17], v[176:179], v[94:97]
	v_mfma_f32_16x16x32_bf16 v[90:93], v[18:21], v[172:175], 0
	v_mfma_f32_16x16x32_bf16 v[90:93], v[22:25], v[176:179], v[90:93]
	v_mfma_f32_16x16x32_bf16 v[78:81], v[10:13], v[184:187], 0
	v_mfma_f32_16x16x32_bf16 v[78:81], v[14:17], v[188:191], v[78:81]
	v_mfma_f32_16x16x32_bf16 v[74:77], v[18:21], v[184:187], 0
	v_mfma_f32_16x16x32_bf16 v[74:77], v[22:25], v[188:191], v[74:77]
	v_mfma_f32_16x16x32_bf16 v[62:65], v[10:13], v[192:195], 0
	v_mfma_f32_16x16x32_bf16 v[62:65], v[14:17], v[196:199], v[62:65]
	v_mfma_f32_16x16x32_bf16 v[58:61], v[18:21], v[192:195], 0
	v_mfma_f32_16x16x32_bf16 v[58:61], v[22:25], v[196:199], v[58:61]
	v_mfma_f32_16x16x32_bf16 v[10:13], v[10:13], v[200:203], 0
	v_mfma_f32_16x16x32_bf16 v[10:13], v[14:17], v[204:207], v[10:13]
	v_mfma_f32_16x16x32_bf16 v[14:17], v[18:21], v[200:203], 0
	v_mfma_f32_16x16x32_bf16 v[14:17], v[22:25], v[204:207], v[14:17]
	s_setprio 0
	s_setprio 1
	v_mfma_f32_16x16x32_bf16 v[30:33], v[26:29], v[184:187], 0
	v_mfma_f32_16x16x32_bf16 v[70:73], v[38:41], v[188:191], v[30:33]
	v_mfma_f32_16x16x32_bf16 v[30:33], v[50:53], v[184:187], 0
	v_mfma_f32_16x16x32_bf16 v[66:69], v[54:57], v[188:191], v[30:33]
	v_mfma_f32_16x16x32_bf16 v[30:33], v[26:29], v[192:195], 0
	v_mfma_f32_16x16x32_bf16 v[46:49], v[38:41], v[196:199], v[30:33]
	v_mfma_f32_16x16x32_bf16 v[30:33], v[50:53], v[192:195], 0
	v_mfma_f32_16x16x32_bf16 v[42:45], v[54:57], v[196:199], v[30:33]
	v_mfma_f32_16x16x32_bf16 v[6:9], v[26:29], v[200:203], 0
	v_mfma_f32_16x16x32_bf16 v[6:9], v[38:41], v[204:207], v[6:9]
	v_mfma_f32_16x16x32_bf16 v[2:5], v[50:53], v[200:203], 0
	v_mfma_f32_16x16x32_bf16 v[2:5], v[54:57], v[204:207], v[2:5]
	v_mfma_f32_16x16x32_bf16 v[18:21], v[26:29], v[172:175], 0
	v_mfma_f32_16x16x32_bf16 v[18:21], v[38:41], v[176:179], v[18:21]
	v_mfma_f32_16x16x32_bf16 v[22:25], v[50:53], v[172:175], 0
	v_mfma_f32_16x16x32_bf16 v[22:25], v[54:57], v[176:179], v[22:25]
	s_barrier
	s_setprio 0
	s_branch .Lin_mid

; #define PG8_STAGE(bufoff, gbase, voff) do { _Pragma("unroll") for (int _i = 0; _i < 2; ++_i) \
;         __builtin_amdgcn_global_load_lds((const unsigned*)((const char*)(gbase) + (voff)[_i]), (PG8_LAS unsigned*)(lds + (bufoff) + ldsw + _i * 8192), 16, 0, 0); } while (0)
; #define PG8_LDA(dst, b, h) do { _Pragma("unroll") for (int m = 0; m < 4; ++m) _Pragma("unroll") for (int k = 0; k < 2; ++k) dst[m][k] = *(const PG8_LAS bf16x8*)(lds + PG8_SA(b, h) + aoff + m * 2048 + k * 1024); } while (0)
; #define PG8_LDB(dst, b, h) do { _Pragma("unroll") for (int n = 0; n < 2; ++n) _Pragma("unroll") for (int k = 0; k < 2; ++k) dst[n][k] = *(const PG8_LAS bf16x8*)(lds + PG8_SB(b, h) + boff + n * 2048 + k * 1024); } while (0)
; #define PG8_MMA(ai, bj, At, Bt) do { __builtin_amdgcn_s_setprio(1); _Pragma("unroll") for (int m = 0; m < 4; ++m) _Pragma("unroll") for (int n = 0; n < 2; ++n) _Pragma("unroll") for (int k = 0; k < 2; ++k) \
;         acc[ai][bj][m][n] = __builtin_amdgcn_mfma_f32_16x16x32_bf16(Bt[n][k], At[m][k], acc[ai][bj][m][n], 0, 0, 0); __builtin_amdgcn_s_setprio(0); } while (0)
; #define PG8_WAIT_V(n) asm volatile("s_waitcnt vmcnt(" #n ")" ::: "memory")
; #define PG8_WAIT_L(n) asm volatile("s_waitcnt lgkmcnt(" #n ")" ::: "memory")
; #define PG8_BAR __builtin_amdgcn_s_barrier()
; #define PG8_SCHED __builtin_amdgcn_sched_barrier(0)
;     ...
;             const bool last = (t == nt - 2);
;             const char* a1 = cA + (ptrdiff_t)(t + 1) * kstepA;
;             const char* a2 = last ? nA : cA + (ptrdiff_t)(t + 2) * kstepA; const char* b2 = last ? nB : cB + (ptrdiff_t)(t + 2) * kstep;
;             const char* a3 = a2 + kstepA; const char* b3 = b2 + kstep;
;             if (last && has_next) S.a_ready(nxt);
;             if constexpr (SP2) {
;             PG8_LDB(B0, 0, 0); PG8_LDB(B1, 0, 1); PG8_SCHED; PG8_LDA(At, 0, 0); PG8_STAGE(PG8_SA(1, 1), a1 + hstepA, voffA);
;             PG8_WAIT_V(8); PG8_WAIT_L(0); PG8_BAR; PG8_MMA(0, 0, At, B0); PG8_MMA(0, 1, At, B1); PG8_BAR; PG8_SCHED;
;             PG8_LDA(At, 0, 1); PG8_STAGE(PG8_SB(0, 0), b2, voffB); PG8_STAGE(PG8_SB(0, 1), b2 + hstepB, voffB); PG8_STAGE(PG8_SA(0, 0), a2, voffA);
;             PG8_WAIT_V(8); PG8_WAIT_L(0); PG8_BAR; PG8_MMA(1, 0, At, B0); PG8_MMA(1, 1, At, B1); PG8_BAR; PG8_SCHED;
.LBB0_328:
	s_add_u32 s65, s6, 0x4000
	s_addc_u32 s66, s7, 0
	s_cmp_eq_u32 vcc_lo, 28
	s_cselect_b32 s90, s54, s65
	s_cselect_b32 s91, s29, s66
	s_cselect_b32 s88, s55, s56
	s_cselect_b32 s89, s31, s57
	s_add_u32 s86, s90, 0x8000
	s_addc_u32 s87, s91, 0
	s_add_i32 s65, 0, 0x10000
	s_add_i32 s66, 0, 0x14000
	v_add_u32_e32 v22, s65, v182
	v_add_u32_e32 v54, s66, v182
	ds_read_b128 v[10:13], v22
	ds_read_b128 v[14:17], v22 offset:1024
	ds_read_b128 v[18:21], v22 offset:2048
	ds_read_b128 v[22:25], v22 offset:3072
	ds_read_b128 v[26:29], v54
	ds_read_b128 v[38:41], v54 offset:1024
	ds_read_b128 v[50:53], v54 offset:2048
	ds_read_b128 v[54:57], v54 offset:3072
	s_add_i32 m0, s51, 0xc000
	ds_read_b128 v[172:175], v183
	ds_read_b128 v[176:179], v183 offset:1024
	ds_read_b128 v[184:187], v183 offset:2048
	ds_read_b128 v[188:191], v183 offset:3072
	ds_read_b128 v[192:195], v183 offset:4096
	ds_read_b128 v[196:199], v183 offset:5120
	ds_read_b128 v[200:203], v183 offset:6144
	ds_read_b128 v[204:207], v183 offset:7168
	global_load_lds_dwordx4 v168, s[6:7]
	s_add_i32 m0, s51, 0xe000
	s_nop 0
	global_load_lds_dwordx4 v170, s[6:7]
	s_waitcnt vmcnt(8)
	s_waitcnt lgkmcnt(0)
	s_barrier
	s_setprio 1
	v_mfma_f32_16x16x32_bf16 v[158:161], v[10:13], v[172:175], v[158:161]
	v_mfma_f32_16x16x32_bf16 v[158:161], v[14:17], v[176:179], v[158:161]
	v_mfma_f32_16x16x32_bf16 v[154:157], v[22:25], v[176:179], v[154:157]
	v_mfma_f32_16x16x32_bf16 v[154:157], v[18:21], v[172:175], v[154:157]
	v_mfma_f32_16x16x32_bf16 v[138:141], v[18:21], v[184:187], v[138:141]
	v_mfma_f32_16x16x32_bf16 v[138:141], v[22:25], v[188:191], v[138:141]
	v_mfma_f32_16x16x32_bf16 v[142:145], v[14:17], v[188:191], v[142:145]
	v_mfma_f32_16x16x32_bf16 v[142:145], v[10:13], v[184:187], v[142:145]
	v_mfma_f32_16x16x32_bf16 v[126:129], v[10:13], v[192:195], v[126:129]
	v_mfma_f32_16x16x32_bf16 v[126:129], v[14:17], v[196:199], v[126:129]
	v_mfma_f32_16x16x32_bf16 v[122:125], v[22:25], v[196:199], v[122:125]
	v_mfma_f32_16x16x32_bf16 v[122:125], v[18:21], v[192:195], v[122:125]
	v_mfma_f32_16x16x32_bf16 v[106:109], v[18:21], v[200:203], v[106:109]
	v_mfma_f32_16x16x32_bf16 v[106:109], v[22:25], v[204:207], v[106:109]
	v_mfma_f32_16x16x32_bf16 v[110:113], v[14:17], v[204:207], v[110:113]
	v_mfma_f32_16x16x32_bf16 v[110:113], v[10:13], v[200:203], v[110:113]
	s_setprio 0
	s_setprio 1
	v_mfma_f32_16x16x32_bf16 v[150:153], v[26:29], v[172:175], v[150:153]
	v_mfma_f32_16x16x32_bf16 v[150:153], v[38:41], v[176:179], v[150:153]
	v_mfma_f32_16x16x32_bf16 v[146:149], v[54:57], v[176:179], v[146:149]
	v_mfma_f32_16x16x32_bf16 v[146:149], v[50:53], v[172:175], v[146:149]
	v_mfma_f32_16x16x32_bf16 v[130:133], v[50:53], v[184:187], v[130:133]
	v_mfma_f32_16x16x32_bf16 v[130:133], v[54:57], v[188:191], v[130:133]
	v_mfma_f32_16x16x32_bf16 v[134:137], v[38:41], v[188:191], v[134:137]
	v_mfma_f32_16x16x32_bf16 v[134:137], v[26:29], v[184:187], v[134:137]
	v_mfma_f32_16x16x32_bf16 v[118:121], v[26:29], v[192:195], v[118:121]
	v_mfma_f32_16x16x32_bf16 v[118:121], v[38:41], v[196:199], v[118:121]
	v_mfma_f32_16x16x32_bf16 v[114:117], v[54:57], v[196:199], v[114:117]
	v_mfma_f32_16x16x32_bf16 v[114:117], v[50:53], v[192:195], v[114:117]
	v_mfma_f32_16x16x32_bf16 v[98:101], v[50:53], v[200:203], v[98:101]
	v_mfma_f32_16x16x32_bf16 v[98:101], v[54:57], v[204:207], v[98:101]
	v_mfma_f32_16x16x32_bf16 v[102:105], v[38:41], v[204:207], v[102:105]
	v_mfma_f32_16x16x32_bf16 v[102:105], v[26:29], v[200:203], v[102:105]
	s_barrier
	s_setprio 0
	s_add_i32 s65, s65, s2
	s_mov_b32 m0, s65
	ds_read_b128 v[172:175], v183 offset:16384
	ds_read_b128 v[176:179], v183 offset:17408
	ds_read_b128 v[184:187], v183 offset:18432
	ds_read_b128 v[188:191], v183 offset:19456
	ds_read_b128 v[192:195], v183 offset:20480
	ds_read_b128 v[196:199], v183 offset:21504
	ds_read_b128 v[200:203], v183 offset:22528
	ds_read_b128 v[204:207], v183 offset:23552
	global_load_lds_dwordx4 v0, s[88:89]
	s_add_i32 m0, s65, 0x2000
	s_add_u32 s96, s88, 0x4000
	s_addc_u32 s97, s89, 0
	s_add_i32 s65, s66, s2
	global_load_lds_dwordx4 v162, s[88:89]
	s_mov_b32 m0, s65
	s_nop 0
	global_load_lds_dwordx4 v0, s[96:97]
	s_add_i32 m0, s65, 0x2000
	s_nop 0
	global_load_lds_dwordx4 v162, s[96:97]
	s_mov_b32 m0, s51
	s_nop 0
	global_load_lds_dwordx4 v166, s[90:91]
	s_mov_b32 m0, s92
	s_nop 0
	global_load_lds_dwordx4 v164, s[90:91]
	s_waitcnt vmcnt(8)
	s_waitcnt lgkmcnt(0)
	s_barrier
	s_setprio 1
	v_mfma_f32_16x16x32_bf16 v[94:97], v[10:13], v[172:175], v[94:97]
	v_mfma_f32_16x16x32_bf16 v[94:97], v[14:17], v[176:179], v[94:97]
	v_mfma_f32_16x16x32_bf16 v[90:93], v[18:21], v[172:175], v[90:93]
	v_mfma_f32_16x16x32_bf16 v[90:93], v[22:25], v[176:179], v[90:93]
	v_mfma_f32_16x16x32_bf16 v[78:81], v[10:13], v[184:187], v[78:81]
	v_mfma_f32_16x16x32_bf16 v[78:81], v[14:17], v[188:191], v[78:81]
	v_mfma_f32_16x16x32_bf16 v[74:77], v[18:21], v[184:187], v[74:77]
	v_mfma_f32_16x16x32_bf16 v[74:77], v[22:25], v[188:191], v[74:77]
	v_mfma_f32_16x16x32_bf16 v[62:65], v[10:13], v[192:195], v[62:65]
	v_mfma_f32_16x16x32_bf16 v[62:65], v[14:17], v[196:199], v[62:65]
	v_mfma_f32_16x16x32_bf16 v[58:61], v[18:21], v[192:195], v[58:61]
	v_mfma_f32_16x16x32_bf16 v[58:61], v[22:25], v[196:199], v[58:61]
	v_mfma_f32_16x16x32_bf16 v[10:13], v[10:13], v[200:203], v[34:37]
	v_mfma_f32_16x16x32_bf16 v[10:13], v[14:17], v[204:207], v[10:13]
	v_mfma_f32_16x16x32_bf16 v[14:17], v[18:21], v[200:203], v[30:33]
	v_mfma_f32_16x16x32_bf16 v[14:17], v[22:25], v[204:207], v[14:17]
	s_setprio 0
	s_setprio 1
	v_mfma_f32_16x16x32_bf16 v[30:33], v[26:29], v[184:187], v[70:73]
	v_mfma_f32_16x16x32_bf16 v[70:73], v[38:41], v[188:191], v[30:33]
	v_mfma_f32_16x16x32_bf16 v[30:33], v[50:53], v[184:187], v[66:69]
	v_mfma_f32_16x16x32_bf16 v[66:69], v[54:57], v[188:191], v[30:33]
	v_mfma_f32_16x16x32_bf16 v[30:33], v[26:29], v[192:195], v[46:49]
	v_mfma_f32_16x16x32_bf16 v[46:49], v[38:41], v[196:199], v[30:33]
	v_mfma_f32_16x16x32_bf16 v[30:33], v[50:53], v[192:195], v[42:45]
	v_mfma_f32_16x16x32_bf16 v[42:45], v[54:57], v[196:199], v[30:33]
	v_mfma_f32_16x16x32_bf16 v[6:9], v[26:29], v[200:203], v[6:9]
	v_mfma_f32_16x16x32_bf16 v[6:9], v[38:41], v[204:207], v[6:9]
	v_mfma_f32_16x16x32_bf16 v[2:5], v[50:53], v[200:203], v[2:5]
	v_mfma_f32_16x16x32_bf16 v[2:5], v[54:57], v[204:207], v[2:5]
	v_mfma_f32_16x16x32_bf16 v[18:21], v[26:29], v[172:175], v[86:89]
	v_mfma_f32_16x16x32_bf16 v[18:21], v[38:41], v[176:179], v[18:21]
	v_mfma_f32_16x16x32_bf16 v[22:25], v[50:53], v[172:175], v[82:85]
	v_mfma_f32_16x16x32_bf16 v[22:25], v[54:57], v[176:179], v[22:25]
	s_barrier
	s_setprio 0
; #define PG8_STAGE(bufoff, gbase, voff) do { _Pragma("unroll") for (int _i = 0; _i < 2; ++_i) \
;         __builtin_amdgcn_global_load_lds((const unsigned*)((const char*)(gbase) + (voff)[_i]), (PG8_LAS unsigned*)(lds + (bufoff) + ldsw + _i * 8192), 16, 0, 0); } while (0)
; #define PG8_LDA(dst, b, h) do { _Pragma("unroll") for (int m = 0; m < 4; ++m) _Pragma("unroll") for (int k = 0; k < 2; ++k) dst[m][k] = *(const PG8_LAS bf16x8*)(lds + PG8_SA(b, h) + aoff + m * 2048 + k * 1024); } while (0)
; #define PG8_LDB(dst, b, h) do { _Pragma("unroll") for (int n = 0; n < 2; ++n) _Pragma("unroll") for (int k = 0; k < 2; ++k) dst[n][k] = *(const PG8_LAS bf16x8*)(lds + PG8_SB(b, h) + boff + n * 2048 + k * 1024); } while (0)
; #define PG8_MMA(ai, bj, At, Bt) do { __builtin_amdgcn_s_setprio(1); _Pragma("unroll") for (int m = 0; m < 4; ++m) _Pragma("unroll") for (int n = 0; n < 2; ++n) _Pragma("unroll") for (int k = 0; k < 2; ++k) \
;         acc[ai][bj][m][n] = __builtin_amdgcn_mfma_f32_16x16x32_bf16(Bt[n][k], At[m][k], acc[ai][bj][m][n], 0, 0, 0); __builtin_amdgcn_s_setprio(0); } while (0)
; #define PG8_WAIT_V(n) asm volatile("s_waitcnt vmcnt(" #n ")" ::: "memory")
; #define PG8_WAIT_L(n) asm volatile("s_waitcnt lgkmcnt(" #n ")" ::: "memory")
; #define PG8_BAR __builtin_amdgcn_s_barrier()
; #define PG8_SCHED __builtin_amdgcn_sched_barrier(0)
;     ...
;         for (int t = 0; t < nt; t += 2) {
;     ...
;             PG8_LDB(B0, 1, 0); PG8_LDB(B1, 1, 1); PG8_SCHED; PG8_LDA(At, 1, 0); PG8_STAGE(PG8_SA(0, 1), a2 + hstepA, voffA);
;             PG8_WAIT_V(8); PG8_WAIT_L(0); PG8_BAR; PG8_MMA(0, 0, At, B0); PG8_MMA(0, 1, At, B1); PG8_BAR; PG8_SCHED;
;             PG8_LDA(At, 1, 1); PG8_STAGE(PG8_SB(1, 0), b3, voffB); PG8_STAGE(PG8_SB(1, 1), b3 + hstepB, voffB); PG8_STAGE(PG8_SA(1, 0), a3, voffA);
;             PG8_WAIT_V(8); PG8_WAIT_L(0); PG8_BAR; PG8_MMA(1, 0, At, B0); PG8_MMA(1, 1, At, B1); PG8_BAR; PG8_SCHED;
.Lin_mid:
	s_add_i32 s65, 0, 0x18000
	v_add_u32_e32 v34, s65, v182
	s_add_i32 s66, 0, 0x1c000
	ds_read_b128 v[26:29], v34
	ds_read_b128 v[30:33], v34 offset:1024
	ds_read_b128 v[38:41], v34 offset:2048
	ds_read_b128 v[50:53], v34 offset:3072
	v_add_u32_e32 v34, s66, v182
	ds_read_b128 v[54:57], v34
	ds_read_b128 v[172:175], v34 offset:1024
	ds_read_b128 v[176:179], v34 offset:2048
	ds_read_b128 v[184:187], v34 offset:3072
	s_add_u32 s90, s90, 0x4000
	s_addc_u32 s91, s91, 0
	s_mov_b32 m0, s14
	ds_read_b128 v[34:37], v183 offset:32768
	ds_read_b128 v[82:85], v183 offset:33792
	ds_read_b128 v[86:89], v183 offset:34816
	ds_read_b128 v[188:191], v183 offset:35840
	ds_read_b128 v[192:195], v183 offset:36864
	ds_read_b128 v[196:199], v183 offset:37888
	ds_read_b128 v[200:203], v183 offset:38912
	ds_read_b128 v[204:207], v183 offset:39936
	global_load_lds_dwordx4 v166, s[90:91]
	v_lshl_add_u64 v[208:209], s[90:91], 0, v[164:165]
	s_mov_b32 m0, s15
	s_nop 0
	global_load_lds_dwordx4 v[208:209], off
	s_waitcnt vmcnt(8)
	s_waitcnt lgkmcnt(0)
	s_barrier
	s_setprio 1
	v_mfma_f32_16x16x32_bf16 v[158:161], v[26:29], v[34:37], v[158:161]
	v_mfma_f32_16x16x32_bf16 v[158:161], v[30:33], v[82:85], v[158:161]
	v_mfma_f32_16x16x32_bf16 v[154:157], v[50:53], v[82:85], v[154:157]
	v_mfma_f32_16x16x32_bf16 v[154:157], v[38:41], v[34:37], v[154:157]
	v_mfma_f32_16x16x32_bf16 v[138:141], v[38:41], v[86:89], v[138:141]
	v_mfma_f32_16x16x32_bf16 v[138:141], v[50:53], v[188:191], v[138:141]
	v_mfma_f32_16x16x32_bf16 v[142:145], v[30:33], v[188:191], v[142:145]
	v_mfma_f32_16x16x32_bf16 v[142:145], v[26:29], v[86:89], v[142:145]
	v_mfma_f32_16x16x32_bf16 v[126:129], v[26:29], v[192:195], v[126:129]
	v_mfma_f32_16x16x32_bf16 v[126:129], v[30:33], v[196:199], v[126:129]
	v_mfma_f32_16x16x32_bf16 v[122:125], v[50:53], v[196:199], v[122:125]
	v_mfma_f32_16x16x32_bf16 v[122:125], v[38:41], v[192:195], v[122:125]
	v_mfma_f32_16x16x32_bf16 v[106:109], v[38:41], v[200:203], v[106:109]
	v_mfma_f32_16x16x32_bf16 v[106:109], v[50:53], v[204:207], v[106:109]
	v_mfma_f32_16x16x32_bf16 v[110:113], v[30:33], v[204:207], v[110:113]
	v_mfma_f32_16x16x32_bf16 v[110:113], v[26:29], v[200:203], v[110:113]
	s_setprio 0
	s_setprio 1
	v_mfma_f32_16x16x32_bf16 v[150:153], v[54:57], v[34:37], v[150:153]
	v_mfma_f32_16x16x32_bf16 v[150:153], v[172:175], v[82:85], v[150:153]
	v_mfma_f32_16x16x32_bf16 v[34:37], v[176:179], v[34:37], v[146:149]
	v_mfma_f32_16x16x32_bf16 v[146:149], v[184:187], v[82:85], v[34:37]
	v_mfma_f32_16x16x32_bf16 v[34:37], v[54:57], v[86:89], v[134:137]
	v_mfma_f32_16x16x32_bf16 v[134:137], v[172:175], v[188:191], v[34:37]
	v_mfma_f32_16x16x32_bf16 v[34:37], v[176:179], v[86:89], v[130:133]
	v_mfma_f32_16x16x32_bf16 v[130:133], v[184:187], v[188:191], v[34:37]
	v_mfma_f32_16x16x32_bf16 v[34:37], v[54:57], v[192:195], v[118:121]
	v_mfma_f32_16x16x32_bf16 v[118:121], v[172:175], v[196:199], v[34:37]
	v_mfma_f32_16x16x32_bf16 v[34:37], v[176:179], v[192:195], v[114:117]
	v_mfma_f32_16x16x32_bf16 v[114:117], v[184:187], v[196:199], v[34:37]
	v_mfma_f32_16x16x32_bf16 v[34:37], v[54:57], v[200:203], v[102:105]
	v_mfma_f32_16x16x32_bf16 v[102:105], v[172:175], v[204:207], v[34:37]
	v_mfma_f32_16x16x32_bf16 v[34:37], v[176:179], v[200:203], v[98:101]
	v_mfma_f32_16x16x32_bf16 v[98:101], v[184:187], v[204:207], v[34:37]
	s_barrier
	s_setprio 0
	s_add_u32 s90, s88, 0x8000
	s_addc_u32 s91, s89, 0
	s_add_i32 s65, s65, s2
	s_nop 0
	s_mov_b32 m0, s65
	ds_read_b128 v[82:85], v183 offset:49152
	ds_read_b128 v[188:191], v183 offset:50176
	ds_read_b128 v[192:195], v183 offset:51200
	ds_read_b128 v[196:199], v183 offset:52224
	ds_read_b128 v[200:203], v183 offset:53248
	ds_read_b128 v[204:207], v183 offset:54272
	ds_read_b128 v[208:211], v183 offset:55296
	ds_read_b128 v[216:219], v183 offset:56320
	global_load_lds_dwordx4 v0, s[90:91]
	s_add_i32 m0, s65, 0x2000
	s_add_u32 s88, s88, 0xc000
	s_addc_u32 s89, s89, 0
	s_add_i32 s65, s66, s2
	global_load_lds_dwordx4 v162, s[90:91]
	s_mov_b32 m0, s65
	s_nop 0
	global_load_lds_dwordx4 v0, s[88:89]
	s_add_i32 m0, s65, 0x2000
	s_nop 0
	global_load_lds_dwordx4 v162, s[88:89]
	s_mov_b32 m0, s71
	s_nop 0
	global_load_lds_dwordx4 v166, s[86:87]
	v_lshl_add_u64 v[34:35], s[86:87], 0, v[164:165]
	s_mov_b32 m0, s80
	s_nop 0
	global_load_lds_dwordx4 v[34:35], off
	s_waitcnt vmcnt(8)
	s_waitcnt lgkmcnt(0)
	s_barrier
	s_setprio 1
	v_mfma_f32_16x16x32_bf16 v[34:37], v[26:29], v[82:85], v[94:97]
	v_mfma_f32_16x16x32_bf16 v[94:97], v[30:33], v[188:191], v[34:37]
	v_mfma_f32_16x16x32_bf16 v[34:37], v[38:41], v[82:85], v[90:93]
	v_mfma_f32_16x16x32_bf16 v[90:93], v[50:53], v[188:191], v[34:37]
	v_mfma_f32_16x16x32_bf16 v[34:37], v[26:29], v[192:195], v[78:81]
	v_mfma_f32_16x16x32_bf16 v[78:81], v[30:33], v[196:199], v[34:37]
	v_mfma_f32_16x16x32_bf16 v[34:37], v[38:41], v[192:195], v[74:77]
	v_mfma_f32_16x16x32_bf16 v[74:77], v[50:53], v[196:199], v[34:37]
	v_mfma_f32_16x16x32_bf16 v[34:37], v[26:29], v[200:203], v[62:65]
	v_mfma_f32_16x16x32_bf16 v[62:65], v[30:33], v[204:207], v[34:37]
	v_mfma_f32_16x16x32_bf16 v[34:37], v[38:41], v[200:203], v[58:61]
	v_mfma_f32_16x16x32_bf16 v[58:61], v[50:53], v[204:207], v[34:37]
	v_mfma_f32_16x16x32_bf16 v[10:13], v[26:29], v[208:211], v[10:13]
	v_mfma_f32_16x16x32_bf16 v[34:37], v[30:33], v[216:219], v[10:13]
	v_mfma_f32_16x16x32_bf16 v[10:13], v[38:41], v[208:211], v[14:17]
	v_mfma_f32_16x16x32_bf16 v[30:33], v[50:53], v[216:219], v[10:13]
	s_setprio 0
	s_setprio 1
	v_mfma_f32_16x16x32_bf16 v[10:13], v[54:57], v[82:85], v[18:21]
	v_mfma_f32_16x16x32_bf16 v[86:89], v[172:175], v[188:191], v[10:13]
	v_mfma_f32_16x16x32_bf16 v[10:13], v[176:179], v[82:85], v[22:25]
	v_mfma_f32_16x16x32_bf16 v[82:85], v[184:187], v[188:191], v[10:13]
	v_mfma_f32_16x16x32_bf16 v[10:13], v[54:57], v[192:195], v[70:73]
	v_mfma_f32_16x16x32_bf16 v[70:73], v[172:175], v[196:199], v[10:13]
	v_mfma_f32_16x16x32_bf16 v[10:13], v[176:179], v[192:195], v[66:69]
	v_mfma_f32_16x16x32_bf16 v[66:69], v[184:187], v[196:199], v[10:13]
	v_mfma_f32_16x16x32_bf16 v[10:13], v[54:57], v[200:203], v[46:49]
	v_mfma_f32_16x16x32_bf16 v[46:49], v[172:175], v[204:207], v[10:13]
	v_mfma_f32_16x16x32_bf16 v[10:13], v[176:179], v[200:203], v[42:45]
	v_mfma_f32_16x16x32_bf16 v[42:45], v[184:187], v[204:207], v[10:13]
	v_mfma_f32_16x16x32_bf16 v[6:9], v[54:57], v[208:211], v[6:9]
	v_mfma_f32_16x16x32_bf16 v[6:9], v[172:175], v[216:219], v[6:9]
	v_mfma_f32_16x16x32_bf16 v[2:5], v[176:179], v[208:211], v[2:5]
	v_mfma_f32_16x16x32_bf16 v[2:5], v[184:187], v[216:219], v[2:5]
	s_barrier
	s_setprio 0
	s_add_i32 vcc_lo, vcc_lo, 2
	s_add_u32 s6, s6, 0x10000
	s_addc_u32 s7, s7, 0
	s_add_u32 s56, s56, 0x10000
	s_addc_u32 s57, s57, 0
	s_cmp_gt_u32 vcc_lo, 29
	s_cbranch_scc0 .LBB0_328
	s_and_b64 vcc, exec, s[26:27]
	s_cbranch_vccz .LBB0_331
	s_barrier

; #define PG8_STAGE(bufoff, gbase, voff) do { _Pragma("unroll") for (int _i = 0; _i < 2; ++_i) \
;         __builtin_amdgcn_global_load_lds((const unsigned*)((const char*)(gbase) + (voff)[_i]), (PG8_LAS unsigned*)(lds + (bufoff) + ldsw + _i * 8192), 16, 0, 0); } while (0)
; #define PG8_LDA(dst, b, h) do { _Pragma("unroll") for (int m = 0; m < 4; ++m) _Pragma("unroll") for (int k = 0; k < 2; ++k) dst[m][k] = *(const PG8_LAS bf16x8*)(lds + PG8_SA(b, h) + aoff + m * 2048 + k * 1024); } while (0)
; #define PG8_LDB(dst, b, h) do { _Pragma("unroll") for (int n = 0; n < 2; ++n) _Pragma("unroll") for (int k = 0; k < 2; ++k) dst[n][k] = *(const PG8_LAS bf16x8*)(lds + PG8_SB(b, h) + boff + n * 2048 + k * 1024); } while (0)
; #define PG8_MMA(ai, bj, At, Bt) do { __builtin_amdgcn_s_setprio(1); _Pragma("unroll") for (int m = 0; m < 4; ++m) _Pragma("unroll") for (int n = 0; n < 2; ++n) _Pragma("unroll") for (int k = 0; k < 2; ++k) \
;         acc[ai][bj][m][n] = __builtin_amdgcn_mfma_f32_16x16x32_bf16(Bt[n][k], At[m][k], acc[ai][bj][m][n], 0, 0, 0); __builtin_amdgcn_s_setprio(0); } while (0)
; #define PG8_WAIT_V(n) asm volatile("s_waitcnt vmcnt(" #n ")" ::: "memory")
; #define PG8_WAIT_L(n) asm volatile("s_waitcnt lgkmcnt(" #n ")" ::: "memory")
; #define PG8_BAR __builtin_amdgcn_s_barrier()
; #define PG8_SCHED __builtin_amdgcn_sched_barrier(0)
;     ...
;             const bool last = (t == nt - 2);
;             const char* a1 = cA + (ptrdiff_t)(t + 1) * kstepA;
;             const char* a2 = last ? nA : cA + (ptrdiff_t)(t + 2) * kstepA; const char* b2 = last ? nB : cB + (ptrdiff_t)(t + 2) * kstep;
;             const char* a3 = a2 + kstepA; const char* b3 = b2 + kstep;
;             if (last && has_next) S.a_ready(nxt);
;             if constexpr (SP2) {
;             PG8_LDB(B0, 0, 0); PG8_LDB(B1, 0, 1); PG8_SCHED; PG8_LDA(At, 0, 0); PG8_STAGE(PG8_SA(1, 1), a1 + hstepA, voffA);
;             PG8_WAIT_V(8); PG8_WAIT_L(0); PG8_BAR; PG8_MMA(0, 0, At, B0); PG8_MMA(0, 1, At, B1); PG8_BAR; PG8_SCHED;
;             PG8_LDA(At, 0, 1); PG8_STAGE(PG8_SB(0, 0), b2, voffB); PG8_STAGE(PG8_SB(0, 1), b2 + hstepB, voffB); PG8_STAGE(PG8_SA(0, 0), a2, voffA);
;             PG8_WAIT_V(8); PG8_WAIT_L(0); PG8_BAR; PG8_MMA(1, 0, At, B0); PG8_MMA(1, 1, At, B1); PG8_BAR; PG8_SCHED;
.Lout_nostg:
	s_add_u32 s36, s34, 0x4000
	s_addc_u32 s37, s35, 0
	s_cmp_eq_u32 s57, 28
	s_cselect_b32 s86, s29, s36
	s_cselect_b32 s87, s23, s37
	s_cselect_b32 s46, s31, s44
	s_cselect_b32 s47, s21, s56
	s_add_u32 s36, s86, 0x8000
	s_addc_u32 s37, s87, 0
	s_add_i32 s65, 0, 0x10000
	v_add_u32_e32 v0, s65, v242
	s_add_i32 s66, 0, 0x14000
	s_waitcnt lgkmcnt(0)
	ds_read_b128 v[130:133], v0
	ds_read_b128 v[134:137], v0 offset:1024
	ds_read_b128 v[138:141], v0 offset:2048
	ds_read_b128 v[142:145], v0 offset:3072
	v_add_u32_e32 v0, s66, v242
	ds_read_b128 v[146:149], v0
	ds_read_b128 v[150:153], v0 offset:1024
	ds_read_b128 v[154:157], v0 offset:2048
	ds_read_b128 v[158:161], v0 offset:3072
	s_add_i32 m0, s51, 0xc000
	ds_read_b128 v[162:165], v243
	ds_read_b128 v[166:169], v243 offset:1024
	ds_read_b128 v[170:173], v243 offset:2048
	ds_read_b128 v[174:177], v243 offset:3072
	ds_read_b128 v[178:181], v243 offset:4096
	ds_read_b128 v[182:185], v243 offset:5120
	ds_read_b128 v[198:201], v243 offset:6144
	ds_read_b128 v[202:205], v243 offset:7168
	global_load_lds_dwordx4 v194, s[34:35]
	s_add_i32 m0, s51, 0xe000
	s_nop 0
	global_load_lds_dwordx4 v196, s[34:35]
	s_waitcnt vmcnt(8)
	s_waitcnt lgkmcnt(0)
	s_barrier
	s_setprio 1
	v_mfma_f32_16x16x32_bf16 v[126:129], v[130:133], v[162:165], 0
	v_mfma_f32_16x16x32_bf16 v[126:129], v[134:137], v[166:169], v[126:129]
	v_mfma_f32_16x16x32_bf16 v[122:125], v[142:145], v[166:169], 0
	v_mfma_f32_16x16x32_bf16 v[122:125], v[138:141], v[162:165], v[122:125]
	v_mfma_f32_16x16x32_bf16 v[106:109], v[138:141], v[170:173], 0
	v_mfma_f32_16x16x32_bf16 v[106:109], v[142:145], v[174:177], v[106:109]
	v_mfma_f32_16x16x32_bf16 v[110:113], v[134:137], v[174:177], 0
	v_mfma_f32_16x16x32_bf16 v[110:113], v[130:133], v[170:173], v[110:113]
	v_mfma_f32_16x16x32_bf16 v[94:97], v[130:133], v[178:181], 0
	v_mfma_f32_16x16x32_bf16 v[94:97], v[134:137], v[182:185], v[94:97]
	v_mfma_f32_16x16x32_bf16 v[90:93], v[142:145], v[182:185], 0
	v_mfma_f32_16x16x32_bf16 v[90:93], v[138:141], v[178:181], v[90:93]
	v_mfma_f32_16x16x32_bf16 v[74:77], v[138:141], v[198:201], 0
	v_mfma_f32_16x16x32_bf16 v[74:77], v[142:145], v[202:205], v[74:77]
	v_mfma_f32_16x16x32_bf16 v[78:81], v[134:137], v[202:205], 0
	v_mfma_f32_16x16x32_bf16 v[78:81], v[130:133], v[198:201], v[78:81]
	s_setprio 0
	s_setprio 1
	v_mfma_f32_16x16x32_bf16 v[118:121], v[146:149], v[162:165], 0
	v_mfma_f32_16x16x32_bf16 v[118:121], v[150:153], v[166:169], v[118:121]
	v_mfma_f32_16x16x32_bf16 v[114:117], v[158:161], v[166:169], 0
	v_mfma_f32_16x16x32_bf16 v[114:117], v[154:157], v[162:165], v[114:117]
	v_mfma_f32_16x16x32_bf16 v[98:101], v[154:157], v[170:173], 0
	v_mfma_f32_16x16x32_bf16 v[98:101], v[158:161], v[174:177], v[98:101]
	v_mfma_f32_16x16x32_bf16 v[102:105], v[150:153], v[174:177], 0
	v_mfma_f32_16x16x32_bf16 v[102:105], v[146:149], v[170:173], v[102:105]
	v_mfma_f32_16x16x32_bf16 v[86:89], v[146:149], v[178:181], 0
	v_mfma_f32_16x16x32_bf16 v[86:89], v[150:153], v[182:185], v[86:89]
	v_mfma_f32_16x16x32_bf16 v[82:85], v[158:161], v[182:185], 0
	v_mfma_f32_16x16x32_bf16 v[82:85], v[154:157], v[178:181], v[82:85]
	v_mfma_f32_16x16x32_bf16 v[66:69], v[154:157], v[198:201], 0
	v_mfma_f32_16x16x32_bf16 v[66:69], v[158:161], v[202:205], v[66:69]
	v_mfma_f32_16x16x32_bf16 v[70:73], v[150:153], v[202:205], 0
	v_mfma_f32_16x16x32_bf16 v[70:73], v[146:149], v[198:201], v[70:73]
	s_barrier
	s_setprio 0
	s_add_i32 s65, s65, s49
	s_mov_b32 m0, s65
	ds_read_b128 v[162:165], v243 offset:16384
	ds_read_b128 v[166:169], v243 offset:17408
	ds_read_b128 v[170:173], v243 offset:18432
	ds_read_b128 v[174:177], v243 offset:19456
	ds_read_b128 v[178:181], v243 offset:20480
	ds_read_b128 v[182:185], v243 offset:21504
	ds_read_b128 v[198:201], v243 offset:22528
	ds_read_b128 v[202:205], v243 offset:23552
	global_load_lds_dwordx4 v188, s[46:47]
	s_add_i32 m0, s65, 0x2000
	s_add_u32 s90, s46, 0x4000
	s_addc_u32 s91, s47, 0
	s_add_i32 s65, s66, s49
	global_load_lds_dwordx4 v192, s[46:47]
	s_mov_b32 m0, s65
	s_nop 0
	global_load_lds_dwordx4 v188, s[90:91]
	s_add_i32 m0, s65, 0x2000
	s_nop 0
	global_load_lds_dwordx4 v192, s[90:91]
	s_mov_b32 m0, s51
	s_nop 0
	global_load_lds_dwordx4 v186, s[86:87]
	s_mov_b32 m0, s54
	s_nop 0
	global_load_lds_dwordx4 v190, s[86:87]
	s_waitcnt vmcnt(8)
	s_waitcnt lgkmcnt(0)
	s_barrier
	s_setprio 1
	v_mfma_f32_16x16x32_bf16 v[62:65], v[130:133], v[162:165], 0
	v_mfma_f32_16x16x32_bf16 v[62:65], v[134:137], v[166:169], v[62:65]
	v_mfma_f32_16x16x32_bf16 v[58:61], v[142:145], v[166:169], 0
	v_mfma_f32_16x16x32_bf16 v[58:61], v[138:141], v[162:165], v[58:61]
	v_mfma_f32_16x16x32_bf16 v[42:45], v[138:141], v[170:173], 0
	v_mfma_f32_16x16x32_bf16 v[42:45], v[142:145], v[174:177], v[42:45]
	v_mfma_f32_16x16x32_bf16 v[46:49], v[134:137], v[174:177], 0
	v_mfma_f32_16x16x32_bf16 v[46:49], v[130:133], v[170:173], v[46:49]
	v_mfma_f32_16x16x32_bf16 v[30:33], v[130:133], v[178:181], 0
	v_mfma_f32_16x16x32_bf16 v[30:33], v[134:137], v[182:185], v[30:33]
	v_mfma_f32_16x16x32_bf16 v[26:29], v[142:145], v[182:185], 0
	v_mfma_f32_16x16x32_bf16 v[26:29], v[138:141], v[178:181], v[26:29]
	v_mfma_f32_16x16x32_bf16 v[10:13], v[138:141], v[198:201], 0
	v_mfma_f32_16x16x32_bf16 v[10:13], v[142:145], v[202:205], v[10:13]
	v_mfma_f32_16x16x32_bf16 v[14:17], v[134:137], v[202:205], 0
	v_mfma_f32_16x16x32_bf16 v[14:17], v[130:133], v[198:201], v[14:17]
	s_setprio 0
	s_setprio 1
	v_mfma_f32_16x16x32_bf16 v[54:57], v[146:149], v[162:165], 0
	v_mfma_f32_16x16x32_bf16 v[54:57], v[150:153], v[166:169], v[54:57]
	v_mfma_f32_16x16x32_bf16 v[50:53], v[158:161], v[166:169], 0
	v_mfma_f32_16x16x32_bf16 v[50:53], v[154:157], v[162:165], v[50:53]
	v_mfma_f32_16x16x32_bf16 v[34:37], v[154:157], v[170:173], 0
	v_mfma_f32_16x16x32_bf16 v[34:37], v[158:161], v[174:177], v[34:37]
	v_mfma_f32_16x16x32_bf16 v[38:41], v[150:153], v[174:177], 0
	v_mfma_f32_16x16x32_bf16 v[38:41], v[146:149], v[170:173], v[38:41]
	v_mfma_f32_16x16x32_bf16 v[22:25], v[146:149], v[178:181], 0
	v_mfma_f32_16x16x32_bf16 v[22:25], v[150:153], v[182:185], v[22:25]
	v_mfma_f32_16x16x32_bf16 v[18:21], v[158:161], v[182:185], 0
	v_mfma_f32_16x16x32_bf16 v[18:21], v[154:157], v[178:181], v[18:21]
	v_mfma_f32_16x16x32_bf16 v[2:5], v[154:157], v[198:201], 0
	v_mfma_f32_16x16x32_bf16 v[2:5], v[158:161], v[202:205], v[2:5]
	v_mfma_f32_16x16x32_bf16 v[6:9], v[150:153], v[202:205], 0
	v_mfma_f32_16x16x32_bf16 v[6:9], v[146:149], v[198:201], v[6:9]
	s_barrier
	s_setprio 0
	s_branch .Lout_mid

; #define PG8_STAGE(bufoff, gbase, voff) do { _Pragma("unroll") for (int _i = 0; _i < 2; ++_i) \
;         __builtin_amdgcn_global_load_lds((const unsigned*)((const char*)(gbase) + (voff)[_i]), (PG8_LAS unsigned*)(lds + (bufoff) + ldsw + _i * 8192), 16, 0, 0); } while (0)
; #define PG8_LDA(dst, b, h) do { _Pragma("unroll") for (int m = 0; m < 4; ++m) _Pragma("unroll") for (int k = 0; k < 2; ++k) dst[m][k] = *(const PG8_LAS bf16x8*)(lds + PG8_SA(b, h) + aoff + m * 2048 + k * 1024); } while (0)
; #define PG8_LDB(dst, b, h) do { _Pragma("unroll") for (int n = 0; n < 2; ++n) _Pragma("unroll") for (int k = 0; k < 2; ++k) dst[n][k] = *(const PG8_LAS bf16x8*)(lds + PG8_SB(b, h) + boff + n * 2048 + k * 1024); } while (0)
; #define PG8_MMA(ai, bj, At, Bt) do { __builtin_amdgcn_s_setprio(1); _Pragma("unroll") for (int m = 0; m < 4; ++m) _Pragma("unroll") for (int n = 0; n < 2; ++n) _Pragma("unroll") for (int k = 0; k < 2; ++k) \
;         acc[ai][bj][m][n] = __builtin_amdgcn_mfma_f32_16x16x32_bf16(Bt[n][k], At[m][k], acc[ai][bj][m][n], 0, 0, 0); __builtin_amdgcn_s_setprio(0); } while (0)
; #define PG8_WAIT_V(n) asm volatile("s_waitcnt vmcnt(" #n ")" ::: "memory")
; #define PG8_WAIT_L(n) asm volatile("s_waitcnt lgkmcnt(" #n ")" ::: "memory")
; #define PG8_BAR __builtin_amdgcn_s_barrier()
; #define PG8_SCHED __builtin_amdgcn_sched_barrier(0)
;     ...
;             const bool last = (t == nt - 2);
;             const char* a1 = cA + (ptrdiff_t)(t + 1) * kstepA;
;             const char* a2 = last ? nA : cA + (ptrdiff_t)(t + 2) * kstepA; const char* b2 = last ? nB : cB + (ptrdiff_t)(t + 2) * kstep;
;             const char* a3 = a2 + kstepA; const char* b3 = b2 + kstep;
;             if (last && has_next) S.a_ready(nxt);
;             if constexpr (SP2) {
;             PG8_LDB(B0, 0, 0); PG8_LDB(B1, 0, 1); PG8_SCHED; PG8_LDA(At, 0, 0); PG8_STAGE(PG8_SA(1, 1), a1 + hstepA, voffA);
;             PG8_WAIT_V(8); PG8_WAIT_L(0); PG8_BAR; PG8_MMA(0, 0, At, B0); PG8_MMA(0, 1, At, B1); PG8_BAR; PG8_SCHED;
;             PG8_LDA(At, 0, 1); PG8_STAGE(PG8_SB(0, 0), b2, voffB); PG8_STAGE(PG8_SB(0, 1), b2 + hstepB, voffB); PG8_STAGE(PG8_SA(0, 0), a2, voffA);
;             PG8_WAIT_V(8); PG8_WAIT_L(0); PG8_BAR; PG8_MMA(1, 0, At, B0); PG8_MMA(1, 1, At, B1); PG8_BAR; PG8_SCHED;
.LBB0_1128:
	s_add_u32 s36, s34, 0x4000
	s_addc_u32 s37, s35, 0
	s_cmp_eq_u32 s57, 28
	s_cselect_b32 s86, s29, s36
	s_cselect_b32 s87, s23, s37
	s_cselect_b32 s46, s31, s44
	s_cselect_b32 s47, s21, s56
	s_add_u32 s36, s86, 0x8000
	s_addc_u32 s37, s87, 0
	s_add_i32 s65, 0, 0x10000
	v_add_u32_e32 v0, s65, v242
	s_add_i32 s66, 0, 0x14000
	s_waitcnt lgkmcnt(0)
	ds_read_b128 v[130:133], v0
	ds_read_b128 v[134:137], v0 offset:1024
	ds_read_b128 v[138:141], v0 offset:2048
	ds_read_b128 v[142:145], v0 offset:3072
	v_add_u32_e32 v0, s66, v242
	ds_read_b128 v[146:149], v0
	ds_read_b128 v[150:153], v0 offset:1024
	ds_read_b128 v[154:157], v0 offset:2048
	ds_read_b128 v[158:161], v0 offset:3072
	s_add_i32 m0, s51, 0xc000
	ds_read_b128 v[162:165], v243
	ds_read_b128 v[166:169], v243 offset:1024
	ds_read_b128 v[170:173], v243 offset:2048
	ds_read_b128 v[174:177], v243 offset:3072
	ds_read_b128 v[178:181], v243 offset:4096
	ds_read_b128 v[182:185], v243 offset:5120
	ds_read_b128 v[198:201], v243 offset:6144
	ds_read_b128 v[202:205], v243 offset:7168
	global_load_lds_dwordx4 v194, s[34:35]
	s_add_i32 m0, s51, 0xe000
	s_nop 0
	global_load_lds_dwordx4 v196, s[34:35]
	s_waitcnt vmcnt(8)
	s_waitcnt lgkmcnt(0)
	s_barrier
	s_setprio 1
	v_mfma_f32_16x16x32_bf16 v[126:129], v[130:133], v[162:165], v[126:129]
	v_mfma_f32_16x16x32_bf16 v[126:129], v[134:137], v[166:169], v[126:129]
	v_mfma_f32_16x16x32_bf16 v[122:125], v[142:145], v[166:169], v[122:125]
	v_mfma_f32_16x16x32_bf16 v[122:125], v[138:141], v[162:165], v[122:125]
	v_mfma_f32_16x16x32_bf16 v[106:109], v[138:141], v[170:173], v[106:109]
	v_mfma_f32_16x16x32_bf16 v[106:109], v[142:145], v[174:177], v[106:109]
	v_mfma_f32_16x16x32_bf16 v[110:113], v[134:137], v[174:177], v[110:113]
	v_mfma_f32_16x16x32_bf16 v[110:113], v[130:133], v[170:173], v[110:113]
	v_mfma_f32_16x16x32_bf16 v[94:97], v[130:133], v[178:181], v[94:97]
	v_mfma_f32_16x16x32_bf16 v[94:97], v[134:137], v[182:185], v[94:97]
	v_mfma_f32_16x16x32_bf16 v[90:93], v[142:145], v[182:185], v[90:93]
	v_mfma_f32_16x16x32_bf16 v[90:93], v[138:141], v[178:181], v[90:93]
	v_mfma_f32_16x16x32_bf16 v[74:77], v[138:141], v[198:201], v[74:77]
	v_mfma_f32_16x16x32_bf16 v[74:77], v[142:145], v[202:205], v[74:77]
	v_mfma_f32_16x16x32_bf16 v[78:81], v[134:137], v[202:205], v[78:81]
	v_mfma_f32_16x16x32_bf16 v[78:81], v[130:133], v[198:201], v[78:81]
	s_setprio 0
	s_setprio 1
	v_mfma_f32_16x16x32_bf16 v[118:121], v[146:149], v[162:165], v[118:121]
	v_mfma_f32_16x16x32_bf16 v[118:121], v[150:153], v[166:169], v[118:121]
	v_mfma_f32_16x16x32_bf16 v[114:117], v[158:161], v[166:169], v[114:117]
	v_mfma_f32_16x16x32_bf16 v[114:117], v[154:157], v[162:165], v[114:117]
	v_mfma_f32_16x16x32_bf16 v[98:101], v[154:157], v[170:173], v[98:101]
	v_mfma_f32_16x16x32_bf16 v[98:101], v[158:161], v[174:177], v[98:101]
	v_mfma_f32_16x16x32_bf16 v[102:105], v[150:153], v[174:177], v[102:105]
	v_mfma_f32_16x16x32_bf16 v[102:105], v[146:149], v[170:173], v[102:105]
	v_mfma_f32_16x16x32_bf16 v[86:89], v[146:149], v[178:181], v[86:89]
	v_mfma_f32_16x16x32_bf16 v[86:89], v[150:153], v[182:185], v[86:89]
	v_mfma_f32_16x16x32_bf16 v[82:85], v[158:161], v[182:185], v[82:85]
	v_mfma_f32_16x16x32_bf16 v[82:85], v[154:157], v[178:181], v[82:85]
	v_mfma_f32_16x16x32_bf16 v[66:69], v[154:157], v[198:201], v[66:69]
	v_mfma_f32_16x16x32_bf16 v[66:69], v[158:161], v[202:205], v[66:69]
	v_mfma_f32_16x16x32_bf16 v[70:73], v[150:153], v[202:205], v[70:73]
	v_mfma_f32_16x16x32_bf16 v[70:73], v[146:149], v[198:201], v[70:73]
	s_barrier
	s_setprio 0
	s_add_i32 s65, s65, s49
	s_mov_b32 m0, s65
	ds_read_b128 v[162:165], v243 offset:16384
	ds_read_b128 v[166:169], v243 offset:17408
	ds_read_b128 v[170:173], v243 offset:18432
	ds_read_b128 v[174:177], v243 offset:19456
	ds_read_b128 v[178:181], v243 offset:20480
	ds_read_b128 v[182:185], v243 offset:21504
	ds_read_b128 v[198:201], v243 offset:22528
	ds_read_b128 v[202:205], v243 offset:23552
	global_load_lds_dwordx4 v188, s[46:47]
	s_add_i32 m0, s65, 0x2000
	s_add_u32 s90, s46, 0x4000
	s_addc_u32 s91, s47, 0
	s_add_i32 s65, s66, s49
	global_load_lds_dwordx4 v192, s[46:47]
	s_mov_b32 m0, s65
	s_nop 0
	global_load_lds_dwordx4 v188, s[90:91]
	s_add_i32 m0, s65, 0x2000
	s_nop 0
	global_load_lds_dwordx4 v192, s[90:91]
	s_mov_b32 m0, s51
	s_nop 0
	global_load_lds_dwordx4 v186, s[86:87]
	s_mov_b32 m0, s54
	s_nop 0
	global_load_lds_dwordx4 v190, s[86:87]
	s_waitcnt vmcnt(8)
	s_waitcnt lgkmcnt(0)
	s_barrier
	s_setprio 1
	v_mfma_f32_16x16x32_bf16 v[62:65], v[130:133], v[162:165], v[62:65]
	v_mfma_f32_16x16x32_bf16 v[62:65], v[134:137], v[166:169], v[62:65]
	v_mfma_f32_16x16x32_bf16 v[58:61], v[142:145], v[166:169], v[58:61]
	v_mfma_f32_16x16x32_bf16 v[58:61], v[138:141], v[162:165], v[58:61]
	v_mfma_f32_16x16x32_bf16 v[42:45], v[138:141], v[170:173], v[42:45]
	v_mfma_f32_16x16x32_bf16 v[42:45], v[142:145], v[174:177], v[42:45]
	v_mfma_f32_16x16x32_bf16 v[46:49], v[134:137], v[174:177], v[46:49]
	v_mfma_f32_16x16x32_bf16 v[46:49], v[130:133], v[170:173], v[46:49]
	v_mfma_f32_16x16x32_bf16 v[30:33], v[130:133], v[178:181], v[30:33]
	v_mfma_f32_16x16x32_bf16 v[30:33], v[134:137], v[182:185], v[30:33]
	v_mfma_f32_16x16x32_bf16 v[26:29], v[142:145], v[182:185], v[26:29]
	v_mfma_f32_16x16x32_bf16 v[26:29], v[138:141], v[178:181], v[26:29]
	v_mfma_f32_16x16x32_bf16 v[10:13], v[138:141], v[198:201], v[10:13]
	v_mfma_f32_16x16x32_bf16 v[10:13], v[142:145], v[202:205], v[10:13]
	v_mfma_f32_16x16x32_bf16 v[14:17], v[134:137], v[202:205], v[14:17]
	v_mfma_f32_16x16x32_bf16 v[14:17], v[130:133], v[198:201], v[14:17]
	s_setprio 0
	s_setprio 1
	v_mfma_f32_16x16x32_bf16 v[54:57], v[146:149], v[162:165], v[54:57]
	v_mfma_f32_16x16x32_bf16 v[54:57], v[150:153], v[166:169], v[54:57]
	v_mfma_f32_16x16x32_bf16 v[50:53], v[158:161], v[166:169], v[50:53]
	v_mfma_f32_16x16x32_bf16 v[50:53], v[154:157], v[162:165], v[50:53]
	v_mfma_f32_16x16x32_bf16 v[34:37], v[154:157], v[170:173], v[34:37]
	v_mfma_f32_16x16x32_bf16 v[34:37], v[158:161], v[174:177], v[34:37]
	v_mfma_f32_16x16x32_bf16 v[38:41], v[150:153], v[174:177], v[38:41]
	v_mfma_f32_16x16x32_bf16 v[38:41], v[146:149], v[170:173], v[38:41]
	v_mfma_f32_16x16x32_bf16 v[22:25], v[146:149], v[178:181], v[22:25]
	v_mfma_f32_16x16x32_bf16 v[22:25], v[150:153], v[182:185], v[22:25]
	v_mfma_f32_16x16x32_bf16 v[18:21], v[158:161], v[182:185], v[18:21]
	v_mfma_f32_16x16x32_bf16 v[18:21], v[154:157], v[178:181], v[18:21]
	v_mfma_f32_16x16x32_bf16 v[2:5], v[154:157], v[198:201], v[2:5]
	v_mfma_f32_16x16x32_bf16 v[2:5], v[158:161], v[202:205], v[2:5]
	v_mfma_f32_16x16x32_bf16 v[6:9], v[150:153], v[202:205], v[6:9]
	v_mfma_f32_16x16x32_bf16 v[6:9], v[146:149], v[198:201], v[6:9]
	s_barrier
	s_setprio 0
; #define PG8_STAGE(bufoff, gbase, voff) do { _Pragma("unroll") for (int _i = 0; _i < 2; ++_i) \
;         __builtin_amdgcn_global_load_lds((const unsigned*)((const char*)(gbase) + (voff)[_i]), (PG8_LAS unsigned*)(lds + (bufoff) + ldsw + _i * 8192), 16, 0, 0); } while (0)
; #define PG8_LDA(dst, b, h) do { _Pragma("unroll") for (int m = 0; m < 4; ++m) _Pragma("unroll") for (int k = 0; k < 2; ++k) dst[m][k] = *(const PG8_LAS bf16x8*)(lds + PG8_SA(b, h) + aoff + m * 2048 + k * 1024); } while (0)
; #define PG8_LDB(dst, b, h) do { _Pragma("unroll") for (int n = 0; n < 2; ++n) _Pragma("unroll") for (int k = 0; k < 2; ++k) dst[n][k] = *(const PG8_LAS bf16x8*)(lds + PG8_SB(b, h) + boff + n * 2048 + k * 1024); } while (0)
; #define PG8_MMA(ai, bj, At, Bt) do { __builtin_amdgcn_s_setprio(1); _Pragma("unroll") for (int m = 0; m < 4; ++m) _Pragma("unroll") for (int n = 0; n < 2; ++n) _Pragma("unroll") for (int k = 0; k < 2; ++k) \
;         acc[ai][bj][m][n] = __builtin_amdgcn_mfma_f32_16x16x32_bf16(Bt[n][k], At[m][k], acc[ai][bj][m][n], 0, 0, 0); __builtin_amdgcn_s_setprio(0); } while (0)
; #define PG8_WAIT_V(n) asm volatile("s_waitcnt vmcnt(" #n ")" ::: "memory")
; #define PG8_WAIT_L(n) asm volatile("s_waitcnt lgkmcnt(" #n ")" ::: "memory")
; #define PG8_BAR __builtin_amdgcn_s_barrier()
; #define PG8_SCHED __builtin_amdgcn_sched_barrier(0)
;     ...
;         for (int t = 0; t < nt; t += 2) {
;     ...
;             PG8_LDB(B0, 1, 0); PG8_LDB(B1, 1, 1); PG8_SCHED; PG8_LDA(At, 1, 0); PG8_STAGE(PG8_SA(0, 1), a2 + hstepA, voffA);
;             PG8_WAIT_V(8); PG8_WAIT_L(0); PG8_BAR; PG8_MMA(0, 0, At, B0); PG8_MMA(0, 1, At, B1); PG8_BAR; PG8_SCHED;
;             PG8_LDA(At, 1, 1); PG8_STAGE(PG8_SB(1, 0), b3, voffB); PG8_STAGE(PG8_SB(1, 1), b3 + hstepB, voffB); PG8_STAGE(PG8_SA(1, 0), a3, voffA);
;             PG8_WAIT_V(8); PG8_WAIT_L(0); PG8_BAR; PG8_MMA(1, 0, At, B0); PG8_MMA(1, 1, At, B1); PG8_BAR; PG8_SCHED;
.Lout_mid:
	s_add_i32 s65, 0, 0x18000
	v_add_u32_e32 v0, s65, v242
	s_add_i32 s66, 0, 0x1c000
	ds_read_b128 v[130:133], v0
	ds_read_b128 v[134:137], v0 offset:1024
	ds_read_b128 v[138:141], v0 offset:2048
	ds_read_b128 v[142:145], v0 offset:3072
	v_add_u32_e32 v0, s66, v242
	ds_read_b128 v[146:149], v0
	ds_read_b128 v[150:153], v0 offset:1024
	ds_read_b128 v[154:157], v0 offset:2048
	ds_read_b128 v[158:161], v0 offset:3072
	s_add_u32 s86, s86, 0x4000
	s_addc_u32 s87, s87, 0
	s_mov_b32 m0, s55
	ds_read_b128 v[162:165], v243 offset:32768
	ds_read_b128 v[166:169], v243 offset:33792
	ds_read_b128 v[170:173], v243 offset:34816
	ds_read_b128 v[174:177], v243 offset:35840
	ds_read_b128 v[178:181], v243 offset:36864
	ds_read_b128 v[182:185], v243 offset:37888
	ds_read_b128 v[198:201], v243 offset:38912
	ds_read_b128 v[202:205], v243 offset:39936
	global_load_lds_dwordx4 v186, s[86:87]
	s_mov_b32 m0, s61
	s_nop 0
	global_load_lds_dwordx4 v190, s[86:87]
	s_waitcnt vmcnt(8)
	s_waitcnt lgkmcnt(0)
	s_barrier
	s_setprio 1
	v_mfma_f32_16x16x32_bf16 v[126:129], v[130:133], v[162:165], v[126:129]
	v_mfma_f32_16x16x32_bf16 v[126:129], v[134:137], v[166:169], v[126:129]
	v_mfma_f32_16x16x32_bf16 v[122:125], v[142:145], v[166:169], v[122:125]
	v_mfma_f32_16x16x32_bf16 v[122:125], v[138:141], v[162:165], v[122:125]
	v_mfma_f32_16x16x32_bf16 v[106:109], v[138:141], v[170:173], v[106:109]
	v_mfma_f32_16x16x32_bf16 v[106:109], v[142:145], v[174:177], v[106:109]
	v_mfma_f32_16x16x32_bf16 v[110:113], v[134:137], v[174:177], v[110:113]
	v_mfma_f32_16x16x32_bf16 v[110:113], v[130:133], v[170:173], v[110:113]
	v_mfma_f32_16x16x32_bf16 v[94:97], v[130:133], v[178:181], v[94:97]
	v_mfma_f32_16x16x32_bf16 v[94:97], v[134:137], v[182:185], v[94:97]
	v_mfma_f32_16x16x32_bf16 v[90:93], v[142:145], v[182:185], v[90:93]
	v_mfma_f32_16x16x32_bf16 v[90:93], v[138:141], v[178:181], v[90:93]
	v_mfma_f32_16x16x32_bf16 v[74:77], v[138:141], v[198:201], v[74:77]
	v_mfma_f32_16x16x32_bf16 v[74:77], v[142:145], v[202:205], v[74:77]
	v_mfma_f32_16x16x32_bf16 v[78:81], v[134:137], v[202:205], v[78:81]
	v_mfma_f32_16x16x32_bf16 v[78:81], v[130:133], v[198:201], v[78:81]
	s_setprio 0
	s_setprio 1
	v_mfma_f32_16x16x32_bf16 v[118:121], v[146:149], v[162:165], v[118:121]
	v_mfma_f32_16x16x32_bf16 v[118:121], v[150:153], v[166:169], v[118:121]
	v_mfma_f32_16x16x32_bf16 v[114:117], v[158:161], v[166:169], v[114:117]
	v_mfma_f32_16x16x32_bf16 v[114:117], v[154:157], v[162:165], v[114:117]
	v_mfma_f32_16x16x32_bf16 v[98:101], v[154:157], v[170:173], v[98:101]
	v_mfma_f32_16x16x32_bf16 v[98:101], v[158:161], v[174:177], v[98:101]
	v_mfma_f32_16x16x32_bf16 v[102:105], v[150:153], v[174:177], v[102:105]
	v_mfma_f32_16x16x32_bf16 v[102:105], v[146:149], v[170:173], v[102:105]
	v_mfma_f32_16x16x32_bf16 v[86:89], v[146:149], v[178:181], v[86:89]
	v_mfma_f32_16x16x32_bf16 v[86:89], v[150:153], v[182:185], v[86:89]
	v_mfma_f32_16x16x32_bf16 v[82:85], v[158:161], v[182:185], v[82:85]
	v_mfma_f32_16x16x32_bf16 v[82:85], v[154:157], v[178:181], v[82:85]
	v_mfma_f32_16x16x32_bf16 v[66:69], v[154:157], v[198:201], v[66:69]
	v_mfma_f32_16x16x32_bf16 v[66:69], v[158:161], v[202:205], v[66:69]
	v_mfma_f32_16x16x32_bf16 v[70:73], v[150:153], v[202:205], v[70:73]
	v_mfma_f32_16x16x32_bf16 v[70:73], v[146:149], v[198:201], v[70:73]
	s_barrier
	s_setprio 0
	s_add_u32 s86, s46, 0x8000
	s_addc_u32 s87, s47, 0
	s_add_i32 s65, s65, s49
	s_mov_b32 m0, s65
	ds_read_b128 v[162:165], v243 offset:49152
	ds_read_b128 v[166:169], v243 offset:50176
	ds_read_b128 v[170:173], v243 offset:51200
	ds_read_b128 v[174:177], v243 offset:52224
	ds_read_b128 v[178:181], v243 offset:53248
	ds_read_b128 v[182:185], v243 offset:54272
	ds_read_b128 v[198:201], v243 offset:55296
	ds_read_b128 v[202:205], v243 offset:56320
	global_load_lds_dwordx4 v188, s[86:87]
	s_add_i32 m0, s65, 0x2000
	s_add_u32 s46, s46, 0xc000
	s_addc_u32 s47, s47, 0
	s_add_i32 s65, s66, s49
	global_load_lds_dwordx4 v192, s[86:87]
	s_mov_b32 m0, s65
	s_nop 0
	global_load_lds_dwordx4 v188, s[46:47]
	s_add_i32 m0, s65, 0x2000
	s_nop 0
	global_load_lds_dwordx4 v192, s[46:47]
	s_mov_b32 m0, s83
	s_nop 0
	global_load_lds_dwordx4 v186, s[36:37]
	v_lshl_add_u64 v[206:207], s[36:37], 0, v[190:191]
	s_mov_b32 m0, s85
	s_nop 0
	global_load_lds_dwordx4 v[206:207], off
	s_waitcnt vmcnt(8)
	s_waitcnt lgkmcnt(0)
	s_barrier
	s_setprio 1
	v_mfma_f32_16x16x32_bf16 v[62:65], v[130:133], v[162:165], v[62:65]
	v_mfma_f32_16x16x32_bf16 v[62:65], v[134:137], v[166:169], v[62:65]
	v_mfma_f32_16x16x32_bf16 v[58:61], v[142:145], v[166:169], v[58:61]
	v_mfma_f32_16x16x32_bf16 v[58:61], v[138:141], v[162:165], v[58:61]
	v_mfma_f32_16x16x32_bf16 v[42:45], v[138:141], v[170:173], v[42:45]
	v_mfma_f32_16x16x32_bf16 v[42:45], v[142:145], v[174:177], v[42:45]
	v_mfma_f32_16x16x32_bf16 v[46:49], v[134:137], v[174:177], v[46:49]
	v_mfma_f32_16x16x32_bf16 v[46:49], v[130:133], v[170:173], v[46:49]
	v_mfma_f32_16x16x32_bf16 v[30:33], v[130:133], v[178:181], v[30:33]
	v_mfma_f32_16x16x32_bf16 v[30:33], v[134:137], v[182:185], v[30:33]
	v_mfma_f32_16x16x32_bf16 v[26:29], v[142:145], v[182:185], v[26:29]
	v_mfma_f32_16x16x32_bf16 v[26:29], v[138:141], v[178:181], v[26:29]
	v_mfma_f32_16x16x32_bf16 v[10:13], v[138:141], v[198:201], v[10:13]
	v_mfma_f32_16x16x32_bf16 v[10:13], v[142:145], v[202:205], v[10:13]
	v_mfma_f32_16x16x32_bf16 v[14:17], v[134:137], v[202:205], v[14:17]
	v_mfma_f32_16x16x32_bf16 v[14:17], v[130:133], v[198:201], v[14:17]
	s_setprio 0
	s_setprio 1
	v_mfma_f32_16x16x32_bf16 v[54:57], v[146:149], v[162:165], v[54:57]
	v_mfma_f32_16x16x32_bf16 v[54:57], v[150:153], v[166:169], v[54:57]
	v_mfma_f32_16x16x32_bf16 v[50:53], v[158:161], v[166:169], v[50:53]
	v_mfma_f32_16x16x32_bf16 v[50:53], v[154:157], v[162:165], v[50:53]
	v_mfma_f32_16x16x32_bf16 v[34:37], v[154:157], v[170:173], v[34:37]
	v_mfma_f32_16x16x32_bf16 v[34:37], v[158:161], v[174:177], v[34:37]
	v_mfma_f32_16x16x32_bf16 v[38:41], v[150:153], v[174:177], v[38:41]
	v_mfma_f32_16x16x32_bf16 v[38:41], v[146:149], v[170:173], v[38:41]
	v_mfma_f32_16x16x32_bf16 v[22:25], v[146:149], v[178:181], v[22:25]
	v_mfma_f32_16x16x32_bf16 v[22:25], v[150:153], v[182:185], v[22:25]
	v_mfma_f32_16x16x32_bf16 v[18:21], v[158:161], v[182:185], v[18:21]
	v_mfma_f32_16x16x32_bf16 v[18:21], v[154:157], v[178:181], v[18:21]
	v_mfma_f32_16x16x32_bf16 v[2:5], v[154:157], v[198:201], v[2:5]
	v_mfma_f32_16x16x32_bf16 v[2:5], v[158:161], v[202:205], v[2:5]
	v_mfma_f32_16x16x32_bf16 v[6:9], v[150:153], v[202:205], v[6:9]
	v_mfma_f32_16x16x32_bf16 v[6:9], v[146:149], v[198:201], v[6:9]
	s_barrier
	s_setprio 0
	s_add_i32 s57, s57, 2
	s_add_u32 s34, s34, 0x10000
	s_addc_u32 s35, s35, 0
	s_add_u32 s44, s44, 0x10000
	s_addc_u32 s56, s56, 0
	s_cmp_gt_u32 s57, 29
	s_cbranch_scc0 .LBB0_1128
	s_and_b64 vcc, exec, s[92:93]
	s_cbranch_vccz .LBB0_1131
	s_barrier

; #define PG8_STAGE(bufoff, gbase, voff) do { _Pragma("unroll") for (int _i = 0; _i < 2; ++_i) \
;         __builtin_amdgcn_global_load_lds((const unsigned*)((const char*)(gbase) + (voff)[_i]), (PG8_LAS unsigned*)(lds + (bufoff) + ldsw + _i * 8192), 16, 0, 0); } while (0)
; #define PG8_LDA(dst, b, h) do { _Pragma("unroll") for (int m = 0; m < 4; ++m) _Pragma("unroll") for (int k = 0; k < 2; ++k) dst[m][k] = *(const PG8_LAS bf16x8*)(lds + PG8_SA(b, h) + aoff + m * 2048 + k * 1024); } while (0)
; #define PG8_LDB(dst, b, h) do { _Pragma("unroll") for (int n = 0; n < 2; ++n) _Pragma("unroll") for (int k = 0; k < 2; ++k) dst[n][k] = *(const PG8_LAS bf16x8*)(lds + PG8_SB(b, h) + boff + n * 2048 + k * 1024); } while (0)
; #define PG8_MMA(ai, bj, At, Bt) do { __builtin_amdgcn_s_setprio(1); _Pragma("unroll") for (int m = 0; m < 4; ++m) _Pragma("unroll") for (int n = 0; n < 2; ++n) _Pragma("unroll") for (int k = 0; k < 2; ++k) \
;         acc[ai][bj][m][n] = __builtin_amdgcn_mfma_f32_16x16x32_bf16(Bt[n][k], At[m][k], acc[ai][bj][m][n], 0, 0, 0); __builtin_amdgcn_s_setprio(0); } while (0)
; #define PG8_WAIT_V(n) asm volatile("s_waitcnt vmcnt(" #n ")" ::: "memory")
; #define PG8_WAIT_L(n) asm volatile("s_waitcnt lgkmcnt(" #n ")" ::: "memory")
; #define PG8_BAR __builtin_amdgcn_s_barrier()
; #define PG8_SCHED __builtin_amdgcn_sched_barrier(0)
;     ...
;             const bool last = (t == nt - 2);
;             const char* a1 = cA + (ptrdiff_t)(t + 1) * kstepA;
;             const char* a2 = last ? nA : cA + (ptrdiff_t)(t + 2) * kstepA; const char* b2 = last ? nB : cB + (ptrdiff_t)(t + 2) * kstep;
;             const char* a3 = a2 + kstepA; const char* b3 = b2 + kstep;
;             if (last && has_next) S.a_ready(nxt);
;             if constexpr (SP2) {
;             PG8_LDB(B0, 0, 0); PG8_LDB(B1, 0, 1); PG8_SCHED; PG8_LDA(At, 0, 0); PG8_STAGE(PG8_SA(1, 1), a1 + hstepA, voffA);
;             PG8_WAIT_V(8); PG8_WAIT_L(0); PG8_BAR; PG8_MMA(0, 0, At, B0); PG8_MMA(0, 1, At, B1); PG8_BAR; PG8_SCHED;
;             PG8_LDA(At, 0, 1); PG8_STAGE(PG8_SB(0, 0), b2, voffB); PG8_STAGE(PG8_SB(0, 1), b2 + hstepB, voffB); PG8_STAGE(PG8_SA(0, 0), a2, voffA);
;             PG8_WAIT_V(8); PG8_WAIT_L(0); PG8_BAR; PG8_MMA(1, 0, At, B0); PG8_MMA(1, 1, At, B1); PG8_BAR; PG8_SCHED;
.Lup_nostg:
	s_add_u32 s36, s34, 0x10000
	s_addc_u32 s37, s35, 0
	s_cmp_eq_u32 s66, 28
	s_cselect_b32 s88, s57, s36
	s_cselect_b32 s89, s27, s37
	s_cselect_b32 s86, vcc_lo, vcc_hi
	s_cselect_b32 s87, s25, s65
	s_add_u32 s46, s88, 0x8000
	s_addc_u32 s47, s89, 0
	s_add_i32 s96, 0, 0x10000
	v_add_u32_e32 v0, s96, v192
	s_add_i32 s97, 0, 0x14000
	ds_read_b128 v[130:133], v0
	ds_read_b128 v[134:137], v0 offset:1024
	ds_read_b128 v[138:141], v0 offset:2048
	ds_read_b128 v[142:145], v0 offset:3072
	v_add_u32_e32 v0, s97, v192
	ds_read_b128 v[146:149], v0
	ds_read_b128 v[150:153], v0 offset:1024
	ds_read_b128 v[154:157], v0 offset:2048
	ds_read_b128 v[170:173], v0 offset:3072
	s_add_i32 m0, s48, 0xc000
	ds_read_b128 v[174:177], v193
	ds_read_b128 v[178:181], v193 offset:1024
	ds_read_b128 v[182:185], v193 offset:2048
	ds_read_b128 v[186:189], v193 offset:3072
	ds_read_b128 v[194:197], v193 offset:4096
	ds_read_b128 v[198:201], v193 offset:5120
	ds_read_b128 v[202:205], v193 offset:6144
	ds_read_b128 v[206:209], v193 offset:7168
	global_load_lds_dwordx4 v166, s[34:35]
	s_add_i32 m0, s48, 0xe000
	s_nop 0
	global_load_lds_dwordx4 v168, s[34:35]
	s_waitcnt vmcnt(8)
	s_waitcnt lgkmcnt(0)
	s_barrier
	s_setprio 1
	v_mfma_f32_16x16x32_bf16 v[126:129], v[130:133], v[174:177], 0
	v_mfma_f32_16x16x32_bf16 v[126:129], v[134:137], v[178:181], v[126:129]
	v_mfma_f32_16x16x32_bf16 v[122:125], v[142:145], v[178:181], 0
	v_mfma_f32_16x16x32_bf16 v[122:125], v[138:141], v[174:177], v[122:125]
	v_mfma_f32_16x16x32_bf16 v[114:117], v[138:141], v[182:185], 0
	v_mfma_f32_16x16x32_bf16 v[114:117], v[142:145], v[186:189], v[114:117]
	v_mfma_f32_16x16x32_bf16 v[118:121], v[134:137], v[186:189], 0
	v_mfma_f32_16x16x32_bf16 v[118:121], v[130:133], v[182:185], v[118:121]
	v_mfma_f32_16x16x32_bf16 v[110:113], v[130:133], v[194:197], 0
	v_mfma_f32_16x16x32_bf16 v[110:113], v[134:137], v[198:201], v[110:113]
	v_mfma_f32_16x16x32_bf16 v[106:109], v[142:145], v[198:201], 0
	v_mfma_f32_16x16x32_bf16 v[106:109], v[138:141], v[194:197], v[106:109]
	v_mfma_f32_16x16x32_bf16 v[98:101], v[138:141], v[202:205], 0
	v_mfma_f32_16x16x32_bf16 v[98:101], v[142:145], v[206:209], v[98:101]
	v_mfma_f32_16x16x32_bf16 v[102:105], v[134:137], v[206:209], 0
	v_mfma_f32_16x16x32_bf16 v[102:105], v[130:133], v[202:205], v[102:105]
	s_setprio 0
	s_setprio 1
	v_mfma_f32_16x16x32_bf16 v[30:33], v[146:149], v[174:177], 0
	v_mfma_f32_16x16x32_bf16 v[30:33], v[150:153], v[178:181], v[30:33]
	v_mfma_f32_16x16x32_bf16 v[46:49], v[170:173], v[178:181], 0
	v_mfma_f32_16x16x32_bf16 v[46:49], v[154:157], v[174:177], v[46:49]
	v_mfma_f32_16x16x32_bf16 v[34:37], v[154:157], v[182:185], 0
	v_mfma_f32_16x16x32_bf16 v[34:37], v[170:173], v[186:189], v[34:37]
	v_mfma_f32_16x16x32_bf16 v[26:29], v[150:153], v[186:189], 0
	v_mfma_f32_16x16x32_bf16 v[26:29], v[146:149], v[182:185], v[26:29]
	v_mfma_f32_16x16x32_bf16 v[94:97], v[146:149], v[194:197], 0
	v_mfma_f32_16x16x32_bf16 v[94:97], v[150:153], v[198:201], v[94:97]
	v_mfma_f32_16x16x32_bf16 v[90:93], v[170:173], v[198:201], 0
	v_mfma_f32_16x16x32_bf16 v[90:93], v[154:157], v[194:197], v[90:93]
	v_mfma_f32_16x16x32_bf16 v[82:85], v[154:157], v[202:205], 0
	v_mfma_f32_16x16x32_bf16 v[82:85], v[170:173], v[206:209], v[82:85]
	v_mfma_f32_16x16x32_bf16 v[86:89], v[150:153], v[206:209], 0
	v_mfma_f32_16x16x32_bf16 v[86:89], v[146:149], v[202:205], v[86:89]
	s_barrier
	s_setprio 0
	s_add_i32 s34, s96, s44
	s_mov_b32 m0, s34
	ds_read_b128 v[174:177], v193 offset:16384
	ds_read_b128 v[178:181], v193 offset:17408
	ds_read_b128 v[182:185], v193 offset:18432
	ds_read_b128 v[186:189], v193 offset:19456
	ds_read_b128 v[194:197], v193 offset:20480
	ds_read_b128 v[198:201], v193 offset:21504
	ds_read_b128 v[202:205], v193 offset:22528
	ds_read_b128 v[206:209], v193 offset:23552
	global_load_lds_dwordx4 v162, s[86:87]
	s_add_i32 m0, s34, 0x2000
	s_add_u32 s34, s86, 0x4000
	s_addc_u32 s35, s87, 0
	s_add_i32 s96, s97, s44
	global_load_lds_dwordx4 v158, s[86:87]
	s_mov_b32 m0, s96
	v_lshl_add_u64 v[210:211], s[88:89], 0, v[160:161]
	global_load_lds_dwordx4 v162, s[34:35]
	s_add_i32 m0, s96, 0x2000
	s_nop 0
	global_load_lds_dwordx4 v158, s[34:35]
	v_lshl_add_u64 v[190:191], s[88:89], 0, v[164:165]
	s_mov_b32 m0, s48
	s_nop 0
	global_load_lds_dwordx4 v[190:191], off
	s_mov_b32 m0, s49
	s_nop 0
	global_load_lds_dwordx4 v[210:211], off
	s_waitcnt vmcnt(8)
	s_waitcnt lgkmcnt(0)
	s_barrier
	s_setprio 1
	v_mfma_f32_16x16x32_bf16 v[78:81], v[130:133], v[174:177], 0
	v_mfma_f32_16x16x32_bf16 v[78:81], v[134:137], v[178:181], v[78:81]
	v_mfma_f32_16x16x32_bf16 v[74:77], v[142:145], v[178:181], 0
	v_mfma_f32_16x16x32_bf16 v[74:77], v[138:141], v[174:177], v[74:77]
	v_mfma_f32_16x16x32_bf16 v[66:69], v[138:141], v[182:185], 0
	v_mfma_f32_16x16x32_bf16 v[66:69], v[142:145], v[186:189], v[66:69]
	v_mfma_f32_16x16x32_bf16 v[70:73], v[134:137], v[186:189], 0
	v_mfma_f32_16x16x32_bf16 v[70:73], v[130:133], v[182:185], v[70:73]
	v_mfma_f32_16x16x32_bf16 v[42:45], v[130:133], v[194:197], 0
	v_mfma_f32_16x16x32_bf16 v[42:45], v[134:137], v[198:201], v[42:45]
	v_mfma_f32_16x16x32_bf16 v[6:9], v[142:145], v[198:201], 0
	v_mfma_f32_16x16x32_bf16 v[6:9], v[138:141], v[194:197], v[6:9]
	v_mfma_f32_16x16x32_bf16 v[2:5], v[138:141], v[202:205], 0
	v_mfma_f32_16x16x32_bf16 v[2:5], v[142:145], v[206:209], v[2:5]
	v_mfma_f32_16x16x32_bf16 v[38:41], v[134:137], v[206:209], 0
	v_mfma_f32_16x16x32_bf16 v[38:41], v[130:133], v[202:205], v[38:41]
	s_setprio 0
	s_setprio 1
	v_mfma_f32_16x16x32_bf16 v[62:65], v[146:149], v[174:177], 0
	v_mfma_f32_16x16x32_bf16 v[62:65], v[150:153], v[178:181], v[62:65]
	v_mfma_f32_16x16x32_bf16 v[58:61], v[170:173], v[178:181], 0
	v_mfma_f32_16x16x32_bf16 v[58:61], v[154:157], v[174:177], v[58:61]
	v_mfma_f32_16x16x32_bf16 v[50:53], v[154:157], v[182:185], 0
	v_mfma_f32_16x16x32_bf16 v[50:53], v[170:173], v[186:189], v[50:53]
	v_mfma_f32_16x16x32_bf16 v[54:57], v[150:153], v[186:189], 0
	v_mfma_f32_16x16x32_bf16 v[54:57], v[146:149], v[182:185], v[54:57]
	v_mfma_f32_16x16x32_bf16 v[22:25], v[146:149], v[194:197], 0
	v_mfma_f32_16x16x32_bf16 v[22:25], v[150:153], v[198:201], v[22:25]
	v_mfma_f32_16x16x32_bf16 v[18:21], v[170:173], v[198:201], 0
	v_mfma_f32_16x16x32_bf16 v[18:21], v[154:157], v[194:197], v[18:21]
	v_mfma_f32_16x16x32_bf16 v[10:13], v[154:157], v[202:205], 0
	v_mfma_f32_16x16x32_bf16 v[10:13], v[170:173], v[206:209], v[10:13]
	v_mfma_f32_16x16x32_bf16 v[14:17], v[150:153], v[206:209], 0
	v_mfma_f32_16x16x32_bf16 v[14:17], v[146:149], v[202:205], v[14:17]
	s_barrier
	s_setprio 0
	s_branch .Lup_mid

; #define PG8_STAGE(bufoff, gbase, voff) do { _Pragma("unroll") for (int _i = 0; _i < 2; ++_i) \
;         __builtin_amdgcn_global_load_lds((const unsigned*)((const char*)(gbase) + (voff)[_i]), (PG8_LAS unsigned*)(lds + (bufoff) + ldsw + _i * 8192), 16, 0, 0); } while (0)
; #define PG8_LDA(dst, b, h) do { _Pragma("unroll") for (int m = 0; m < 4; ++m) _Pragma("unroll") for (int k = 0; k < 2; ++k) dst[m][k] = *(const PG8_LAS bf16x8*)(lds + PG8_SA(b, h) + aoff + m * 2048 + k * 1024); } while (0)
; #define PG8_LDB(dst, b, h) do { _Pragma("unroll") for (int n = 0; n < 2; ++n) _Pragma("unroll") for (int k = 0; k < 2; ++k) dst[n][k] = *(const PG8_LAS bf16x8*)(lds + PG8_SB(b, h) + boff + n * 2048 + k * 1024); } while (0)
; #define PG8_MMA(ai, bj, At, Bt) do { __builtin_amdgcn_s_setprio(1); _Pragma("unroll") for (int m = 0; m < 4; ++m) _Pragma("unroll") for (int n = 0; n < 2; ++n) _Pragma("unroll") for (int k = 0; k < 2; ++k) \
;         acc[ai][bj][m][n] = __builtin_amdgcn_mfma_f32_16x16x32_bf16(Bt[n][k], At[m][k], acc[ai][bj][m][n], 0, 0, 0); __builtin_amdgcn_s_setprio(0); } while (0)
; #define PG8_WAIT_V(n) asm volatile("s_waitcnt vmcnt(" #n ")" ::: "memory")
; #define PG8_WAIT_L(n) asm volatile("s_waitcnt lgkmcnt(" #n ")" ::: "memory")
; #define PG8_BAR __builtin_amdgcn_s_barrier()
; #define PG8_SCHED __builtin_amdgcn_sched_barrier(0)
;     ...
;             const bool last = (t == nt - 2);
;             const char* a1 = cA + (ptrdiff_t)(t + 1) * kstepA;
;             const char* a2 = last ? nA : cA + (ptrdiff_t)(t + 2) * kstepA; const char* b2 = last ? nB : cB + (ptrdiff_t)(t + 2) * kstep;
;             const char* a3 = a2 + kstepA; const char* b3 = b2 + kstep;
;             if (last && has_next) S.a_ready(nxt);
;             if constexpr (SP2) {
;             PG8_LDB(B0, 0, 0); PG8_LDB(B1, 0, 1); PG8_SCHED; PG8_LDA(At, 0, 0); PG8_STAGE(PG8_SA(1, 1), a1 + hstepA, voffA);
;             PG8_WAIT_V(8); PG8_WAIT_L(0); PG8_BAR; PG8_MMA(0, 0, At, B0); PG8_MMA(0, 1, At, B1); PG8_BAR; PG8_SCHED;
;             PG8_LDA(At, 0, 1); PG8_STAGE(PG8_SB(0, 0), b2, voffB); PG8_STAGE(PG8_SB(0, 1), b2 + hstepB, voffB); PG8_STAGE(PG8_SA(0, 0), a2, voffA);
;             PG8_WAIT_V(8); PG8_WAIT_L(0); PG8_BAR; PG8_MMA(1, 0, At, B0); PG8_MMA(1, 1, At, B1); PG8_BAR; PG8_SCHED;
.LBB0_1256:
	s_add_u32 s36, s34, 0x10000
	s_addc_u32 s37, s35, 0
	s_cmp_eq_u32 s66, 28
	s_cselect_b32 s88, s57, s36
	s_cselect_b32 s89, s27, s37
	s_cselect_b32 s86, vcc_lo, vcc_hi
	s_cselect_b32 s87, s25, s65
	s_add_u32 s46, s88, 0x8000
	s_addc_u32 s47, s89, 0
	s_add_i32 s96, 0, 0x10000
	v_add_u32_e32 v0, s96, v192
	s_add_i32 s97, 0, 0x14000
	ds_read_b128 v[130:133], v0
	ds_read_b128 v[134:137], v0 offset:1024
	ds_read_b128 v[138:141], v0 offset:2048
	ds_read_b128 v[142:145], v0 offset:3072
	v_add_u32_e32 v0, s97, v192
	ds_read_b128 v[146:149], v0
	ds_read_b128 v[150:153], v0 offset:1024
	ds_read_b128 v[154:157], v0 offset:2048
	ds_read_b128 v[170:173], v0 offset:3072
	s_add_i32 m0, s48, 0xc000
	ds_read_b128 v[174:177], v193
	ds_read_b128 v[178:181], v193 offset:1024
	ds_read_b128 v[182:185], v193 offset:2048
	ds_read_b128 v[186:189], v193 offset:3072
	ds_read_b128 v[194:197], v193 offset:4096
	ds_read_b128 v[198:201], v193 offset:5120
	ds_read_b128 v[202:205], v193 offset:6144
	ds_read_b128 v[206:209], v193 offset:7168
	global_load_lds_dwordx4 v166, s[34:35]
	s_add_i32 m0, s48, 0xe000
	s_nop 0
	global_load_lds_dwordx4 v168, s[34:35]
	s_waitcnt vmcnt(8)
	s_waitcnt lgkmcnt(0)
	s_barrier
	s_setprio 1
	v_mfma_f32_16x16x32_bf16 v[126:129], v[130:133], v[174:177], v[126:129]
	v_mfma_f32_16x16x32_bf16 v[126:129], v[134:137], v[178:181], v[126:129]
	v_mfma_f32_16x16x32_bf16 v[122:125], v[142:145], v[178:181], v[122:125]
	v_mfma_f32_16x16x32_bf16 v[122:125], v[138:141], v[174:177], v[122:125]
	v_mfma_f32_16x16x32_bf16 v[114:117], v[138:141], v[182:185], v[114:117]
	v_mfma_f32_16x16x32_bf16 v[114:117], v[142:145], v[186:189], v[114:117]
	v_mfma_f32_16x16x32_bf16 v[118:121], v[134:137], v[186:189], v[118:121]
	v_mfma_f32_16x16x32_bf16 v[118:121], v[130:133], v[182:185], v[118:121]
	v_mfma_f32_16x16x32_bf16 v[110:113], v[130:133], v[194:197], v[110:113]
	v_mfma_f32_16x16x32_bf16 v[110:113], v[134:137], v[198:201], v[110:113]
	v_mfma_f32_16x16x32_bf16 v[106:109], v[142:145], v[198:201], v[106:109]
	v_mfma_f32_16x16x32_bf16 v[106:109], v[138:141], v[194:197], v[106:109]
	v_mfma_f32_16x16x32_bf16 v[98:101], v[138:141], v[202:205], v[98:101]
	v_mfma_f32_16x16x32_bf16 v[98:101], v[142:145], v[206:209], v[98:101]
	v_mfma_f32_16x16x32_bf16 v[102:105], v[134:137], v[206:209], v[102:105]
	v_mfma_f32_16x16x32_bf16 v[102:105], v[130:133], v[202:205], v[102:105]
	s_setprio 0
	s_setprio 1
	v_mfma_f32_16x16x32_bf16 v[30:33], v[146:149], v[174:177], v[30:33]
	v_mfma_f32_16x16x32_bf16 v[30:33], v[150:153], v[178:181], v[30:33]
	v_mfma_f32_16x16x32_bf16 v[46:49], v[170:173], v[178:181], v[46:49]
	v_mfma_f32_16x16x32_bf16 v[46:49], v[154:157], v[174:177], v[46:49]
	v_mfma_f32_16x16x32_bf16 v[34:37], v[154:157], v[182:185], v[34:37]
	v_mfma_f32_16x16x32_bf16 v[34:37], v[170:173], v[186:189], v[34:37]
	v_mfma_f32_16x16x32_bf16 v[26:29], v[150:153], v[186:189], v[26:29]
	v_mfma_f32_16x16x32_bf16 v[26:29], v[146:149], v[182:185], v[26:29]
	v_mfma_f32_16x16x32_bf16 v[94:97], v[146:149], v[194:197], v[94:97]
	v_mfma_f32_16x16x32_bf16 v[94:97], v[150:153], v[198:201], v[94:97]
	v_mfma_f32_16x16x32_bf16 v[90:93], v[170:173], v[198:201], v[90:93]
	v_mfma_f32_16x16x32_bf16 v[90:93], v[154:157], v[194:197], v[90:93]
	v_mfma_f32_16x16x32_bf16 v[82:85], v[154:157], v[202:205], v[82:85]
	v_mfma_f32_16x16x32_bf16 v[82:85], v[170:173], v[206:209], v[82:85]
	v_mfma_f32_16x16x32_bf16 v[86:89], v[150:153], v[206:209], v[86:89]
	v_mfma_f32_16x16x32_bf16 v[86:89], v[146:149], v[202:205], v[86:89]
	s_barrier
	s_setprio 0
	s_add_i32 s34, s96, s44
	s_mov_b32 m0, s34
	ds_read_b128 v[174:177], v193 offset:16384
	ds_read_b128 v[178:181], v193 offset:17408
	ds_read_b128 v[182:185], v193 offset:18432
	ds_read_b128 v[186:189], v193 offset:19456
	ds_read_b128 v[194:197], v193 offset:20480
	ds_read_b128 v[198:201], v193 offset:21504
	ds_read_b128 v[202:205], v193 offset:22528
	ds_read_b128 v[206:209], v193 offset:23552
	global_load_lds_dwordx4 v162, s[86:87]
	s_add_i32 m0, s34, 0x2000
	s_add_u32 s34, s86, 0x4000
	s_addc_u32 s35, s87, 0
	s_add_i32 s96, s97, s44
	global_load_lds_dwordx4 v158, s[86:87]
	s_mov_b32 m0, s96
	v_lshl_add_u64 v[210:211], s[88:89], 0, v[160:161]
	global_load_lds_dwordx4 v162, s[34:35]
	s_add_i32 m0, s96, 0x2000
	s_nop 0
	global_load_lds_dwordx4 v158, s[34:35]
	v_lshl_add_u64 v[190:191], s[88:89], 0, v[164:165]
	s_mov_b32 m0, s48
	s_nop 0
	global_load_lds_dwordx4 v[190:191], off
	s_mov_b32 m0, s49
	s_nop 0
	global_load_lds_dwordx4 v[210:211], off
	s_waitcnt vmcnt(8)
	s_waitcnt lgkmcnt(0)
	s_barrier
	s_setprio 1
	v_mfma_f32_16x16x32_bf16 v[78:81], v[130:133], v[174:177], v[78:81]
	v_mfma_f32_16x16x32_bf16 v[78:81], v[134:137], v[178:181], v[78:81]
	v_mfma_f32_16x16x32_bf16 v[74:77], v[142:145], v[178:181], v[74:77]
	v_mfma_f32_16x16x32_bf16 v[74:77], v[138:141], v[174:177], v[74:77]
	v_mfma_f32_16x16x32_bf16 v[66:69], v[138:141], v[182:185], v[66:69]
	v_mfma_f32_16x16x32_bf16 v[66:69], v[142:145], v[186:189], v[66:69]
	v_mfma_f32_16x16x32_bf16 v[70:73], v[134:137], v[186:189], v[70:73]
	v_mfma_f32_16x16x32_bf16 v[70:73], v[130:133], v[182:185], v[70:73]
	v_mfma_f32_16x16x32_bf16 v[42:45], v[130:133], v[194:197], v[42:45]
	v_mfma_f32_16x16x32_bf16 v[42:45], v[134:137], v[198:201], v[42:45]
	v_mfma_f32_16x16x32_bf16 v[6:9], v[142:145], v[198:201], v[6:9]
	v_mfma_f32_16x16x32_bf16 v[6:9], v[138:141], v[194:197], v[6:9]
	v_mfma_f32_16x16x32_bf16 v[2:5], v[138:141], v[202:205], v[2:5]
	v_mfma_f32_16x16x32_bf16 v[2:5], v[142:145], v[206:209], v[2:5]
	v_mfma_f32_16x16x32_bf16 v[38:41], v[134:137], v[206:209], v[38:41]
	v_mfma_f32_16x16x32_bf16 v[38:41], v[130:133], v[202:205], v[38:41]
	s_setprio 0
	s_setprio 1
	v_mfma_f32_16x16x32_bf16 v[62:65], v[146:149], v[174:177], v[62:65]
	v_mfma_f32_16x16x32_bf16 v[62:65], v[150:153], v[178:181], v[62:65]
	v_mfma_f32_16x16x32_bf16 v[58:61], v[170:173], v[178:181], v[58:61]
	v_mfma_f32_16x16x32_bf16 v[58:61], v[154:157], v[174:177], v[58:61]
	v_mfma_f32_16x16x32_bf16 v[50:53], v[154:157], v[182:185], v[50:53]
	v_mfma_f32_16x16x32_bf16 v[50:53], v[170:173], v[186:189], v[50:53]
	v_mfma_f32_16x16x32_bf16 v[54:57], v[150:153], v[186:189], v[54:57]
	v_mfma_f32_16x16x32_bf16 v[54:57], v[146:149], v[182:185], v[54:57]
	v_mfma_f32_16x16x32_bf16 v[22:25], v[146:149], v[194:197], v[22:25]
	v_mfma_f32_16x16x32_bf16 v[22:25], v[150:153], v[198:201], v[22:25]
	v_mfma_f32_16x16x32_bf16 v[18:21], v[170:173], v[198:201], v[18:21]
	v_mfma_f32_16x16x32_bf16 v[18:21], v[154:157], v[194:197], v[18:21]
	v_mfma_f32_16x16x32_bf16 v[10:13], v[154:157], v[202:205], v[10:13]
	v_mfma_f32_16x16x32_bf16 v[10:13], v[170:173], v[206:209], v[10:13]
	v_mfma_f32_16x16x32_bf16 v[14:17], v[150:153], v[206:209], v[14:17]
	v_mfma_f32_16x16x32_bf16 v[14:17], v[146:149], v[202:205], v[14:17]
	s_barrier
	s_setprio 0
; #define PG8_STAGE(bufoff, gbase, voff) do { _Pragma("unroll") for (int _i = 0; _i < 2; ++_i) \
;         __builtin_amdgcn_global_load_lds((const unsigned*)((const char*)(gbase) + (voff)[_i]), (PG8_LAS unsigned*)(lds + (bufoff) + ldsw + _i * 8192), 16, 0, 0); } while (0)
; #define PG8_LDA(dst, b, h) do { _Pragma("unroll") for (int m = 0; m < 4; ++m) _Pragma("unroll") for (int k = 0; k < 2; ++k) dst[m][k] = *(const PG8_LAS bf16x8*)(lds + PG8_SA(b, h) + aoff + m * 2048 + k * 1024); } while (0)
; #define PG8_LDB(dst, b, h) do { _Pragma("unroll") for (int n = 0; n < 2; ++n) _Pragma("unroll") for (int k = 0; k < 2; ++k) dst[n][k] = *(const PG8_LAS bf16x8*)(lds + PG8_SB(b, h) + boff + n * 2048 + k * 1024); } while (0)
; #define PG8_MMA(ai, bj, At, Bt) do { __builtin_amdgcn_s_setprio(1); _Pragma("unroll") for (int m = 0; m < 4; ++m) _Pragma("unroll") for (int n = 0; n < 2; ++n) _Pragma("unroll") for (int k = 0; k < 2; ++k) \
;         acc[ai][bj][m][n] = __builtin_amdgcn_mfma_f32_16x16x32_bf16(Bt[n][k], At[m][k], acc[ai][bj][m][n], 0, 0, 0); __builtin_amdgcn_s_setprio(0); } while (0)
; #define PG8_WAIT_V(n) asm volatile("s_waitcnt vmcnt(" #n ")" ::: "memory")
; #define PG8_WAIT_L(n) asm volatile("s_waitcnt lgkmcnt(" #n ")" ::: "memory")
; #define PG8_BAR __builtin_amdgcn_s_barrier()
; #define PG8_SCHED __builtin_amdgcn_sched_barrier(0)
;     ...
;         for (int t = 0; t < nt; t += 2) {
;     ...
;             PG8_LDB(B0, 1, 0); PG8_LDB(B1, 1, 1); PG8_SCHED; PG8_LDA(At, 1, 0); PG8_STAGE(PG8_SA(0, 1), a2 + hstepA, voffA);
;             PG8_WAIT_V(8); PG8_WAIT_L(0); PG8_BAR; PG8_MMA(0, 0, At, B0); PG8_MMA(0, 1, At, B1); PG8_BAR; PG8_SCHED;
;             PG8_LDA(At, 1, 1); PG8_STAGE(PG8_SB(1, 0), b3, voffB); PG8_STAGE(PG8_SB(1, 1), b3 + hstepB, voffB); PG8_STAGE(PG8_SA(1, 0), a3, voffA);
;             PG8_WAIT_V(8); PG8_WAIT_L(0); PG8_BAR; PG8_MMA(1, 0, At, B0); PG8_MMA(1, 1, At, B1); PG8_BAR; PG8_SCHED;
.Lup_mid:
	s_add_i32 s88, 0, 0x18000
	v_add_u32_e32 v0, s88, v192
	s_add_i32 s89, 0, 0x1c000
	ds_read_b128 v[130:133], v0
	ds_read_b128 v[134:137], v0 offset:1024
	ds_read_b128 v[138:141], v0 offset:2048
	ds_read_b128 v[142:145], v0 offset:3072
	v_add_u32_e32 v0, s89, v192
	ds_read_b128 v[146:149], v0
	ds_read_b128 v[150:153], v0 offset:1024
	ds_read_b128 v[154:157], v0 offset:2048
	ds_read_b128 v[170:173], v0 offset:3072
	s_mov_b32 m0, s51
	v_lshl_add_u64 v[190:191], v[190:191], 0, s[58:59]
	ds_read_b128 v[174:177], v193 offset:32768
	ds_read_b128 v[178:181], v193 offset:33792
	ds_read_b128 v[182:185], v193 offset:34816
	ds_read_b128 v[186:189], v193 offset:35840
	ds_read_b128 v[194:197], v193 offset:36864
	ds_read_b128 v[198:201], v193 offset:37888
	ds_read_b128 v[202:205], v193 offset:38912
	ds_read_b128 v[206:209], v193 offset:39936
	global_load_lds_dwordx4 v[190:191], off
	v_lshl_add_u64 v[190:191], v[210:211], 0, s[58:59]
	s_mov_b32 m0, s54
	s_nop 0
	global_load_lds_dwordx4 v[190:191], off
	s_waitcnt vmcnt(8)
	s_waitcnt lgkmcnt(0)
	s_barrier
	s_setprio 1
	v_mfma_f32_16x16x32_bf16 v[126:129], v[130:133], v[174:177], v[126:129]
	v_mfma_f32_16x16x32_bf16 v[126:129], v[134:137], v[178:181], v[126:129]
	v_mfma_f32_16x16x32_bf16 v[122:125], v[142:145], v[178:181], v[122:125]
	v_mfma_f32_16x16x32_bf16 v[122:125], v[138:141], v[174:177], v[122:125]
	v_mfma_f32_16x16x32_bf16 v[114:117], v[138:141], v[182:185], v[114:117]
	v_mfma_f32_16x16x32_bf16 v[114:117], v[142:145], v[186:189], v[114:117]
	v_mfma_f32_16x16x32_bf16 v[118:121], v[134:137], v[186:189], v[118:121]
	v_mfma_f32_16x16x32_bf16 v[118:121], v[130:133], v[182:185], v[118:121]
	v_mfma_f32_16x16x32_bf16 v[110:113], v[130:133], v[194:197], v[110:113]
	v_mfma_f32_16x16x32_bf16 v[110:113], v[134:137], v[198:201], v[110:113]
	v_mfma_f32_16x16x32_bf16 v[106:109], v[142:145], v[198:201], v[106:109]
	v_mfma_f32_16x16x32_bf16 v[106:109], v[138:141], v[194:197], v[106:109]
	v_mfma_f32_16x16x32_bf16 v[98:101], v[138:141], v[202:205], v[98:101]
	v_mfma_f32_16x16x32_bf16 v[98:101], v[142:145], v[206:209], v[98:101]
	v_mfma_f32_16x16x32_bf16 v[102:105], v[134:137], v[206:209], v[102:105]
	v_mfma_f32_16x16x32_bf16 v[102:105], v[130:133], v[202:205], v[102:105]
	s_setprio 0
	s_setprio 1
	v_mfma_f32_16x16x32_bf16 v[30:33], v[146:149], v[174:177], v[30:33]
	v_mfma_f32_16x16x32_bf16 v[30:33], v[150:153], v[178:181], v[30:33]
	v_mfma_f32_16x16x32_bf16 v[46:49], v[170:173], v[178:181], v[46:49]
	v_mfma_f32_16x16x32_bf16 v[46:49], v[154:157], v[174:177], v[46:49]
	v_mfma_f32_16x16x32_bf16 v[34:37], v[154:157], v[182:185], v[34:37]
	v_mfma_f32_16x16x32_bf16 v[34:37], v[170:173], v[186:189], v[34:37]
	v_mfma_f32_16x16x32_bf16 v[26:29], v[150:153], v[186:189], v[26:29]
	v_mfma_f32_16x16x32_bf16 v[26:29], v[146:149], v[182:185], v[26:29]
	v_mfma_f32_16x16x32_bf16 v[94:97], v[146:149], v[194:197], v[94:97]
	v_mfma_f32_16x16x32_bf16 v[94:97], v[150:153], v[198:201], v[94:97]
	v_mfma_f32_16x16x32_bf16 v[90:93], v[170:173], v[198:201], v[90:93]
	v_mfma_f32_16x16x32_bf16 v[90:93], v[154:157], v[194:197], v[90:93]
	v_mfma_f32_16x16x32_bf16 v[82:85], v[154:157], v[202:205], v[82:85]
	v_mfma_f32_16x16x32_bf16 v[82:85], v[170:173], v[206:209], v[82:85]
	v_mfma_f32_16x16x32_bf16 v[86:89], v[150:153], v[206:209], v[86:89]
	v_mfma_f32_16x16x32_bf16 v[86:89], v[146:149], v[202:205], v[86:89]
	s_barrier
	s_setprio 0
	s_add_u32 s34, s86, 0x8000
	s_addc_u32 s35, s87, 0
	s_add_i32 s88, s88, s44
	s_mov_b32 m0, s88
	ds_read_b128 v[174:177], v193 offset:49152
	ds_read_b128 v[178:181], v193 offset:50176
	ds_read_b128 v[182:185], v193 offset:51200
	ds_read_b128 v[186:189], v193 offset:52224
	ds_read_b128 v[194:197], v193 offset:53248
	ds_read_b128 v[198:201], v193 offset:54272
	ds_read_b128 v[202:205], v193 offset:55296
	ds_read_b128 v[206:209], v193 offset:56320
	global_load_lds_dwordx4 v162, s[34:35]
	s_add_i32 m0, s88, 0x2000
	v_lshl_add_u64 v[190:191], s[34:35], 0, v[158:159]
	s_add_u32 s34, s86, 0xc000
	s_addc_u32 s35, s87, 0
	s_add_i32 s86, s89, s44
	global_load_lds_dwordx4 v[190:191], off
	s_mov_b32 m0, s86
	s_nop 0
	global_load_lds_dwordx4 v162, s[34:35]
	s_add_i32 m0, s86, 0x2000
	s_nop 0
	global_load_lds_dwordx4 v158, s[34:35]
	s_mov_b32 m0, s85
	s_nop 0
	global_load_lds_dwordx4 v164, s[46:47]
	v_lshl_add_u64 v[190:191], s[46:47], 0, v[160:161]
	s_mov_b32 m0, s90
	s_nop 0
	global_load_lds_dwordx4 v[190:191], off
	s_waitcnt vmcnt(8)
	s_waitcnt lgkmcnt(0)
	s_barrier
	s_setprio 1
	v_mfma_f32_16x16x32_bf16 v[78:81], v[130:133], v[174:177], v[78:81]
	v_mfma_f32_16x16x32_bf16 v[78:81], v[134:137], v[178:181], v[78:81]
	v_mfma_f32_16x16x32_bf16 v[74:77], v[142:145], v[178:181], v[74:77]
	v_mfma_f32_16x16x32_bf16 v[74:77], v[138:141], v[174:177], v[74:77]
	v_mfma_f32_16x16x32_bf16 v[66:69], v[138:141], v[182:185], v[66:69]
	v_mfma_f32_16x16x32_bf16 v[66:69], v[142:145], v[186:189], v[66:69]
	v_mfma_f32_16x16x32_bf16 v[70:73], v[134:137], v[186:189], v[70:73]
	v_mfma_f32_16x16x32_bf16 v[70:73], v[130:133], v[182:185], v[70:73]
	v_mfma_f32_16x16x32_bf16 v[42:45], v[130:133], v[194:197], v[42:45]
	v_mfma_f32_16x16x32_bf16 v[42:45], v[134:137], v[198:201], v[42:45]
	v_mfma_f32_16x16x32_bf16 v[6:9], v[142:145], v[198:201], v[6:9]
	v_mfma_f32_16x16x32_bf16 v[6:9], v[138:141], v[194:197], v[6:9]
	v_mfma_f32_16x16x32_bf16 v[2:5], v[138:141], v[202:205], v[2:5]
	v_mfma_f32_16x16x32_bf16 v[2:5], v[142:145], v[206:209], v[2:5]
	v_mfma_f32_16x16x32_bf16 v[38:41], v[134:137], v[206:209], v[38:41]
	v_mfma_f32_16x16x32_bf16 v[38:41], v[130:133], v[202:205], v[38:41]
	s_setprio 0
	s_setprio 1
	v_mfma_f32_16x16x32_bf16 v[62:65], v[146:149], v[174:177], v[62:65]
	v_mfma_f32_16x16x32_bf16 v[62:65], v[150:153], v[178:181], v[62:65]
	v_mfma_f32_16x16x32_bf16 v[58:61], v[170:173], v[178:181], v[58:61]
	v_mfma_f32_16x16x32_bf16 v[58:61], v[154:157], v[174:177], v[58:61]
	v_mfma_f32_16x16x32_bf16 v[50:53], v[154:157], v[182:185], v[50:53]
	v_mfma_f32_16x16x32_bf16 v[50:53], v[170:173], v[186:189], v[50:53]
	v_mfma_f32_16x16x32_bf16 v[54:57], v[150:153], v[186:189], v[54:57]
	v_mfma_f32_16x16x32_bf16 v[54:57], v[146:149], v[182:185], v[54:57]
	v_mfma_f32_16x16x32_bf16 v[22:25], v[146:149], v[194:197], v[22:25]
	v_mfma_f32_16x16x32_bf16 v[22:25], v[150:153], v[198:201], v[22:25]
	v_mfma_f32_16x16x32_bf16 v[18:21], v[170:173], v[198:201], v[18:21]
	v_mfma_f32_16x16x32_bf16 v[18:21], v[154:157], v[194:197], v[18:21]
	v_mfma_f32_16x16x32_bf16 v[10:13], v[154:157], v[202:205], v[10:13]
	v_mfma_f32_16x16x32_bf16 v[10:13], v[170:173], v[206:209], v[10:13]
	v_mfma_f32_16x16x32_bf16 v[14:17], v[150:153], v[206:209], v[14:17]
	v_mfma_f32_16x16x32_bf16 v[14:17], v[146:149], v[202:205], v[14:17]
	s_barrier
	s_setprio 0
	s_add_i32 s66, s66, 2
	s_add_u32 vcc_hi, vcc_hi, 0x10000
	s_addc_u32 s65, s65, 0
	s_cmp_gt_u32 s66, 29
	s_mov_b64 s[34:35], s[36:37]
	s_cbranch_scc0 .LBB0_1256
	s_and_b64 vcc, exec, s[18:19]
	s_cbranch_vccz .LBB0_1259
	s_barrier

; #define PG8_STAGE(bufoff, gbase, voff) do { _Pragma("unroll") for (int _i = 0; _i < 2; ++_i) \
;         __builtin_amdgcn_global_load_lds((const unsigned*)((const char*)(gbase) + (voff)[_i]), (PG8_LAS unsigned*)(lds + (bufoff) + ldsw + _i * 8192), 16, 0, 0); } while (0)
; #define PG8_LDA(dst, b, h) do { _Pragma("unroll") for (int m = 0; m < 4; ++m) _Pragma("unroll") for (int k = 0; k < 2; ++k) dst[m][k] = *(const PG8_LAS bf16x8*)(lds + PG8_SA(b, h) + aoff + m * 2048 + k * 1024); } while (0)
; #define PG8_LDB(dst, b, h) do { _Pragma("unroll") for (int n = 0; n < 2; ++n) _Pragma("unroll") for (int k = 0; k < 2; ++k) dst[n][k] = *(const PG8_LAS bf16x8*)(lds + PG8_SB(b, h) + boff + n * 2048 + k * 1024); } while (0)
; #define PG8_MMA(ai, bj, At, Bt) do { __builtin_amdgcn_s_setprio(1); _Pragma("unroll") for (int m = 0; m < 4; ++m) _Pragma("unroll") for (int n = 0; n < 2; ++n) _Pragma("unroll") for (int k = 0; k < 2; ++k) \
;         acc[ai][bj][m][n] = __builtin_amdgcn_mfma_f32_16x16x32_bf16(Bt[n][k], At[m][k], acc[ai][bj][m][n], 0, 0, 0); __builtin_amdgcn_s_setprio(0); } while (0)
; #define PG8_WAIT_V(n) asm volatile("s_waitcnt vmcnt(" #n ")" ::: "memory")
; #define PG8_WAIT_L(n) asm volatile("s_waitcnt lgkmcnt(" #n ")" ::: "memory")
; #define PG8_BAR __builtin_amdgcn_s_barrier()
; #define PG8_SCHED __builtin_amdgcn_sched_barrier(0)
;     ...
;             const bool last = (t == nt - 2);
;             const char* a1 = cA + (ptrdiff_t)(t + 1) * kstepA;
;             const char* a2 = last ? nA : cA + (ptrdiff_t)(t + 2) * kstepA; const char* b2 = last ? nB : cB + (ptrdiff_t)(t + 2) * kstep;
;             const char* a3 = a2 + kstepA; const char* b3 = b2 + kstep;
;             if (last && has_next) S.a_ready(nxt);
;             if constexpr (SP2) {
;             PG8_LDB(B0, 0, 0); PG8_LDB(B1, 0, 1); PG8_SCHED; PG8_LDA(At, 0, 0); PG8_STAGE(PG8_SA(1, 1), a1 + hstepA, voffA);
;             PG8_WAIT_V(8); PG8_WAIT_L(0); PG8_BAR; PG8_MMA(0, 0, At, B0); PG8_MMA(0, 1, At, B1); PG8_BAR; PG8_SCHED;
;             PG8_LDA(At, 0, 1); PG8_STAGE(PG8_SB(0, 0), b2, voffB); PG8_STAGE(PG8_SB(0, 1), b2 + hstepB, voffB); PG8_STAGE(PG8_SA(0, 0), a2, voffA);
;             PG8_WAIT_V(8); PG8_WAIT_L(0); PG8_BAR; PG8_MMA(1, 0, At, B0); PG8_MMA(1, 1, At, B1); PG8_BAR; PG8_SCHED;
.Ldn_nostg:
	s_or_b32 s44, s56, 1
	s_lshl_b64 s[34:35], s[44:45], 15
	s_sub_u32 s34, 0, s34
	s_subb_u32 s35, 0, s35
	s_add_u32 s44, s28, s34
	s_addc_u32 s65, s29, s35
	s_add_u32 s34, s30, 0xffff8000
	s_addc_u32 s35, s31, -1
	s_add_i32 s66, 0, 0x10000
	v_add_u32_e32 v0, s66, v230
	s_add_i32 s90, 0, 0x14000
	s_waitcnt lgkmcnt(0)
	ds_read_b128 v[130:133], v0
	ds_read_b128 v[134:137], v0 offset:1024
	ds_read_b128 v[138:141], v0 offset:2048
	ds_read_b128 v[142:145], v0 offset:3072
	v_add_u32_e32 v0, s90, v230
	ds_read_b128 v[146:149], v0
	ds_read_b128 v[150:153], v0 offset:1024
	ds_read_b128 v[154:157], v0 offset:2048
	ds_read_b128 v[158:161], v0 offset:3072
	s_add_u32 s88, s44, 0x4000
	s_addc_u32 s89, s65, 0
	s_add_i32 m0, s46, 0xc000
	ds_read_b128 v[162:165], v231
	ds_read_b128 v[166:169], v231 offset:1024
	ds_read_b128 v[170:173], v231 offset:2048
	ds_read_b128 v[174:177], v231 offset:3072
	ds_read_b128 v[178:181], v231 offset:4096
	ds_read_b128 v[182:185], v231 offset:5120
	ds_read_b128 v[186:189], v231 offset:6144
	ds_read_b128 v[190:193], v231 offset:7168
	global_load_lds_dwordx4 v194, s[88:89]
	s_add_i32 m0, s46, 0xe000
	s_nop 0
	global_load_lds_dwordx4 v198, s[88:89]
	s_waitcnt vmcnt(8)
	s_waitcnt lgkmcnt(0)
	s_barrier
	s_setprio 1
	v_mfma_f32_16x16x32_bf16 v[126:129], v[130:133], v[162:165], 0
	v_mfma_f32_16x16x32_bf16 v[126:129], v[134:137], v[166:169], v[126:129]
	v_mfma_f32_16x16x32_bf16 v[122:125], v[142:145], v[166:169], 0
	v_mfma_f32_16x16x32_bf16 v[122:125], v[138:141], v[162:165], v[122:125]
	v_mfma_f32_16x16x32_bf16 v[106:109], v[138:141], v[170:173], 0
	v_mfma_f32_16x16x32_bf16 v[106:109], v[142:145], v[174:177], v[106:109]
	v_mfma_f32_16x16x32_bf16 v[110:113], v[134:137], v[174:177], 0
	v_mfma_f32_16x16x32_bf16 v[110:113], v[130:133], v[170:173], v[110:113]
	v_mfma_f32_16x16x32_bf16 v[94:97], v[130:133], v[178:181], 0
	v_mfma_f32_16x16x32_bf16 v[94:97], v[134:137], v[182:185], v[94:97]
	v_mfma_f32_16x16x32_bf16 v[90:93], v[142:145], v[182:185], 0
	v_mfma_f32_16x16x32_bf16 v[90:93], v[138:141], v[178:181], v[90:93]
	v_mfma_f32_16x16x32_bf16 v[74:77], v[138:141], v[186:189], 0
	v_mfma_f32_16x16x32_bf16 v[74:77], v[142:145], v[190:193], v[74:77]
	v_mfma_f32_16x16x32_bf16 v[78:81], v[134:137], v[190:193], 0
	v_mfma_f32_16x16x32_bf16 v[78:81], v[130:133], v[186:189], v[78:81]
	s_setprio 0
	s_setprio 1
	v_mfma_f32_16x16x32_bf16 v[118:121], v[146:149], v[162:165], 0
	v_mfma_f32_16x16x32_bf16 v[118:121], v[150:153], v[166:169], v[118:121]
	v_mfma_f32_16x16x32_bf16 v[114:117], v[158:161], v[166:169], 0
	v_mfma_f32_16x16x32_bf16 v[114:117], v[154:157], v[162:165], v[114:117]
	v_mfma_f32_16x16x32_bf16 v[98:101], v[154:157], v[170:173], 0
	v_mfma_f32_16x16x32_bf16 v[98:101], v[158:161], v[174:177], v[98:101]
	v_mfma_f32_16x16x32_bf16 v[102:105], v[150:153], v[174:177], 0
	v_mfma_f32_16x16x32_bf16 v[102:105], v[146:149], v[170:173], v[102:105]
	v_mfma_f32_16x16x32_bf16 v[86:89], v[146:149], v[178:181], 0
	v_mfma_f32_16x16x32_bf16 v[86:89], v[150:153], v[182:185], v[86:89]
	v_mfma_f32_16x16x32_bf16 v[82:85], v[158:161], v[182:185], 0
	v_mfma_f32_16x16x32_bf16 v[82:85], v[154:157], v[178:181], v[82:85]
	v_mfma_f32_16x16x32_bf16 v[66:69], v[154:157], v[186:189], 0
	v_mfma_f32_16x16x32_bf16 v[66:69], v[158:161], v[190:193], v[66:69]
	v_mfma_f32_16x16x32_bf16 v[70:73], v[150:153], v[190:193], 0
	v_mfma_f32_16x16x32_bf16 v[70:73], v[146:149], v[186:189], v[70:73]
	s_barrier
	s_setprio 0
	s_add_i32 s44, s66, s41
	s_mov_b32 m0, s44
	ds_read_b128 v[162:165], v231 offset:16384
	ds_read_b128 v[166:169], v231 offset:17408
	ds_read_b128 v[170:173], v231 offset:18432
	ds_read_b128 v[174:177], v231 offset:19456
	ds_read_b128 v[178:181], v231 offset:20480
	ds_read_b128 v[182:185], v231 offset:21504
	ds_read_b128 v[186:189], v231 offset:22528
	ds_read_b128 v[190:193], v231 offset:23552
	global_load_lds_dwordx4 v196, s[8:9]
	s_add_i32 m0, s44, 0x2000
	s_add_u32 s88, s8, 0x4000
	s_addc_u32 s89, s9, 0
	s_add_i32 s44, s90, s41
	global_load_lds_dwordx4 v200, s[8:9]
	s_mov_b32 m0, s44
	s_nop 0
	global_load_lds_dwordx4 v196, s[88:89]
	s_add_i32 m0, s44, 0x2000
	s_nop 0
	global_load_lds_dwordx4 v200, s[88:89]
	s_mov_b32 m0, s46
	s_nop 0
	global_load_lds_dwordx4 v194, s[30:31]
	s_mov_b32 m0, s47
	s_nop 0
	global_load_lds_dwordx4 v198, s[30:31]
	s_waitcnt vmcnt(8)
	s_waitcnt lgkmcnt(0)
	s_barrier
	s_setprio 1
	v_mfma_f32_16x16x32_bf16 v[62:65], v[130:133], v[162:165], 0
	v_mfma_f32_16x16x32_bf16 v[62:65], v[134:137], v[166:169], v[62:65]
	v_mfma_f32_16x16x32_bf16 v[58:61], v[142:145], v[166:169], 0
	v_mfma_f32_16x16x32_bf16 v[58:61], v[138:141], v[162:165], v[58:61]
	v_mfma_f32_16x16x32_bf16 v[42:45], v[138:141], v[170:173], 0
	v_mfma_f32_16x16x32_bf16 v[42:45], v[142:145], v[174:177], v[42:45]
	v_mfma_f32_16x16x32_bf16 v[46:49], v[134:137], v[174:177], 0
	v_mfma_f32_16x16x32_bf16 v[46:49], v[130:133], v[170:173], v[46:49]
	v_mfma_f32_16x16x32_bf16 v[30:33], v[130:133], v[178:181], 0
	v_mfma_f32_16x16x32_bf16 v[30:33], v[134:137], v[182:185], v[30:33]
	v_mfma_f32_16x16x32_bf16 v[26:29], v[142:145], v[182:185], 0
	v_mfma_f32_16x16x32_bf16 v[26:29], v[138:141], v[178:181], v[26:29]
	v_mfma_f32_16x16x32_bf16 v[10:13], v[138:141], v[186:189], 0
	v_mfma_f32_16x16x32_bf16 v[10:13], v[142:145], v[190:193], v[10:13]
	v_mfma_f32_16x16x32_bf16 v[14:17], v[134:137], v[190:193], 0
	v_mfma_f32_16x16x32_bf16 v[14:17], v[130:133], v[186:189], v[14:17]
	s_setprio 0
	s_setprio 1
	v_mfma_f32_16x16x32_bf16 v[54:57], v[146:149], v[162:165], 0
	v_mfma_f32_16x16x32_bf16 v[54:57], v[150:153], v[166:169], v[54:57]
	v_mfma_f32_16x16x32_bf16 v[50:53], v[158:161], v[166:169], 0
	v_mfma_f32_16x16x32_bf16 v[50:53], v[154:157], v[162:165], v[50:53]
	v_mfma_f32_16x16x32_bf16 v[34:37], v[154:157], v[170:173], 0
	v_mfma_f32_16x16x32_bf16 v[34:37], v[158:161], v[174:177], v[34:37]
	v_mfma_f32_16x16x32_bf16 v[38:41], v[150:153], v[174:177], 0
	v_mfma_f32_16x16x32_bf16 v[38:41], v[146:149], v[170:173], v[38:41]
	v_mfma_f32_16x16x32_bf16 v[22:25], v[146:149], v[178:181], 0
	v_mfma_f32_16x16x32_bf16 v[22:25], v[150:153], v[182:185], v[22:25]
	v_mfma_f32_16x16x32_bf16 v[18:21], v[158:161], v[182:185], 0
	v_mfma_f32_16x16x32_bf16 v[18:21], v[154:157], v[178:181], v[18:21]
	v_mfma_f32_16x16x32_bf16 v[2:5], v[154:157], v[186:189], 0
	v_mfma_f32_16x16x32_bf16 v[2:5], v[158:161], v[190:193], v[2:5]
	v_mfma_f32_16x16x32_bf16 v[6:9], v[150:153], v[190:193], 0
	v_mfma_f32_16x16x32_bf16 v[6:9], v[146:149], v[186:189], v[6:9]
	s_barrier
	s_setprio 0
	s_branch .Ldn_mid

; #define PG8_STAGE(bufoff, gbase, voff) do { _Pragma("unroll") for (int _i = 0; _i < 2; ++_i) \
;         __builtin_amdgcn_global_load_lds((const unsigned*)((const char*)(gbase) + (voff)[_i]), (PG8_LAS unsigned*)(lds + (bufoff) + ldsw + _i * 8192), 16, 0, 0); } while (0)
; #define PG8_LDA(dst, b, h) do { _Pragma("unroll") for (int m = 0; m < 4; ++m) _Pragma("unroll") for (int k = 0; k < 2; ++k) dst[m][k] = *(const PG8_LAS bf16x8*)(lds + PG8_SA(b, h) + aoff + m * 2048 + k * 1024); } while (0)
; #define PG8_LDB(dst, b, h) do { _Pragma("unroll") for (int n = 0; n < 2; ++n) _Pragma("unroll") for (int k = 0; k < 2; ++k) dst[n][k] = *(const PG8_LAS bf16x8*)(lds + PG8_SB(b, h) + boff + n * 2048 + k * 1024); } while (0)
; #define PG8_MMA(ai, bj, At, Bt) do { __builtin_amdgcn_s_setprio(1); _Pragma("unroll") for (int m = 0; m < 4; ++m) _Pragma("unroll") for (int n = 0; n < 2; ++n) _Pragma("unroll") for (int k = 0; k < 2; ++k) \
;         acc[ai][bj][m][n] = __builtin_amdgcn_mfma_f32_16x16x32_bf16(Bt[n][k], At[m][k], acc[ai][bj][m][n], 0, 0, 0); __builtin_amdgcn_s_setprio(0); } while (0)
; #define PG8_WAIT_V(n) asm volatile("s_waitcnt vmcnt(" #n ")" ::: "memory")
; #define PG8_WAIT_L(n) asm volatile("s_waitcnt lgkmcnt(" #n ")" ::: "memory")
; #define PG8_BAR __builtin_amdgcn_s_barrier()
; #define PG8_SCHED __builtin_amdgcn_sched_barrier(0)
;     ...
;             const bool last = (t == nt - 2);
;             const char* a1 = cA + (ptrdiff_t)(t + 1) * kstepA;
;             const char* a2 = last ? nA : cA + (ptrdiff_t)(t + 2) * kstepA; const char* b2 = last ? nB : cB + (ptrdiff_t)(t + 2) * kstep;
;             const char* a3 = a2 + kstepA; const char* b3 = b2 + kstep;
;             if (last && has_next) S.a_ready(nxt);
;             if constexpr (SP2) {
;             PG8_LDB(B0, 0, 0); PG8_LDB(B1, 0, 1); PG8_SCHED; PG8_LDA(At, 0, 0); PG8_STAGE(PG8_SA(1, 1), a1 + hstepA, voffA);
;             PG8_WAIT_V(8); PG8_WAIT_L(0); PG8_BAR; PG8_MMA(0, 0, At, B0); PG8_MMA(0, 1, At, B1); PG8_BAR; PG8_SCHED;
;             PG8_LDA(At, 0, 1); PG8_STAGE(PG8_SB(0, 0), b2, voffB); PG8_STAGE(PG8_SB(0, 1), b2 + hstepB, voffB); PG8_STAGE(PG8_SA(0, 0), a2, voffA);
;             PG8_WAIT_V(8); PG8_WAIT_L(0); PG8_BAR; PG8_MMA(1, 0, At, B0); PG8_MMA(1, 1, At, B1); PG8_BAR; PG8_SCHED;
.LBB0_1444:
	s_or_b32 s44, s56, 1
	s_lshl_b64 s[34:35], s[44:45], 15
	s_sub_u32 s34, 0, s34
	s_subb_u32 s35, 0, s35
	s_add_u32 s44, s28, s34
	s_addc_u32 s65, s29, s35
	s_add_u32 s34, s30, 0xffff8000
	s_addc_u32 s35, s31, -1
	s_add_i32 s66, 0, 0x10000
	v_add_u32_e32 v0, s66, v230
	s_add_i32 s90, 0, 0x14000
	s_waitcnt lgkmcnt(0)
	ds_read_b128 v[130:133], v0
	ds_read_b128 v[134:137], v0 offset:1024
	ds_read_b128 v[138:141], v0 offset:2048
	ds_read_b128 v[142:145], v0 offset:3072
	v_add_u32_e32 v0, s90, v230
	ds_read_b128 v[146:149], v0
	ds_read_b128 v[150:153], v0 offset:1024
	ds_read_b128 v[154:157], v0 offset:2048
	ds_read_b128 v[158:161], v0 offset:3072
	s_add_u32 s88, s44, 0x4000
	s_addc_u32 s89, s65, 0
	s_add_i32 m0, s46, 0xc000
	ds_read_b128 v[162:165], v231
	ds_read_b128 v[166:169], v231 offset:1024
	ds_read_b128 v[170:173], v231 offset:2048
	ds_read_b128 v[174:177], v231 offset:3072
	ds_read_b128 v[178:181], v231 offset:4096
	ds_read_b128 v[182:185], v231 offset:5120
	ds_read_b128 v[186:189], v231 offset:6144
	ds_read_b128 v[190:193], v231 offset:7168
	global_load_lds_dwordx4 v194, s[88:89]
	s_add_i32 m0, s46, 0xe000
	s_nop 0
	global_load_lds_dwordx4 v198, s[88:89]
	s_waitcnt vmcnt(8)
	s_waitcnt lgkmcnt(0)
	s_barrier
	s_setprio 1
	v_mfma_f32_16x16x32_bf16 v[126:129], v[130:133], v[162:165], v[126:129]
	v_mfma_f32_16x16x32_bf16 v[126:129], v[134:137], v[166:169], v[126:129]
	v_mfma_f32_16x16x32_bf16 v[122:125], v[142:145], v[166:169], v[122:125]
	v_mfma_f32_16x16x32_bf16 v[122:125], v[138:141], v[162:165], v[122:125]
	v_mfma_f32_16x16x32_bf16 v[106:109], v[138:141], v[170:173], v[106:109]
	v_mfma_f32_16x16x32_bf16 v[106:109], v[142:145], v[174:177], v[106:109]
	v_mfma_f32_16x16x32_bf16 v[110:113], v[134:137], v[174:177], v[110:113]
	v_mfma_f32_16x16x32_bf16 v[110:113], v[130:133], v[170:173], v[110:113]
	v_mfma_f32_16x16x32_bf16 v[94:97], v[130:133], v[178:181], v[94:97]
	v_mfma_f32_16x16x32_bf16 v[94:97], v[134:137], v[182:185], v[94:97]
	v_mfma_f32_16x16x32_bf16 v[90:93], v[142:145], v[182:185], v[90:93]
	v_mfma_f32_16x16x32_bf16 v[90:93], v[138:141], v[178:181], v[90:93]
	v_mfma_f32_16x16x32_bf16 v[74:77], v[138:141], v[186:189], v[74:77]
	v_mfma_f32_16x16x32_bf16 v[74:77], v[142:145], v[190:193], v[74:77]
	v_mfma_f32_16x16x32_bf16 v[78:81], v[134:137], v[190:193], v[78:81]
	v_mfma_f32_16x16x32_bf16 v[78:81], v[130:133], v[186:189], v[78:81]
	s_setprio 0
	s_setprio 1
	v_mfma_f32_16x16x32_bf16 v[118:121], v[146:149], v[162:165], v[118:121]
	v_mfma_f32_16x16x32_bf16 v[118:121], v[150:153], v[166:169], v[118:121]
	v_mfma_f32_16x16x32_bf16 v[114:117], v[158:161], v[166:169], v[114:117]
	v_mfma_f32_16x16x32_bf16 v[114:117], v[154:157], v[162:165], v[114:117]
	v_mfma_f32_16x16x32_bf16 v[98:101], v[154:157], v[170:173], v[98:101]
	v_mfma_f32_16x16x32_bf16 v[98:101], v[158:161], v[174:177], v[98:101]
	v_mfma_f32_16x16x32_bf16 v[102:105], v[150:153], v[174:177], v[102:105]
	v_mfma_f32_16x16x32_bf16 v[102:105], v[146:149], v[170:173], v[102:105]
	v_mfma_f32_16x16x32_bf16 v[86:89], v[146:149], v[178:181], v[86:89]
	v_mfma_f32_16x16x32_bf16 v[86:89], v[150:153], v[182:185], v[86:89]
	v_mfma_f32_16x16x32_bf16 v[82:85], v[158:161], v[182:185], v[82:85]
	v_mfma_f32_16x16x32_bf16 v[82:85], v[154:157], v[178:181], v[82:85]
	v_mfma_f32_16x16x32_bf16 v[66:69], v[154:157], v[186:189], v[66:69]
	v_mfma_f32_16x16x32_bf16 v[66:69], v[158:161], v[190:193], v[66:69]
	v_mfma_f32_16x16x32_bf16 v[70:73], v[150:153], v[190:193], v[70:73]
	v_mfma_f32_16x16x32_bf16 v[70:73], v[146:149], v[186:189], v[70:73]
	s_barrier
	s_setprio 0
	s_add_i32 s44, s66, s41
	s_mov_b32 m0, s44
	ds_read_b128 v[162:165], v231 offset:16384
	ds_read_b128 v[166:169], v231 offset:17408
	ds_read_b128 v[170:173], v231 offset:18432
	ds_read_b128 v[174:177], v231 offset:19456
	ds_read_b128 v[178:181], v231 offset:20480
	ds_read_b128 v[182:185], v231 offset:21504
	ds_read_b128 v[186:189], v231 offset:22528
	ds_read_b128 v[190:193], v231 offset:23552
	global_load_lds_dwordx4 v196, s[8:9]
	s_add_i32 m0, s44, 0x2000
	s_add_u32 s88, s8, 0x4000
	s_addc_u32 s89, s9, 0
	s_add_i32 s44, s90, s41
	global_load_lds_dwordx4 v200, s[8:9]
	s_mov_b32 m0, s44
	s_nop 0
	global_load_lds_dwordx4 v196, s[88:89]
	s_add_i32 m0, s44, 0x2000
	s_nop 0
	global_load_lds_dwordx4 v200, s[88:89]
	s_mov_b32 m0, s46
	s_nop 0
	global_load_lds_dwordx4 v194, s[30:31]
	s_mov_b32 m0, s47
	s_nop 0
	global_load_lds_dwordx4 v198, s[30:31]
	s_waitcnt vmcnt(8)
	s_waitcnt lgkmcnt(0)
	s_barrier
	s_setprio 1
	v_mfma_f32_16x16x32_bf16 v[62:65], v[130:133], v[162:165], v[62:65]
	v_mfma_f32_16x16x32_bf16 v[62:65], v[134:137], v[166:169], v[62:65]
	v_mfma_f32_16x16x32_bf16 v[58:61], v[142:145], v[166:169], v[58:61]
	v_mfma_f32_16x16x32_bf16 v[58:61], v[138:141], v[162:165], v[58:61]
	v_mfma_f32_16x16x32_bf16 v[42:45], v[138:141], v[170:173], v[42:45]
	v_mfma_f32_16x16x32_bf16 v[42:45], v[142:145], v[174:177], v[42:45]
	v_mfma_f32_16x16x32_bf16 v[46:49], v[134:137], v[174:177], v[46:49]
	v_mfma_f32_16x16x32_bf16 v[46:49], v[130:133], v[170:173], v[46:49]
	v_mfma_f32_16x16x32_bf16 v[30:33], v[130:133], v[178:181], v[30:33]
	v_mfma_f32_16x16x32_bf16 v[30:33], v[134:137], v[182:185], v[30:33]
	v_mfma_f32_16x16x32_bf16 v[26:29], v[142:145], v[182:185], v[26:29]
	v_mfma_f32_16x16x32_bf16 v[26:29], v[138:141], v[178:181], v[26:29]
	v_mfma_f32_16x16x32_bf16 v[10:13], v[138:141], v[186:189], v[10:13]
	v_mfma_f32_16x16x32_bf16 v[10:13], v[142:145], v[190:193], v[10:13]
	v_mfma_f32_16x16x32_bf16 v[14:17], v[134:137], v[190:193], v[14:17]
	v_mfma_f32_16x16x32_bf16 v[14:17], v[130:133], v[186:189], v[14:17]
	s_setprio 0
	s_setprio 1
	v_mfma_f32_16x16x32_bf16 v[54:57], v[146:149], v[162:165], v[54:57]
	v_mfma_f32_16x16x32_bf16 v[54:57], v[150:153], v[166:169], v[54:57]
	v_mfma_f32_16x16x32_bf16 v[50:53], v[158:161], v[166:169], v[50:53]
	v_mfma_f32_16x16x32_bf16 v[50:53], v[154:157], v[162:165], v[50:53]
	v_mfma_f32_16x16x32_bf16 v[34:37], v[154:157], v[170:173], v[34:37]
	v_mfma_f32_16x16x32_bf16 v[34:37], v[158:161], v[174:177], v[34:37]
	v_mfma_f32_16x16x32_bf16 v[38:41], v[150:153], v[174:177], v[38:41]
	v_mfma_f32_16x16x32_bf16 v[38:41], v[146:149], v[170:173], v[38:41]
	v_mfma_f32_16x16x32_bf16 v[22:25], v[146:149], v[178:181], v[22:25]
	v_mfma_f32_16x16x32_bf16 v[22:25], v[150:153], v[182:185], v[22:25]
	v_mfma_f32_16x16x32_bf16 v[18:21], v[158:161], v[182:185], v[18:21]
	v_mfma_f32_16x16x32_bf16 v[18:21], v[154:157], v[178:181], v[18:21]
	v_mfma_f32_16x16x32_bf16 v[2:5], v[154:157], v[186:189], v[2:5]
	v_mfma_f32_16x16x32_bf16 v[2:5], v[158:161], v[190:193], v[2:5]
	v_mfma_f32_16x16x32_bf16 v[6:9], v[150:153], v[190:193], v[6:9]
	v_mfma_f32_16x16x32_bf16 v[6:9], v[146:149], v[186:189], v[6:9]
	s_barrier
	s_setprio 0
; #define PG8_STAGE(bufoff, gbase, voff) do { _Pragma("unroll") for (int _i = 0; _i < 2; ++_i) \
;         __builtin_amdgcn_global_load_lds((const unsigned*)((const char*)(gbase) + (voff)[_i]), (PG8_LAS unsigned*)(lds + (bufoff) + ldsw + _i * 8192), 16, 0, 0); } while (0)
; #define PG8_LDA(dst, b, h) do { _Pragma("unroll") for (int m = 0; m < 4; ++m) _Pragma("unroll") for (int k = 0; k < 2; ++k) dst[m][k] = *(const PG8_LAS bf16x8*)(lds + PG8_SA(b, h) + aoff + m * 2048 + k * 1024); } while (0)
; #define PG8_LDB(dst, b, h) do { _Pragma("unroll") for (int n = 0; n < 2; ++n) _Pragma("unroll") for (int k = 0; k < 2; ++k) dst[n][k] = *(const PG8_LAS bf16x8*)(lds + PG8_SB(b, h) + boff + n * 2048 + k * 1024); } while (0)
; #define PG8_MMA(ai, bj, At, Bt) do { __builtin_amdgcn_s_setprio(1); _Pragma("unroll") for (int m = 0; m < 4; ++m) _Pragma("unroll") for (int n = 0; n < 2; ++n) _Pragma("unroll") for (int k = 0; k < 2; ++k) \
;         acc[ai][bj][m][n] = __builtin_amdgcn_mfma_f32_16x16x32_bf16(Bt[n][k], At[m][k], acc[ai][bj][m][n], 0, 0, 0); __builtin_amdgcn_s_setprio(0); } while (0)
; #define PG8_WAIT_V(n) asm volatile("s_waitcnt vmcnt(" #n ")" ::: "memory")
; #define PG8_WAIT_L(n) asm volatile("s_waitcnt lgkmcnt(" #n ")" ::: "memory")
; #define PG8_BAR __builtin_amdgcn_s_barrier()
; #define PG8_SCHED __builtin_amdgcn_sched_barrier(0)
;     ...
;             PG8_LDB(B0, 1, 0); PG8_LDB(B1, 1, 1); PG8_SCHED; PG8_LDA(At, 1, 0); PG8_STAGE(PG8_SA(0, 1), a2 + hstepA, voffA);
;             PG8_WAIT_V(8); PG8_WAIT_L(0); PG8_BAR; PG8_MMA(0, 0, At, B0); PG8_MMA(0, 1, At, B1); PG8_BAR; PG8_SCHED;
;             PG8_LDA(At, 1, 1); PG8_STAGE(PG8_SB(1, 0), b3, voffB); PG8_STAGE(PG8_SB(1, 1), b3 + hstepB, voffB); PG8_STAGE(PG8_SA(1, 0), a3, voffA);
;             PG8_WAIT_V(8); PG8_WAIT_L(0); PG8_BAR; PG8_MMA(1, 0, At, B0); PG8_MMA(1, 1, At, B1); PG8_BAR; PG8_SCHED;
.Ldn_mid:
	s_add_i32 s44, 0, 0x18000
	v_add_u32_e32 v0, s44, v230
	s_add_i32 s65, 0, 0x1c000
	ds_read_b128 v[130:133], v0
	ds_read_b128 v[134:137], v0 offset:1024
	ds_read_b128 v[138:141], v0 offset:2048
	ds_read_b128 v[142:145], v0 offset:3072
	v_add_u32_e32 v0, s65, v230
	ds_read_b128 v[146:149], v0
	ds_read_b128 v[150:153], v0 offset:1024
	ds_read_b128 v[154:157], v0 offset:2048
	ds_read_b128 v[158:161], v0 offset:3072
	s_add_u32 s30, s30, 0x4000
	s_addc_u32 s31, s31, 0
	s_mov_b32 m0, s48
	ds_read_b128 v[162:165], v231 offset:32768
	ds_read_b128 v[166:169], v231 offset:33792
	ds_read_b128 v[170:173], v231 offset:34816
	ds_read_b128 v[174:177], v231 offset:35840
	ds_read_b128 v[178:181], v231 offset:36864
	ds_read_b128 v[182:185], v231 offset:37888
	ds_read_b128 v[186:189], v231 offset:38912
	ds_read_b128 v[190:193], v231 offset:39936
	global_load_lds_dwordx4 v194, s[30:31]
	s_mov_b32 m0, s49
	s_nop 0
	global_load_lds_dwordx4 v198, s[30:31]
	s_waitcnt vmcnt(8)
	s_waitcnt lgkmcnt(0)
	s_barrier
	s_setprio 1
	v_mfma_f32_16x16x32_bf16 v[126:129], v[130:133], v[162:165], v[126:129]
	v_mfma_f32_16x16x32_bf16 v[126:129], v[134:137], v[166:169], v[126:129]
	v_mfma_f32_16x16x32_bf16 v[122:125], v[142:145], v[166:169], v[122:125]
	v_mfma_f32_16x16x32_bf16 v[122:125], v[138:141], v[162:165], v[122:125]
	v_mfma_f32_16x16x32_bf16 v[106:109], v[138:141], v[170:173], v[106:109]
	v_mfma_f32_16x16x32_bf16 v[106:109], v[142:145], v[174:177], v[106:109]
	v_mfma_f32_16x16x32_bf16 v[110:113], v[134:137], v[174:177], v[110:113]
	v_mfma_f32_16x16x32_bf16 v[110:113], v[130:133], v[170:173], v[110:113]
	v_mfma_f32_16x16x32_bf16 v[94:97], v[130:133], v[178:181], v[94:97]
	v_mfma_f32_16x16x32_bf16 v[94:97], v[134:137], v[182:185], v[94:97]
	v_mfma_f32_16x16x32_bf16 v[90:93], v[142:145], v[182:185], v[90:93]
	v_mfma_f32_16x16x32_bf16 v[90:93], v[138:141], v[178:181], v[90:93]
	v_mfma_f32_16x16x32_bf16 v[74:77], v[138:141], v[186:189], v[74:77]
	v_mfma_f32_16x16x32_bf16 v[74:77], v[142:145], v[190:193], v[74:77]
	v_mfma_f32_16x16x32_bf16 v[78:81], v[134:137], v[190:193], v[78:81]
	v_mfma_f32_16x16x32_bf16 v[78:81], v[130:133], v[186:189], v[78:81]
	s_setprio 0
	s_setprio 1
	v_mfma_f32_16x16x32_bf16 v[118:121], v[146:149], v[162:165], v[118:121]
	v_mfma_f32_16x16x32_bf16 v[118:121], v[150:153], v[166:169], v[118:121]
	v_mfma_f32_16x16x32_bf16 v[114:117], v[158:161], v[166:169], v[114:117]
	v_mfma_f32_16x16x32_bf16 v[114:117], v[154:157], v[162:165], v[114:117]
	v_mfma_f32_16x16x32_bf16 v[98:101], v[154:157], v[170:173], v[98:101]
	v_mfma_f32_16x16x32_bf16 v[98:101], v[158:161], v[174:177], v[98:101]
	v_mfma_f32_16x16x32_bf16 v[102:105], v[150:153], v[174:177], v[102:105]
	v_mfma_f32_16x16x32_bf16 v[102:105], v[146:149], v[170:173], v[102:105]
	v_mfma_f32_16x16x32_bf16 v[86:89], v[146:149], v[178:181], v[86:89]
	v_mfma_f32_16x16x32_bf16 v[86:89], v[150:153], v[182:185], v[86:89]
	v_mfma_f32_16x16x32_bf16 v[82:85], v[158:161], v[182:185], v[82:85]
	v_mfma_f32_16x16x32_bf16 v[82:85], v[154:157], v[178:181], v[82:85]
	v_mfma_f32_16x16x32_bf16 v[66:69], v[154:157], v[186:189], v[66:69]
	v_mfma_f32_16x16x32_bf16 v[66:69], v[158:161], v[190:193], v[66:69]
	v_mfma_f32_16x16x32_bf16 v[70:73], v[150:153], v[190:193], v[70:73]
	v_mfma_f32_16x16x32_bf16 v[70:73], v[146:149], v[186:189], v[70:73]
	s_barrier
	s_setprio 0
	s_add_u32 s30, s8, 0xffff8000
	s_addc_u32 s31, s9, -1
	s_add_i32 s44, s44, s41
	s_mov_b32 m0, s44
	ds_read_b128 v[162:165], v231 offset:49152
	ds_read_b128 v[166:169], v231 offset:50176
	ds_read_b128 v[170:173], v231 offset:51200
	ds_read_b128 v[174:177], v231 offset:52224
	ds_read_b128 v[178:181], v231 offset:53248
	ds_read_b128 v[182:185], v231 offset:54272
	ds_read_b128 v[186:189], v231 offset:55296
	ds_read_b128 v[190:193], v231 offset:56320
	global_load_lds_dwordx4 v196, s[30:31]
	s_add_i32 m0, s44, 0x2000
	s_add_u32 s8, s8, 0xffffc000
	v_lshl_add_u64 v[202:203], s[30:31], 0, v[200:201]
	s_addc_u32 s9, s9, -1
	s_add_i32 s30, s65, s41
	global_load_lds_dwordx4 v[202:203], off
	s_mov_b32 m0, s30
	s_nop 0
	global_load_lds_dwordx4 v196, s[8:9]
	s_add_i32 m0, s30, 0x2000
	s_nop 0
	global_load_lds_dwordx4 v200, s[8:9]
	s_mov_b32 m0, s71
	s_nop 0
	global_load_lds_dwordx4 v194, s[34:35]
	v_lshl_add_u64 v[202:203], s[34:35], 0, v[198:199]
	s_mov_b32 m0, s80
	s_nop 0
	global_load_lds_dwordx4 v[202:203], off
	s_waitcnt vmcnt(8)
	s_waitcnt lgkmcnt(0)
	s_barrier
	s_setprio 1
	v_mfma_f32_16x16x32_bf16 v[62:65], v[130:133], v[162:165], v[62:65]
	v_mfma_f32_16x16x32_bf16 v[62:65], v[134:137], v[166:169], v[62:65]
	v_mfma_f32_16x16x32_bf16 v[58:61], v[142:145], v[166:169], v[58:61]
	v_mfma_f32_16x16x32_bf16 v[58:61], v[138:141], v[162:165], v[58:61]
	v_mfma_f32_16x16x32_bf16 v[42:45], v[138:141], v[170:173], v[42:45]
	v_mfma_f32_16x16x32_bf16 v[42:45], v[142:145], v[174:177], v[42:45]
	v_mfma_f32_16x16x32_bf16 v[46:49], v[134:137], v[174:177], v[46:49]
	v_mfma_f32_16x16x32_bf16 v[46:49], v[130:133], v[170:173], v[46:49]
	v_mfma_f32_16x16x32_bf16 v[30:33], v[130:133], v[178:181], v[30:33]
	v_mfma_f32_16x16x32_bf16 v[30:33], v[134:137], v[182:185], v[30:33]
	v_mfma_f32_16x16x32_bf16 v[26:29], v[142:145], v[182:185], v[26:29]
	v_mfma_f32_16x16x32_bf16 v[26:29], v[138:141], v[178:181], v[26:29]
	v_mfma_f32_16x16x32_bf16 v[10:13], v[138:141], v[186:189], v[10:13]
	v_mfma_f32_16x16x32_bf16 v[10:13], v[142:145], v[190:193], v[10:13]
	v_mfma_f32_16x16x32_bf16 v[14:17], v[134:137], v[190:193], v[14:17]
	v_mfma_f32_16x16x32_bf16 v[14:17], v[130:133], v[186:189], v[14:17]
	s_setprio 0
	s_setprio 1
	v_mfma_f32_16x16x32_bf16 v[54:57], v[146:149], v[162:165], v[54:57]
	v_mfma_f32_16x16x32_bf16 v[54:57], v[150:153], v[166:169], v[54:57]
	v_mfma_f32_16x16x32_bf16 v[50:53], v[158:161], v[166:169], v[50:53]
	v_mfma_f32_16x16x32_bf16 v[50:53], v[154:157], v[162:165], v[50:53]
	v_mfma_f32_16x16x32_bf16 v[34:37], v[154:157], v[170:173], v[34:37]
	v_mfma_f32_16x16x32_bf16 v[34:37], v[158:161], v[174:177], v[34:37]
	v_mfma_f32_16x16x32_bf16 v[38:41], v[150:153], v[174:177], v[38:41]
	v_mfma_f32_16x16x32_bf16 v[38:41], v[146:149], v[170:173], v[38:41]
	v_mfma_f32_16x16x32_bf16 v[22:25], v[146:149], v[178:181], v[22:25]
	v_mfma_f32_16x16x32_bf16 v[22:25], v[150:153], v[182:185], v[22:25]
	v_mfma_f32_16x16x32_bf16 v[18:21], v[158:161], v[182:185], v[18:21]
	v_mfma_f32_16x16x32_bf16 v[18:21], v[154:157], v[178:181], v[18:21]
	v_mfma_f32_16x16x32_bf16 v[2:5], v[154:157], v[186:189], v[2:5]
	v_mfma_f32_16x16x32_bf16 v[2:5], v[158:161], v[190:193], v[2:5]
	v_mfma_f32_16x16x32_bf16 v[6:9], v[150:153], v[190:193], v[6:9]
	v_mfma_f32_16x16x32_bf16 v[6:9], v[146:149], v[186:189], v[6:9]
	s_barrier
	s_setprio 0
	s_cmpk_gt_u32 s56, 0x55
	s_mov_b32 s56, s57
	s_cbranch_scc1 .LBB0_1449
